# SwiGLU epilogue of the GU GEMMs: adjacent scalar v_mul/v_add pairs packed into v_pk_mul_f32 / v_pk_add_f32 (same f32 math, half the issue slots)
# speedup vs baseline: 1.0549x; 1.0010x over previous
; #define PG8_STAGE(bufoff, gbase, voff) do { _Pragma("unroll") for (int _i = 0; _i < 2; ++_i) \
;         __builtin_amdgcn_global_load_lds((const unsigned*)((const char*)(gbase) + (voff)[_i]), (LAS unsigned*)(lds + (bufoff) + ldsw + _i * 8192), 16, 0, 0); } while (0)
; #define PG8_LDA(dst, b, h) do { _Pragma("unroll") for (int m = 0; m < 4; ++m) _Pragma("unroll") for (int k = 0; k < 2; ++k) dst[m][k] = *(const LAS bf16x8*)(lds + PG8_SA(b, h) + aoff + m * 2048 + k * 1024); } while (0)
; #define PG8_LDB(dst, b, h) do { _Pragma("unroll") for (int n = 0; n < 2; ++n) _Pragma("unroll") for (int k = 0; k < 2; ++k) dst[n][k] = *(const LAS bf16x8*)(lds + PG8_SB(b, h) + boff + n * 2048 + k * 1024); } while (0)
; #define PG8_MMA(ai, bj, At, Bt) do { __builtin_amdgcn_s_setprio(1); _Pragma("unroll") for (int m = 0; m < 4; ++m) _Pragma("unroll") for (int n = 0; n < 2; ++n) _Pragma("unroll") for (int k = 0; k < 2; ++k) \
;         acc[ai][bj][m][n] = __builtin_amdgcn_mfma_f32_16x16x32_bf16(Bt[n][k], At[m][k], acc[ai][bj][m][n], 0, 0, 0); __builtin_amdgcn_s_setprio(0); } while (0)
; #define PG8_WAIT_L(n) asm volatile("s_waitcnt lgkmcnt(" #n ")" ::: "memory")
; #define PG8_BAR __builtin_amdgcn_s_barrier()
; #define PG8_SCHED __builtin_amdgcn_sched_barrier(0)
; template <class Epi>
; DI void gemm_phase(int wv, LAS unsigned char* lds, const Gemm g, const StaticOrder& S, const Epi& E) {
;     ...
;         for (int t = 0; t < nt; t += 2) {
;             const bool last = (t == nt - 2);
;             const char* a1 = cA + (size_t)(t + 1) * kstep;
;             const char* a2 = last ? nA : cA + (size_t)(t + 2) * kstep; const char* b2 = last ? nB : cB + (size_t)(t + 2) * kstep;
;             const char* a3 = a2 + kstep; const char* b3 = b2 + kstep;
;             PG8_LDB(B0, 0, 0); PG8_SCHED; PG8_LDA(At, 0, 0); PG8_STAGE(PG8_SA(1, 1), a1 + hstep, voffA);
;             PG8_WAIT_L(8); PG8_BAR; PG8_WAIT_L(0); PG8_MMA(0, 0, At, B0); PG8_BAR; PG8_SCHED;
;             PG8_LDB(B1, 0, 1); PG8_STAGE(PG8_SB(0, 0), b2, voffB);
;             PG8_BAR; PG8_WAIT_L(0); PG8_MMA(0, 1, At, B1); PG8_BAR;
;             PG8_LDA(At, 0, 1); PG8_STAGE(PG8_SA(0, 0), a2, voffA);
;             PG8_BAR; PG8_WAIT_L(0); PG8_MMA(1, 0, At, B0); PG8_BAR; PG8_SCHED;
.LBB0_101:
	ds_read_b128 v[152:155], v149
	ds_read_b128 v[156:159], v149 offset:1024
	ds_read_b128 v[160:163], v149 offset:2048
	ds_read_b128 v[164:167], v149 offset:3072
	s_add_u32 s28, s20, 0xfffc0080
	s_addc_u32 s29, s21, -1
	s_cmp_eq_u32 s68, 12
	s_cselect_b32 s31, s13, s29
	s_cselect_b32 s30, s19, s28
	s_cselect_b32 s29, s11, s67
	s_cselect_b32 s28, s65, s66
	v_lshl_add_u64 v[200:201], s[20:21], 0, v[140:141]
	s_add_i32 m0, s41, 0xc000
	ds_read_b128 v[168:171], v150
	ds_read_b128 v[172:175], v150 offset:1024
	ds_read_b128 v[176:179], v150 offset:2048
	ds_read_b128 v[180:183], v150 offset:3072
	ds_read_b128 v[184:187], v150 offset:4096
	ds_read_b128 v[188:191], v150 offset:5120
	ds_read_b128 v[192:195], v150 offset:6144
	ds_read_b128 v[196:199], v150 offset:7168
	global_load_lds_dwordx4 v[200:201], off
	v_lshl_add_u64 v[200:201], s[20:21], 0, v[142:143]
	s_add_i32 m0, s41, 0xe000
	s_nop 0
	global_load_lds_dwordx4 v[200:201], off
	s_waitcnt lgkmcnt(8)
	s_barrier
	s_waitcnt lgkmcnt(0)
	s_setprio 1
	s_waitcnt lgkmcnt(0)
	v_mfma_f32_16x16x32_bf16 v[124:127], v[152:155], v[168:171], v[124:127]
	v_mfma_f32_16x16x32_bf16 v[120:123], v[160:163], v[168:171], v[120:123]
	v_mfma_f32_16x16x32_bf16 v[108:111], v[152:155], v[176:179], v[108:111]
	v_mfma_f32_16x16x32_bf16 v[104:107], v[160:163], v[176:179], v[104:107]
	v_mfma_f32_16x16x32_bf16 v[92:95], v[152:155], v[184:187], v[92:95]
	v_mfma_f32_16x16x32_bf16 v[88:91], v[160:163], v[184:187], v[88:91]
	v_mfma_f32_16x16x32_bf16 v[76:79], v[152:155], v[192:195], v[76:79]
	v_mfma_f32_16x16x32_bf16 v[72:75], v[160:163], v[192:195], v[72:75]
	v_mfma_f32_16x16x32_bf16 v[124:127], v[156:159], v[172:175], v[124:127]
	v_mfma_f32_16x16x32_bf16 v[120:123], v[164:167], v[172:175], v[120:123]
	v_mfma_f32_16x16x32_bf16 v[108:111], v[156:159], v[180:183], v[108:111]
	v_mfma_f32_16x16x32_bf16 v[104:107], v[164:167], v[180:183], v[104:107]
	v_mfma_f32_16x16x32_bf16 v[92:95], v[156:159], v[188:191], v[92:95]
	v_mfma_f32_16x16x32_bf16 v[88:91], v[164:167], v[188:191], v[88:91]
	v_mfma_f32_16x16x32_bf16 v[76:79], v[156:159], v[196:199], v[76:79]
	v_mfma_f32_16x16x32_bf16 v[72:75], v[164:167], v[196:199], v[72:75]
	s_setprio 0
	s_barrier
	s_add_i32 s69, s52, s39
	v_lshl_add_u64 v[200:201], s[28:29], 0, v[130:131]
	s_mov_b32 m0, s69
	ds_read_b128 v[202:205], v151
	ds_read_b128 v[206:209], v151 offset:1024
	ds_read_b128 v[210:213], v151 offset:2048
	ds_read_b128 v[214:217], v151 offset:3072
	global_load_lds_dwordx4 v[200:201], off
	v_lshl_add_u64 v[218:219], s[28:29], 0, v[134:135]
	s_add_i32 m0, s69, 0x2000
	s_nop 0
	global_load_lds_dwordx4 v[218:219], off
	s_barrier
	s_waitcnt lgkmcnt(0)
	s_setprio 1
	s_waitcnt lgkmcnt(0)
	v_mfma_f32_16x16x32_bf16 v[116:119], v[202:205], v[168:171], v[116:119]
	v_mfma_f32_16x16x32_bf16 v[112:115], v[210:213], v[168:171], v[112:115]
	v_mfma_f32_16x16x32_bf16 v[100:103], v[202:205], v[176:179], v[100:103]
	v_mfma_f32_16x16x32_bf16 v[96:99], v[210:213], v[176:179], v[96:99]
	v_mfma_f32_16x16x32_bf16 v[84:87], v[202:205], v[184:187], v[84:87]
	v_mfma_f32_16x16x32_bf16 v[80:83], v[210:213], v[184:187], v[80:83]
	v_mfma_f32_16x16x32_bf16 v[68:71], v[202:205], v[192:195], v[68:71]
	v_mfma_f32_16x16x32_bf16 v[64:67], v[210:213], v[192:195], v[64:67]
	v_mfma_f32_16x16x32_bf16 v[116:119], v[206:209], v[172:175], v[116:119]
	v_mfma_f32_16x16x32_bf16 v[112:115], v[214:217], v[172:175], v[112:115]
	v_mfma_f32_16x16x32_bf16 v[100:103], v[206:209], v[180:183], v[100:103]
	v_mfma_f32_16x16x32_bf16 v[96:99], v[214:217], v[180:183], v[96:99]
	v_mfma_f32_16x16x32_bf16 v[84:87], v[206:209], v[188:191], v[84:87]
	v_mfma_f32_16x16x32_bf16 v[80:83], v[214:217], v[188:191], v[80:83]
	v_mfma_f32_16x16x32_bf16 v[68:71], v[206:209], v[196:199], v[68:71]
	v_mfma_f32_16x16x32_bf16 v[64:67], v[214:217], v[196:199], v[64:67]
	s_setprio 0
	s_mov_b32 m0, s41
	v_lshl_add_u64 v[220:221], s[30:31], 0, v[128:129]
	s_barrier
	ds_read_b128 v[168:171], v150 offset:16384
	ds_read_b128 v[172:175], v150 offset:17408
	ds_read_b128 v[176:179], v150 offset:18432
	ds_read_b128 v[180:183], v150 offset:19456
	ds_read_b128 v[184:187], v150 offset:20480
	ds_read_b128 v[188:191], v150 offset:21504
	ds_read_b128 v[192:195], v150 offset:22528
	ds_read_b128 v[196:199], v150 offset:23552
	global_load_lds_dwordx4 v[220:221], off
	v_lshl_add_u64 v[222:223], s[30:31], 0, v[132:133]
	s_mov_b32 m0, s46
	s_nop 0
	global_load_lds_dwordx4 v[222:223], off
	s_barrier
	s_waitcnt lgkmcnt(0)
	s_setprio 1
	s_waitcnt lgkmcnt(0)
	v_mfma_f32_16x16x32_bf16 v[60:63], v[152:155], v[168:171], v[60:63]
	v_mfma_f32_16x16x32_bf16 v[56:59], v[160:163], v[168:171], v[56:59]
	v_mfma_f32_16x16x32_bf16 v[44:47], v[152:155], v[176:179], v[44:47]
	v_mfma_f32_16x16x32_bf16 v[40:43], v[160:163], v[176:179], v[40:43]
	v_mfma_f32_16x16x32_bf16 v[28:31], v[152:155], v[184:187], v[28:31]
	v_mfma_f32_16x16x32_bf16 v[24:27], v[160:163], v[184:187], v[24:27]
	v_mfma_f32_16x16x32_bf16 v[12:15], v[152:155], v[192:195], v[12:15]
	v_mfma_f32_16x16x32_bf16 v[8:11], v[160:163], v[192:195], v[8:11]
	v_mfma_f32_16x16x32_bf16 v[60:63], v[156:159], v[172:175], v[60:63]
	v_mfma_f32_16x16x32_bf16 v[56:59], v[164:167], v[172:175], v[56:59]
	v_mfma_f32_16x16x32_bf16 v[44:47], v[156:159], v[180:183], v[44:47]
	v_mfma_f32_16x16x32_bf16 v[40:43], v[164:167], v[180:183], v[40:43]
	v_mfma_f32_16x16x32_bf16 v[28:31], v[156:159], v[188:191], v[28:31]
	v_mfma_f32_16x16x32_bf16 v[24:27], v[164:167], v[188:191], v[24:27]
	v_mfma_f32_16x16x32_bf16 v[12:15], v[156:159], v[196:199], v[12:15]
	v_mfma_f32_16x16x32_bf16 v[8:11], v[164:167], v[196:199], v[8:11]
	s_setprio 0
	s_barrier
; #define PG8_STAGE(bufoff, gbase, voff) do { _Pragma("unroll") for (int _i = 0; _i < 2; ++_i) \
;         __builtin_amdgcn_global_load_lds((const unsigned*)((const char*)(gbase) + (voff)[_i]), (LAS unsigned*)(lds + (bufoff) + ldsw + _i * 8192), 16, 0, 0); } while (0)
; #define PG8_LDA(dst, b, h) do { _Pragma("unroll") for (int m = 0; m < 4; ++m) _Pragma("unroll") for (int k = 0; k < 2; ++k) dst[m][k] = *(const LAS bf16x8*)(lds + PG8_SA(b, h) + aoff + m * 2048 + k * 1024); } while (0)
; #define PG8_LDB(dst, b, h) do { _Pragma("unroll") for (int n = 0; n < 2; ++n) _Pragma("unroll") for (int k = 0; k < 2; ++k) dst[n][k] = *(const LAS bf16x8*)(lds + PG8_SB(b, h) + boff + n * 2048 + k * 1024); } while (0)
; #define PG8_MMA(ai, bj, At, Bt) do { __builtin_amdgcn_s_setprio(1); _Pragma("unroll") for (int m = 0; m < 4; ++m) _Pragma("unroll") for (int n = 0; n < 2; ++n) _Pragma("unroll") for (int k = 0; k < 2; ++k) \
;         acc[ai][bj][m][n] = __builtin_amdgcn_mfma_f32_16x16x32_bf16(Bt[n][k], At[m][k], acc[ai][bj][m][n], 0, 0, 0); __builtin_amdgcn_s_setprio(0); } while (0)
; #define PG8_WAIT_V(n) asm volatile("s_waitcnt vmcnt(" #n ")" ::: "memory")
; #define PG8_WAIT_L(n) asm volatile("s_waitcnt lgkmcnt(" #n ")" ::: "memory")
; #define PG8_BAR __builtin_amdgcn_s_barrier()
; #define PG8_SCHED __builtin_amdgcn_sched_barrier(0)
; template <class Epi>
; DI void gemm_phase(int wv, LAS unsigned char* lds, const Gemm g, const StaticOrder& S, const Epi& E) {
;     ...
;             PG8_STAGE(PG8_SB(0, 1), b2 + hstep, voffB);
;             PG8_WAIT_V(6); PG8_BAR; PG8_MMA(1, 1, At, B1); PG8_BAR;
;             PG8_LDB(B0, 1, 0); PG8_SCHED; PG8_LDA(At, 1, 0); PG8_STAGE(PG8_SA(0, 1), a2 + hstep, voffA);
;             PG8_WAIT_L(8); PG8_BAR; PG8_WAIT_L(0); PG8_MMA(0, 0, At, B0); PG8_BAR; PG8_SCHED;
;             PG8_LDB(B1, 1, 1); PG8_STAGE(PG8_SB(1, 0), b3, voffB);
;             PG8_BAR; PG8_WAIT_L(0); PG8_MMA(0, 1, At, B1); PG8_BAR;
;             PG8_LDA(At, 1, 1); PG8_STAGE(PG8_SA(1, 0), a3, voffA);
;             PG8_BAR; PG8_WAIT_L(0); PG8_MMA(1, 0, At, B0); PG8_BAR; PG8_SCHED;
	s_add_u32 s70, s28, 0x40000
	s_addc_u32 s71, s29, 0
	s_add_i32 s69, s53, s39
	v_lshl_add_u64 v[152:153], s[70:71], 0, v[130:131]
	s_mov_b32 m0, s69
	s_nop 0
	global_load_lds_dwordx4 v[152:153], off
	v_lshl_add_u64 v[152:153], s[70:71], 0, v[134:135]
	s_add_i32 m0, s69, 0x2000
	s_nop 0
	global_load_lds_dwordx4 v[152:153], off
	s_waitcnt vmcnt(6)
	s_barrier
	s_setprio 1
	v_mfma_f32_16x16x32_bf16 v[52:55], v[202:205], v[168:171], v[52:55]
	v_mfma_f32_16x16x32_bf16 v[48:51], v[210:213], v[168:171], v[48:51]
	v_mfma_f32_16x16x32_bf16 v[36:39], v[202:205], v[176:179], v[36:39]
	v_mfma_f32_16x16x32_bf16 v[32:35], v[210:213], v[176:179], v[32:35]
	v_mfma_f32_16x16x32_bf16 v[20:23], v[202:205], v[184:187], v[20:23]
	v_mfma_f32_16x16x32_bf16 v[16:19], v[210:213], v[184:187], v[16:19]
	v_mfma_f32_16x16x32_bf16 v[4:7], v[202:205], v[192:195], v[4:7]
	v_mfma_f32_16x16x32_bf16 v[0:3], v[210:213], v[192:195], v[0:3]
	v_mfma_f32_16x16x32_bf16 v[52:55], v[206:209], v[172:175], v[52:55]
	v_mfma_f32_16x16x32_bf16 v[48:51], v[214:217], v[172:175], v[48:51]
	v_mfma_f32_16x16x32_bf16 v[36:39], v[206:209], v[180:183], v[36:39]
	v_mfma_f32_16x16x32_bf16 v[32:35], v[214:217], v[180:183], v[32:35]
	v_mfma_f32_16x16x32_bf16 v[20:23], v[206:209], v[188:191], v[20:23]
	v_mfma_f32_16x16x32_bf16 v[16:19], v[214:217], v[188:191], v[16:19]
	v_mfma_f32_16x16x32_bf16 v[4:7], v[206:209], v[196:199], v[4:7]
	v_mfma_f32_16x16x32_bf16 v[0:3], v[214:217], v[196:199], v[0:3]
	s_setprio 0
	s_add_i32 s69, 0, 0x18000
	v_add_u32_e32 v164, s69, v148
	s_barrier
	ds_read_b128 v[152:155], v164
	ds_read_b128 v[156:159], v164 offset:1024
	ds_read_b128 v[160:163], v164 offset:2048
	ds_read_b128 v[164:167], v164 offset:3072
	s_add_u32 s30, s30, 0x40000
	s_addc_u32 s31, s31, 0
	s_mov_b32 m0, s47
	v_lshl_add_u64 v[202:203], s[30:31], 0, v[128:129]
	ds_read_b128 v[168:171], v150 offset:32768
	ds_read_b128 v[172:175], v150 offset:33792
	ds_read_b128 v[176:179], v150 offset:34816
	ds_read_b128 v[180:183], v150 offset:35840
	ds_read_b128 v[184:187], v150 offset:36864
	ds_read_b128 v[188:191], v150 offset:37888
	ds_read_b128 v[192:195], v150 offset:38912
	ds_read_b128 v[196:199], v150 offset:39936
	global_load_lds_dwordx4 v[202:203], off
	v_lshl_add_u64 v[202:203], s[30:31], 0, v[132:133]
	s_mov_b32 m0, s48
	s_nop 0
	global_load_lds_dwordx4 v[202:203], off
	s_waitcnt lgkmcnt(8)
	s_barrier
	s_waitcnt lgkmcnt(0)
	s_setprio 1
	s_waitcnt lgkmcnt(0)
	v_mfma_f32_16x16x32_bf16 v[124:127], v[152:155], v[168:171], v[124:127]
	v_mfma_f32_16x16x32_bf16 v[120:123], v[160:163], v[168:171], v[120:123]
	v_mfma_f32_16x16x32_bf16 v[108:111], v[152:155], v[176:179], v[108:111]
	v_mfma_f32_16x16x32_bf16 v[104:107], v[160:163], v[176:179], v[104:107]
	v_mfma_f32_16x16x32_bf16 v[92:95], v[152:155], v[184:187], v[92:95]
	v_mfma_f32_16x16x32_bf16 v[88:91], v[160:163], v[184:187], v[88:91]
	v_mfma_f32_16x16x32_bf16 v[76:79], v[152:155], v[192:195], v[76:79]
	v_mfma_f32_16x16x32_bf16 v[72:75], v[160:163], v[192:195], v[72:75]
	v_mfma_f32_16x16x32_bf16 v[124:127], v[156:159], v[172:175], v[124:127]
	v_mfma_f32_16x16x32_bf16 v[120:123], v[164:167], v[172:175], v[120:123]
	v_mfma_f32_16x16x32_bf16 v[108:111], v[156:159], v[180:183], v[108:111]
	v_mfma_f32_16x16x32_bf16 v[104:107], v[164:167], v[180:183], v[104:107]
	v_mfma_f32_16x16x32_bf16 v[92:95], v[156:159], v[188:191], v[92:95]
	v_mfma_f32_16x16x32_bf16 v[88:91], v[164:167], v[188:191], v[88:91]
	v_mfma_f32_16x16x32_bf16 v[76:79], v[156:159], v[196:199], v[76:79]
	v_mfma_f32_16x16x32_bf16 v[72:75], v[164:167], v[196:199], v[72:75]
	s_setprio 0
	s_barrier
	s_add_i32 s30, 0, 0x1c000
	s_add_i32 s31, s69, s39
	v_add_u32_e32 v214, s30, v148
	v_lshl_add_u64 v[200:201], v[200:201], 0, s[8:9]
	s_mov_b32 m0, s31
	ds_read_b128 v[202:205], v214
	ds_read_b128 v[206:209], v214 offset:1024
	ds_read_b128 v[210:213], v214 offset:2048
	ds_read_b128 v[214:217], v214 offset:3072
	global_load_lds_dwordx4 v[200:201], off
	v_lshl_add_u64 v[200:201], v[218:219], 0, s[8:9]
	s_add_i32 m0, s31, 0x2000
	s_nop 0
	global_load_lds_dwordx4 v[200:201], off
	s_barrier
	s_waitcnt lgkmcnt(0)
	s_setprio 1
	s_waitcnt lgkmcnt(0)
	v_mfma_f32_16x16x32_bf16 v[116:119], v[202:205], v[168:171], v[116:119]
	v_mfma_f32_16x16x32_bf16 v[112:115], v[210:213], v[168:171], v[112:115]
	v_mfma_f32_16x16x32_bf16 v[100:103], v[202:205], v[176:179], v[100:103]
	v_mfma_f32_16x16x32_bf16 v[96:99], v[210:213], v[176:179], v[96:99]
	v_mfma_f32_16x16x32_bf16 v[84:87], v[202:205], v[184:187], v[84:87]
	v_mfma_f32_16x16x32_bf16 v[80:83], v[210:213], v[184:187], v[80:83]
	v_mfma_f32_16x16x32_bf16 v[68:71], v[202:205], v[192:195], v[68:71]
	v_mfma_f32_16x16x32_bf16 v[64:67], v[210:213], v[192:195], v[64:67]
	v_mfma_f32_16x16x32_bf16 v[116:119], v[206:209], v[172:175], v[116:119]
	v_mfma_f32_16x16x32_bf16 v[112:115], v[214:217], v[172:175], v[112:115]
	v_mfma_f32_16x16x32_bf16 v[100:103], v[206:209], v[180:183], v[100:103]
	v_mfma_f32_16x16x32_bf16 v[96:99], v[214:217], v[180:183], v[96:99]
	v_mfma_f32_16x16x32_bf16 v[84:87], v[206:209], v[188:191], v[84:87]
	v_mfma_f32_16x16x32_bf16 v[80:83], v[214:217], v[188:191], v[80:83]
	v_mfma_f32_16x16x32_bf16 v[68:71], v[206:209], v[196:199], v[68:71]
	v_mfma_f32_16x16x32_bf16 v[64:67], v[214:217], v[196:199], v[64:67]
	s_setprio 0
	s_mov_b32 m0, s50
	v_lshl_add_u64 v[200:201], v[220:221], 0, s[8:9]
	s_barrier
	ds_read_b128 v[168:171], v150 offset:49152
	ds_read_b128 v[172:175], v150 offset:50176
	ds_read_b128 v[176:179], v150 offset:51200
	ds_read_b128 v[180:183], v150 offset:52224
	ds_read_b128 v[184:187], v150 offset:53248
	ds_read_b128 v[188:191], v150 offset:54272
	ds_read_b128 v[192:195], v150 offset:55296
	ds_read_b128 v[196:199], v150 offset:56320
	global_load_lds_dwordx4 v[200:201], off
	v_lshl_add_u64 v[200:201], v[222:223], 0, s[8:9]
	s_mov_b32 m0, s51
	s_nop 0
	global_load_lds_dwordx4 v[200:201], off
	s_barrier
; DI unsigned pack2(float lo, float hi) { f32x2 v = {lo, hi}; bf16v2 r = __builtin_convertvector(v, bf16v2); return __builtin_bit_cast(unsigned, r); }
; DI float fexp2(float x) { return __builtin_amdgcn_exp2f(x); }
; DI float frcp(float x) { return __builtin_amdgcn_rcpf(x); }
; DI float sigmoidf_(float x) { return frcp(1.f + fexp2(-x * LOG2E)); }
;     DI void operator()(const AccT& acc, const Unit& u, int wr, int wc, int fr, int fq) const {
; #pragma unroll
;         for (int ai = 0; ai < 2; ++ai)
; #pragma unroll
;             for (int m = 0; m < 4; ++m) {
;                 const size_t row = (size_t)u.pm * 256 + ai * 128 + wr * 64 + m * 16 + fr;
;                 float o[8];
; #pragma unroll
;                 for (int n = 0; n < 2; ++n) {
;                     const f32x4 g = acc[ai][0][m][n], up = acc[ai][1][m][n];
; #pragma unroll
;                     for (int e = 0; e < 4; ++e) o[4 * n + e] = g[e] * sigmoidf_(g[e]) * up[e];
;                 }
;                 u32x4 pk = {pack2(o[0], o[1]), pack2(o[2], o[3]), pack2(o[4], o[5]), pack2(o[6], o[7])};
;                 *(u32x4*)(O + row * DFF + u.pn * 128 + wc * 32 + 8 * fq) = pk;
;             }
	s_waitcnt lgkmcnt(0)
	s_setprio 1
	s_waitcnt lgkmcnt(0)
	v_mfma_f32_16x16x32_bf16 v[60:63], v[152:155], v[168:171], v[60:63]
	v_mfma_f32_16x16x32_bf16 v[56:59], v[160:163], v[168:171], v[56:59]
	v_mfma_f32_16x16x32_bf16 v[44:47], v[152:155], v[176:179], v[44:47]
	v_mfma_f32_16x16x32_bf16 v[40:43], v[160:163], v[176:179], v[40:43]
	v_mfma_f32_16x16x32_bf16 v[28:31], v[152:155], v[184:187], v[28:31]
	v_mfma_f32_16x16x32_bf16 v[24:27], v[160:163], v[184:187], v[24:27]
	v_mfma_f32_16x16x32_bf16 v[12:15], v[152:155], v[192:195], v[12:15]
	v_mfma_f32_16x16x32_bf16 v[8:11], v[160:163], v[192:195], v[8:11]
	v_mfma_f32_16x16x32_bf16 v[60:63], v[156:159], v[172:175], v[60:63]
	v_mfma_f32_16x16x32_bf16 v[56:59], v[164:167], v[172:175], v[56:59]
	v_mfma_f32_16x16x32_bf16 v[44:47], v[156:159], v[180:183], v[44:47]
	v_mfma_f32_16x16x32_bf16 v[40:43], v[164:167], v[180:183], v[40:43]
	v_mfma_f32_16x16x32_bf16 v[28:31], v[156:159], v[188:191], v[28:31]
	v_mfma_f32_16x16x32_bf16 v[24:27], v[164:167], v[188:191], v[24:27]
	v_mfma_f32_16x16x32_bf16 v[12:15], v[156:159], v[196:199], v[12:15]
	v_mfma_f32_16x16x32_bf16 v[8:11], v[164:167], v[196:199], v[8:11]
	s_setprio 0
	s_barrier
	s_add_u32 s28, s28, 0x40080
	s_addc_u32 s29, s29, 0
	s_add_i32 s30, s30, s39
	v_lshl_add_u64 v[152:153], s[28:29], 0, v[130:131]
	s_mov_b32 m0, s30
	s_nop 0
	global_load_lds_dwordx4 v[152:153], off
	v_lshl_add_u64 v[152:153], s[28:29], 0, v[134:135]
	s_add_i32 m0, s30, 0x2000
	s_nop 0
	global_load_lds_dwordx4 v[152:153], off
	s_waitcnt vmcnt(6)
	s_barrier
	s_setprio 1
	v_mfma_f32_16x16x32_bf16 v[52:55], v[202:205], v[168:171], v[52:55]
	v_mfma_f32_16x16x32_bf16 v[48:51], v[210:213], v[168:171], v[48:51]
	v_mfma_f32_16x16x32_bf16 v[36:39], v[202:205], v[176:179], v[36:39]
	v_mfma_f32_16x16x32_bf16 v[32:35], v[210:213], v[176:179], v[32:35]
	v_mfma_f32_16x16x32_bf16 v[20:23], v[202:205], v[184:187], v[20:23]
	v_mfma_f32_16x16x32_bf16 v[16:19], v[210:213], v[184:187], v[16:19]
	v_mfma_f32_16x16x32_bf16 v[4:7], v[202:205], v[192:195], v[4:7]
	v_mfma_f32_16x16x32_bf16 v[0:3], v[210:213], v[192:195], v[0:3]
	v_mfma_f32_16x16x32_bf16 v[52:55], v[206:209], v[172:175], v[52:55]
	v_mfma_f32_16x16x32_bf16 v[48:51], v[214:217], v[172:175], v[48:51]
	v_mfma_f32_16x16x32_bf16 v[36:39], v[206:209], v[180:183], v[36:39]
	v_mfma_f32_16x16x32_bf16 v[32:35], v[214:217], v[180:183], v[32:35]
	v_mfma_f32_16x16x32_bf16 v[20:23], v[206:209], v[188:191], v[20:23]
	v_mfma_f32_16x16x32_bf16 v[16:19], v[214:217], v[188:191], v[16:19]
	v_mfma_f32_16x16x32_bf16 v[4:7], v[206:209], v[196:199], v[4:7]
	v_mfma_f32_16x16x32_bf16 v[0:3], v[214:217], v[196:199], v[0:3]
	s_setprio 0
	s_add_i32 s68, s68, 2
	s_add_u32 s20, s20, 0x100
	s_addc_u32 s21, s21, 0
	s_add_u32 s66, s66, 0x100
	s_addc_u32 s67, s67, 0
	s_cmp_gt_u32 s68, 13
	s_barrier
	s_cbranch_scc0 .LBB0_101
	s_mov_b32 s98, 0xbfb8aa3b
	v_pk_mul_f32 v[152:153], v[124:125], s[98:99] op_sel_hi:[1,0]
	v_exp_f32_e32 v152, v152
	v_exp_f32_e32 v153, v153
	s_ashr_i32 s19, s18, 31
	s_lshl_b64 s[18:19], s[18:19], 8
	v_pk_add_f32 v[152:153], v[152:153], 1.0 op_sel_hi:[1,0]
	v_rcp_f32_e32 v152, v152
	v_rcp_f32_e32 v153, v153
	v_lshl_add_u64 v[154:155], v[138:139], 0, s[18:19]
	s_lshl_b32 s18, s64, 7
	s_ashr_i32 s19, s18, 31
	v_pk_mul_f32 v[124:125], v[124:125], v[152:153]
	v_pk_mul_f32 v[152:153], v[126:127], s[98:99] op_sel_hi:[1,0]
	v_exp_f32_e32 v152, v152
	v_exp_f32_e32 v153, v153
	v_pk_mul_f32 v[116:117], v[124:125], v[116:117]
	s_mov_b32 s64, s10
	v_pk_add_f32 v[124:125], v[152:153], 1.0 op_sel_hi:[1,0]
	v_pk_mul_f32 v[152:153], v[120:121], s[98:99] op_sel_hi:[1,0]
	v_rcp_f32_e32 v124, v124
	v_rcp_f32_e32 v125, v125
	v_exp_f32_e32 v152, v152
	v_exp_f32_e32 v153, v153
	s_mov_b64 s[28:29], s[16:17]
	v_pk_mul_f32 v[124:125], v[126:127], v[124:125]
	v_pk_add_f32 v[126:127], v[152:153], 1.0 op_sel_hi:[1,0]
	v_pk_mul_f32 v[152:153], v[122:123], s[98:99] op_sel_hi:[1,0]
	v_exp_f32_e32 v152, v152
	v_exp_f32_e32 v153, v153
	v_rcp_f32_e32 v126, v126
	v_rcp_f32_e32 v127, v127
	v_pk_add_f32 v[152:153], v[152:153], 1.0 op_sel_hi:[1,0]
	v_rcp_f32_e32 v152, v152
	v_rcp_f32_e32 v153, v153
	v_pk_mul_f32 v[120:121], v[120:121], v[126:127]
	v_pk_mul_f32 v[118:119], v[124:125], v[118:119]
	v_pk_mul_f32 v[112:113], v[120:121], v[112:113]
	v_pk_mul_f32 v[120:121], v[122:123], v[152:153]
	s_nop 0
	v_pk_mul_f32 v[120:121], v[120:121], v[114:115]
	v_cvt_pk_bf16_f32 v114, v116, v117
	v_cvt_pk_bf16_f32 v116, v112, v113
	v_mov_b64_e32 v[112:113], s[22:23]
	v_mad_u64_u32 v[112:113], s[20:21], v154, s55, v[112:113]
	v_cvt_pk_bf16_f32 v115, v118, v119
	v_mov_b32_e32 v118, v113
	v_mad_u64_u32 v[118:119], s[20:21], v155, s55, v[118:119]
	v_mov_b32_e32 v113, v118
	v_pk_mul_f32 v[118:119], v[108:109], s[98:99] op_sel_hi:[1,0]
	v_exp_f32_e32 v118, v118
	v_exp_f32_e32 v119, v119
	v_lshl_add_u64 v[112:113], s[18:19], 1, v[112:113]
	v_lshl_add_u64 v[112:113], v[112:113], 0, s[6:7]
	v_cvt_pk_bf16_f32 v117, v120, v121
	v_pk_add_f32 v[118:119], v[118:119], 1.0 op_sel_hi:[1,0]
	v_lshl_add_u64 v[112:113], v[112:113], 0, v[136:137]
	v_rcp_f32_e32 v118, v118
	v_rcp_f32_e32 v119, v119
	global_store_dwordx4 v[112:113], v[114:117], off
	s_mov_b32 s18, s12
	s_mov_b64 s[20:21], s[14:15]
	v_pk_mul_f32 v[114:115], v[110:111], s[98:99] op_sel_hi:[1,0]
	v_exp_f32_e32 v114, v114
	v_exp_f32_e32 v115, v115
	v_pk_mul_f32 v[108:109], v[108:109], v[118:119]
	s_nop 0
	v_pk_mul_f32 v[100:101], v[108:109], v[100:101]
	v_pk_add_f32 v[108:109], v[114:115], 1.0 op_sel_hi:[1,0]
	v_pk_mul_f32 v[114:115], v[104:105], s[98:99] op_sel_hi:[1,0]
	v_rcp_f32_e32 v108, v108
	v_rcp_f32_e32 v109, v109
	v_exp_f32_e32 v114, v114
; DI unsigned pack2(float lo, float hi) { f32x2 v = {lo, hi}; bf16v2 r = __builtin_convertvector(v, bf16v2); return __builtin_bit_cast(unsigned, r); }
; DI float fexp2(float x) { return __builtin_amdgcn_exp2f(x); }
; DI float frcp(float x) { return __builtin_amdgcn_rcpf(x); }
; DI float sigmoidf_(float x) { return frcp(1.f + fexp2(-x * LOG2E)); }
;     DI void operator()(const AccT& acc, const Unit& u, int wr, int wc, int fr, int fq) const {
; #pragma unroll
;         for (int ai = 0; ai < 2; ++ai)
; #pragma unroll
;             for (int m = 0; m < 4; ++m) {
;                 const size_t row = (size_t)u.pm * 256 + ai * 128 + wr * 64 + m * 16 + fr;
;                 float o[8];
; #pragma unroll
;                 for (int n = 0; n < 2; ++n) {
;                     const f32x4 g = acc[ai][0][m][n], up = acc[ai][1][m][n];
; #pragma unroll
;                     for (int e = 0; e < 4; ++e) o[4 * n + e] = g[e] * sigmoidf_(g[e]) * up[e];
;                 }
;                 u32x4 pk = {pack2(o[0], o[1]), pack2(o[2], o[3]), pack2(o[4], o[5]), pack2(o[6], o[7])};
;                 *(u32x4*)(O + row * DFF + u.pn * 128 + wc * 32 + 8 * fq) = pk;
;             }
	v_exp_f32_e32 v115, v115
	v_pk_mul_f32 v[108:109], v[110:111], v[108:109]
	v_pk_add_f32 v[110:111], v[114:115], 1.0 op_sel_hi:[1,0]
	v_pk_mul_f32 v[114:115], v[106:107], s[98:99] op_sel_hi:[1,0]
	v_exp_f32_e32 v114, v114
	v_exp_f32_e32 v115, v115
	v_rcp_f32_e32 v110, v110
	v_rcp_f32_e32 v111, v111
	v_pk_add_f32 v[114:115], v[114:115], 1.0 op_sel_hi:[1,0]
	v_rcp_f32_e32 v114, v114
	v_rcp_f32_e32 v115, v115
	v_pk_mul_f32 v[104:105], v[104:105], v[110:111]
	v_pk_mul_f32 v[102:103], v[108:109], v[102:103]
	v_pk_mul_f32 v[104:105], v[104:105], v[96:97]
	v_pk_mul_f32 v[96:97], v[106:107], v[114:115]
	s_nop 0
	v_pk_mul_f32 v[106:107], v[96:97], v[98:99]
	v_mul_f32_e32 v99, 0xbfb8aa3b, v92
	v_cvt_pk_bf16_f32 v96, v100, v101
	v_exp_f32_e32 v100, v99
	v_mul_f32_e32 v99, 0xbfb8aa3b, v93
	v_exp_f32_e32 v101, v99
	v_cvt_pk_bf16_f32 v97, v102, v103
	v_add_co_u32_e32 v102, vcc, s49, v112
	v_cvt_pk_bf16_f32 v98, v104, v105
	v_cvt_pk_bf16_f32 v99, v106, v107
	v_pk_add_f32 v[100:101], v[100:101], 1.0 op_sel_hi:[1,0]
	v_addc_co_u32_e32 v103, vcc, 0, v113, vcc
	v_rcp_f32_e32 v100, v100
	v_rcp_f32_e32 v101, v101
	global_store_dwordx4 v[102:103], v[96:99], off
	v_pk_mul_f32 v[92:93], v[92:93], v[100:101]
	s_nop 0
	v_pk_mul_f32 v[96:97], v[94:95], s[98:99] op_sel_hi:[1,0]
	v_exp_f32_e32 v96, v96
	v_exp_f32_e32 v97, v97
	v_pk_mul_f32 v[84:85], v[92:93], v[84:85]
	v_pk_add_f32 v[92:93], v[96:97], 1.0 op_sel_hi:[1,0]
	v_pk_mul_f32 v[96:97], v[88:89], s[98:99] op_sel_hi:[1,0]
	v_rcp_f32_e32 v92, v92
	v_rcp_f32_e32 v93, v93
	v_exp_f32_e32 v96, v96
	v_exp_f32_e32 v97, v97
	v_pk_mul_f32 v[92:93], v[94:95], v[92:93]
	v_pk_add_f32 v[94:95], v[96:97], 1.0 op_sel_hi:[1,0]
	v_pk_mul_f32 v[96:97], v[90:91], s[98:99] op_sel_hi:[1,0]
	v_exp_f32_e32 v96, v96
	v_exp_f32_e32 v97, v97
	v_rcp_f32_e32 v94, v94
	v_rcp_f32_e32 v95, v95
	v_pk_add_f32 v[96:97], v[96:97], 1.0 op_sel_hi:[1,0]
	v_rcp_f32_e32 v96, v96
	v_rcp_f32_e32 v97, v97
	v_pk_mul_f32 v[88:89], v[88:89], v[94:95]
	v_pk_mul_f32 v[86:87], v[92:93], v[86:87]
	v_pk_mul_f32 v[88:89], v[88:89], v[80:81]
	v_pk_mul_f32 v[80:81], v[90:91], v[96:97]
	s_nop 0
	v_pk_mul_f32 v[90:91], v[80:81], v[82:83]
	v_mul_f32_e32 v83, 0xbfb8aa3b, v76
	v_cvt_pk_bf16_f32 v80, v84, v85
	v_exp_f32_e32 v84, v83
	v_mul_f32_e32 v83, 0xbfb8aa3b, v77
	v_exp_f32_e32 v85, v83
	v_cvt_pk_bf16_f32 v81, v86, v87
	v_add_co_u32_e32 v86, vcc, s58, v112
	v_cvt_pk_bf16_f32 v82, v88, v89
	v_cvt_pk_bf16_f32 v83, v90, v91
	v_pk_add_f32 v[84:85], v[84:85], 1.0 op_sel_hi:[1,0]
	v_addc_co_u32_e32 v87, vcc, 0, v113, vcc
	v_rcp_f32_e32 v84, v84
	v_rcp_f32_e32 v85, v85
	global_store_dwordx4 v[86:87], v[80:83], off
	v_pk_mul_f32 v[76:77], v[76:77], v[84:85]
	s_nop 0
	v_pk_mul_f32 v[80:81], v[78:79], s[98:99] op_sel_hi:[1,0]
	v_exp_f32_e32 v80, v80
	v_exp_f32_e32 v81, v81
	v_pk_mul_f32 v[68:69], v[76:77], v[68:69]
	v_pk_add_f32 v[76:77], v[80:81], 1.0 op_sel_hi:[1,0]
	v_pk_mul_f32 v[80:81], v[72:73], s[98:99] op_sel_hi:[1,0]
	v_rcp_f32_e32 v76, v76
	v_rcp_f32_e32 v77, v77
	v_exp_f32_e32 v80, v80
	v_exp_f32_e32 v81, v81
	v_pk_mul_f32 v[76:77], v[78:79], v[76:77]
	v_pk_add_f32 v[78:79], v[80:81], 1.0 op_sel_hi:[1,0]
	v_pk_mul_f32 v[80:81], v[74:75], s[98:99] op_sel_hi:[1,0]
	v_exp_f32_e32 v80, v80
	v_exp_f32_e32 v81, v81
	v_rcp_f32_e32 v78, v78
	v_rcp_f32_e32 v79, v79
	v_pk_add_f32 v[80:81], v[80:81], 1.0 op_sel_hi:[1,0]
	v_rcp_f32_e32 v80, v80
	v_rcp_f32_e32 v81, v81
	v_pk_mul_f32 v[72:73], v[72:73], v[78:79]
	v_pk_mul_f32 v[70:71], v[76:77], v[70:71]
	v_pk_mul_f32 v[72:73], v[72:73], v[64:65]
	v_pk_mul_f32 v[64:65], v[74:75], v[80:81]
	s_nop 0
	v_pk_mul_f32 v[74:75], v[64:65], v[66:67]
	v_mul_f32_e32 v67, 0xbfb8aa3b, v60
	v_cvt_pk_bf16_f32 v64, v68, v69
	v_exp_f32_e32 v68, v67
	v_mul_f32_e32 v67, 0xbfb8aa3b, v61
	v_exp_f32_e32 v69, v67
	v_cvt_pk_bf16_f32 v65, v70, v71
	v_add_co_u32_e32 v70, vcc, s59, v112
	v_cvt_pk_bf16_f32 v66, v72, v73
	v_cvt_pk_bf16_f32 v67, v74, v75
	v_pk_add_f32 v[68:69], v[68:69], 1.0 op_sel_hi:[1,0]
	v_addc_co_u32_e32 v71, vcc, 0, v113, vcc
	v_rcp_f32_e32 v68, v68
	v_rcp_f32_e32 v69, v69
	global_store_dwordx4 v[70:71], v[64:67], off
	v_pk_mul_f32 v[60:61], v[60:61], v[68:69]
	s_nop 0
	v_pk_mul_f32 v[64:65], v[62:63], s[98:99] op_sel_hi:[1,0]
	v_exp_f32_e32 v64, v64
	v_exp_f32_e32 v65, v65
	v_pk_mul_f32 v[52:53], v[60:61], v[52:53]
	v_pk_add_f32 v[60:61], v[64:65], 1.0 op_sel_hi:[1,0]
	v_pk_mul_f32 v[64:65], v[56:57], s[98:99] op_sel_hi:[1,0]
	v_rcp_f32_e32 v60, v60
	v_rcp_f32_e32 v61, v61
	v_exp_f32_e32 v64, v64
	v_exp_f32_e32 v65, v65
	v_pk_mul_f32 v[60:61], v[62:63], v[60:61]
	v_pk_add_f32 v[62:63], v[64:65], 1.0 op_sel_hi:[1,0]
	v_pk_mul_f32 v[64:65], v[58:59], s[98:99] op_sel_hi:[1,0]
	v_exp_f32_e32 v64, v64
	v_exp_f32_e32 v65, v65
	v_rcp_f32_e32 v62, v62
	v_rcp_f32_e32 v63, v63
	v_pk_add_f32 v[64:65], v[64:65], 1.0 op_sel_hi:[1,0]
	v_rcp_f32_e32 v64, v64
	v_rcp_f32_e32 v65, v65
	v_pk_mul_f32 v[56:57], v[56:57], v[62:63]
	v_pk_mul_f32 v[54:55], v[60:61], v[54:55]
; DI unsigned pack2(float lo, float hi) { f32x2 v = {lo, hi}; bf16v2 r = __builtin_convertvector(v, bf16v2); return __builtin_bit_cast(unsigned, r); }
; DI float fexp2(float x) { return __builtin_amdgcn_exp2f(x); }
; DI float frcp(float x) { return __builtin_amdgcn_rcpf(x); }
; DI float sigmoidf_(float x) { return frcp(1.f + fexp2(-x * LOG2E)); }
;     DI void operator()(const AccT& acc, const Unit& u, int wr, int wc, int fr, int fq) const {
; #pragma unroll
;         for (int ai = 0; ai < 2; ++ai)
; #pragma unroll
;             for (int m = 0; m < 4; ++m) {
;                 const size_t row = (size_t)u.pm * 256 + ai * 128 + wr * 64 + m * 16 + fr;
;                 float o[8];
; #pragma unroll
;                 for (int n = 0; n < 2; ++n) {
;                     const f32x4 g = acc[ai][0][m][n], up = acc[ai][1][m][n];
; #pragma unroll
;                     for (int e = 0; e < 4; ++e) o[4 * n + e] = g[e] * sigmoidf_(g[e]) * up[e];
;                 }
;                 u32x4 pk = {pack2(o[0], o[1]), pack2(o[2], o[3]), pack2(o[4], o[5]), pack2(o[6], o[7])};
;                 *(u32x4*)(O + row * DFF + u.pn * 128 + wc * 32 + 8 * fq) = pk;
;             }
	v_pk_mul_f32 v[56:57], v[56:57], v[48:49]
	v_pk_mul_f32 v[48:49], v[58:59], v[64:65]
	s_nop 0
	v_pk_mul_f32 v[58:59], v[48:49], v[50:51]
	v_mul_f32_e32 v51, 0xbfb8aa3b, v44
	v_cvt_pk_bf16_f32 v48, v52, v53
	v_exp_f32_e32 v52, v51
	v_mul_f32_e32 v51, 0xbfb8aa3b, v45
	v_exp_f32_e32 v53, v51
	v_cvt_pk_bf16_f32 v49, v54, v55
	v_add_co_u32_e32 v54, vcc, s60, v112
	v_cvt_pk_bf16_f32 v50, v56, v57
	v_cvt_pk_bf16_f32 v51, v58, v59
	v_pk_add_f32 v[52:53], v[52:53], 1.0 op_sel_hi:[1,0]
	v_addc_co_u32_e32 v55, vcc, 0, v113, vcc
	v_rcp_f32_e32 v52, v52
	v_rcp_f32_e32 v53, v53
	global_store_dwordx4 v[54:55], v[48:51], off
	v_pk_mul_f32 v[44:45], v[44:45], v[52:53]
	s_nop 0
	v_pk_mul_f32 v[48:49], v[46:47], s[98:99] op_sel_hi:[1,0]
	v_exp_f32_e32 v48, v48
	v_exp_f32_e32 v49, v49
	v_pk_mul_f32 v[36:37], v[44:45], v[36:37]
	v_pk_add_f32 v[44:45], v[48:49], 1.0 op_sel_hi:[1,0]
	v_pk_mul_f32 v[48:49], v[40:41], s[98:99] op_sel_hi:[1,0]
	v_rcp_f32_e32 v44, v44
	v_rcp_f32_e32 v45, v45
	v_exp_f32_e32 v48, v48
	v_exp_f32_e32 v49, v49
	v_pk_mul_f32 v[44:45], v[46:47], v[44:45]
	v_pk_add_f32 v[46:47], v[48:49], 1.0 op_sel_hi:[1,0]
	v_pk_mul_f32 v[48:49], v[42:43], s[98:99] op_sel_hi:[1,0]
	v_exp_f32_e32 v48, v48
	v_exp_f32_e32 v49, v49
	v_rcp_f32_e32 v46, v46
	v_rcp_f32_e32 v47, v47
	v_pk_add_f32 v[48:49], v[48:49], 1.0 op_sel_hi:[1,0]
	v_rcp_f32_e32 v48, v48
	v_rcp_f32_e32 v49, v49
	v_pk_mul_f32 v[40:41], v[40:41], v[46:47]
	v_pk_mul_f32 v[38:39], v[44:45], v[38:39]
	v_pk_mul_f32 v[40:41], v[40:41], v[32:33]
	v_pk_mul_f32 v[32:33], v[42:43], v[48:49]
	s_nop 0
	v_pk_mul_f32 v[42:43], v[32:33], v[34:35]
	v_mul_f32_e32 v35, 0xbfb8aa3b, v28
	v_cvt_pk_bf16_f32 v32, v36, v37
	v_exp_f32_e32 v36, v35
	v_mul_f32_e32 v35, 0xbfb8aa3b, v29
	v_exp_f32_e32 v37, v35
	v_cvt_pk_bf16_f32 v33, v38, v39
	v_add_co_u32_e32 v38, vcc, s61, v112
	v_cvt_pk_bf16_f32 v34, v40, v41
	v_cvt_pk_bf16_f32 v35, v42, v43
	v_pk_add_f32 v[36:37], v[36:37], 1.0 op_sel_hi:[1,0]
	v_addc_co_u32_e32 v39, vcc, 0, v113, vcc
	v_rcp_f32_e32 v36, v36
	v_rcp_f32_e32 v37, v37
	global_store_dwordx4 v[38:39], v[32:35], off
	v_pk_mul_f32 v[28:29], v[28:29], v[36:37]
	s_nop 0
	v_pk_mul_f32 v[32:33], v[30:31], s[98:99] op_sel_hi:[1,0]
	v_exp_f32_e32 v32, v32
	v_exp_f32_e32 v33, v33
	v_pk_mul_f32 v[20:21], v[28:29], v[20:21]
	v_pk_add_f32 v[28:29], v[32:33], 1.0 op_sel_hi:[1,0]
	v_pk_mul_f32 v[32:33], v[24:25], s[98:99] op_sel_hi:[1,0]
	v_rcp_f32_e32 v28, v28
	v_rcp_f32_e32 v29, v29
	v_exp_f32_e32 v32, v32
	v_exp_f32_e32 v33, v33
	v_pk_mul_f32 v[28:29], v[30:31], v[28:29]
	v_pk_add_f32 v[30:31], v[32:33], 1.0 op_sel_hi:[1,0]
	v_pk_mul_f32 v[32:33], v[26:27], s[98:99] op_sel_hi:[1,0]
	v_exp_f32_e32 v32, v32
	v_exp_f32_e32 v33, v33
	v_rcp_f32_e32 v30, v30
	v_rcp_f32_e32 v31, v31
	v_pk_add_f32 v[32:33], v[32:33], 1.0 op_sel_hi:[1,0]
	v_rcp_f32_e32 v32, v32
	v_rcp_f32_e32 v33, v33
	v_pk_mul_f32 v[24:25], v[24:25], v[30:31]
	v_pk_mul_f32 v[22:23], v[28:29], v[22:23]
	v_pk_mul_f32 v[24:25], v[24:25], v[16:17]
	v_pk_mul_f32 v[16:17], v[26:27], v[32:33]
	s_nop 0
	v_pk_mul_f32 v[26:27], v[16:17], v[18:19]
	v_mul_f32_e32 v19, 0xbfb8aa3b, v12
	v_cvt_pk_bf16_f32 v16, v20, v21
	v_exp_f32_e32 v20, v19
	v_mul_f32_e32 v19, 0xbfb8aa3b, v13
	v_exp_f32_e32 v21, v19
	v_cvt_pk_bf16_f32 v17, v22, v23
	v_add_co_u32_e32 v22, vcc, s62, v112
	v_cvt_pk_bf16_f32 v18, v24, v25
	v_cvt_pk_bf16_f32 v19, v26, v27
	v_pk_add_f32 v[20:21], v[20:21], 1.0 op_sel_hi:[1,0]
	v_addc_co_u32_e32 v23, vcc, 0, v113, vcc
	v_rcp_f32_e32 v20, v20
	v_rcp_f32_e32 v21, v21
	global_store_dwordx4 v[22:23], v[16:19], off
	v_pk_mul_f32 v[12:13], v[12:13], v[20:21]
	s_nop 0
	v_pk_mul_f32 v[16:17], v[14:15], s[98:99] op_sel_hi:[1,0]
	v_exp_f32_e32 v16, v16
	v_exp_f32_e32 v17, v17
	v_pk_mul_f32 v[4:5], v[12:13], v[4:5]
	v_pk_add_f32 v[12:13], v[16:17], 1.0 op_sel_hi:[1,0]
	v_pk_mul_f32 v[16:17], v[8:9], s[98:99] op_sel_hi:[1,0]
	v_rcp_f32_e32 v12, v12
	v_rcp_f32_e32 v13, v13
	v_exp_f32_e32 v16, v16
	v_exp_f32_e32 v17, v17
	v_pk_mul_f32 v[12:13], v[14:15], v[12:13]
	v_pk_add_f32 v[14:15], v[16:17], 1.0 op_sel_hi:[1,0]
	v_pk_mul_f32 v[16:17], v[10:11], s[98:99] op_sel_hi:[1,0]
	v_exp_f32_e32 v16, v16
	v_exp_f32_e32 v17, v17
	v_rcp_f32_e32 v14, v14
	v_rcp_f32_e32 v15, v15
	v_pk_add_f32 v[16:17], v[16:17], 1.0 op_sel_hi:[1,0]
	v_rcp_f32_e32 v16, v16
	v_rcp_f32_e32 v17, v17
	v_pk_mul_f32 v[8:9], v[8:9], v[14:15]
	v_pk_mul_f32 v[6:7], v[12:13], v[6:7]
	v_pk_mul_f32 v[8:9], v[8:9], v[0:1]
	v_pk_mul_f32 v[0:1], v[10:11], v[16:17]
	s_nop 0
	v_pk_mul_f32 v[10:11], v[0:1], v[2:3]
	v_cvt_pk_bf16_f32 v0, v4, v5
	v_add_co_u32_e32 v4, vcc, 0xf2000, v112
	v_cvt_pk_bf16_f32 v1, v6, v7
	s_nop 0
	v_addc_co_u32_e32 v5, vcc, 0, v113, vcc
	v_cvt_pk_bf16_f32 v2, v8, v9
	v_cvt_pk_bf16_f32 v3, v10, v11
	s_and_b64 vcc, exec, s[4:5]
	global_store_dwordx4 v[4:5], v[0:3], off
	s_cbranch_vccz .LBB0_94
	s_waitcnt vmcnt(0)
	s_cmpk_gt_u32 s36, 0xff
	s_cbranch_scc1 .LBB0_105
	s_barrier

; #define PG8_STAGE(bufoff, gbase, voff) do { _Pragma("unroll") for (int _i = 0; _i < 2; ++_i) \
;         __builtin_amdgcn_global_load_lds((const unsigned*)((const char*)(gbase) + (voff)[_i]), (LAS unsigned*)(lds + (bufoff) + ldsw + _i * 8192), 16, 0, 0); } while (0)
; #define PG8_LDA(dst, b, h) do { _Pragma("unroll") for (int m = 0; m < 4; ++m) _Pragma("unroll") for (int k = 0; k < 2; ++k) dst[m][k] = *(const LAS bf16x8*)(lds + PG8_SA(b, h) + aoff + m * 2048 + k * 1024); } while (0)
; #define PG8_LDB(dst, b, h) do { _Pragma("unroll") for (int n = 0; n < 2; ++n) _Pragma("unroll") for (int k = 0; k < 2; ++k) dst[n][k] = *(const LAS bf16x8*)(lds + PG8_SB(b, h) + boff + n * 2048 + k * 1024); } while (0)
; #define PG8_MMA(ai, bj, At, Bt) do { __builtin_amdgcn_s_setprio(1); _Pragma("unroll") for (int m = 0; m < 4; ++m) _Pragma("unroll") for (int n = 0; n < 2; ++n) _Pragma("unroll") for (int k = 0; k < 2; ++k) \
;         acc[ai][bj][m][n] = __builtin_amdgcn_mfma_f32_16x16x32_bf16(Bt[n][k], At[m][k], acc[ai][bj][m][n], 0, 0, 0); __builtin_amdgcn_s_setprio(0); } while (0)
; #define PG8_WAIT_L(n) asm volatile("s_waitcnt lgkmcnt(" #n ")" ::: "memory")
; #define PG8_BAR __builtin_amdgcn_s_barrier()
; #define PG8_SCHED __builtin_amdgcn_sched_barrier(0)
; template <class Epi>
; DI void gemm_phase(int wv, LAS unsigned char* lds, const Gemm g, const StaticOrder& S, const Epi& E) {
;     ...
;         for (int t = 0; t < nt; t += 2) {
;             const bool last = (t == nt - 2);
;             const char* a1 = cA + (size_t)(t + 1) * kstep;
;             const char* a2 = last ? nA : cA + (size_t)(t + 2) * kstep; const char* b2 = last ? nB : cB + (size_t)(t + 2) * kstep;
;             const char* a3 = a2 + kstep; const char* b3 = b2 + kstep;
;             PG8_LDB(B0, 0, 0); PG8_SCHED; PG8_LDA(At, 0, 0); PG8_STAGE(PG8_SA(1, 1), a1 + hstep, voffA);
;             PG8_WAIT_L(8); PG8_BAR; PG8_WAIT_L(0); PG8_MMA(0, 0, At, B0); PG8_BAR; PG8_SCHED;
;             PG8_LDB(B1, 0, 1); PG8_STAGE(PG8_SB(0, 0), b2, voffB);
;             PG8_BAR; PG8_WAIT_L(0); PG8_MMA(0, 1, At, B1); PG8_BAR;
;             PG8_LDA(At, 0, 1); PG8_STAGE(PG8_SA(0, 0), a2, voffA);
;             PG8_BAR; PG8_WAIT_L(0); PG8_MMA(1, 0, At, B0); PG8_BAR; PG8_SCHED;
.LBB0_1530:
	ds_read_b128 v[152:155], v149
	ds_read_b128 v[156:159], v149 offset:1024
	ds_read_b128 v[160:163], v149 offset:2048
	ds_read_b128 v[164:167], v149 offset:3072
	s_add_u32 s60, s58, 0xfffc0080
	s_addc_u32 s61, s59, -1
	s_cmp_eq_u32 s79, 12
	s_cselect_b32 s63, s31, s61
	s_cselect_b32 s62, s57, s60
	s_cselect_b32 s61, s29, s78
	s_cselect_b32 s60, s76, s77
	v_lshl_add_u64 v[200:201], s[58:59], 0, v[140:141]
	s_add_i32 m0, s41, 0xc000
	ds_read_b128 v[168:171], v150
	ds_read_b128 v[172:175], v150 offset:1024
	ds_read_b128 v[176:179], v150 offset:2048
	ds_read_b128 v[180:183], v150 offset:3072
	ds_read_b128 v[184:187], v150 offset:4096
	ds_read_b128 v[188:191], v150 offset:5120
	ds_read_b128 v[192:195], v150 offset:6144
	ds_read_b128 v[196:199], v150 offset:7168
	global_load_lds_dwordx4 v[200:201], off
	v_lshl_add_u64 v[200:201], s[58:59], 0, v[142:143]
	s_add_i32 m0, s41, 0xe000
	s_nop 0
	global_load_lds_dwordx4 v[200:201], off
	s_waitcnt lgkmcnt(8)
	s_barrier
	s_waitcnt lgkmcnt(0)
	s_setprio 1
	s_waitcnt lgkmcnt(0)
	v_mfma_f32_16x16x32_bf16 v[124:127], v[152:155], v[168:171], v[124:127]
	v_mfma_f32_16x16x32_bf16 v[120:123], v[160:163], v[168:171], v[120:123]
	v_mfma_f32_16x16x32_bf16 v[108:111], v[152:155], v[176:179], v[108:111]
	v_mfma_f32_16x16x32_bf16 v[104:107], v[160:163], v[176:179], v[104:107]
	v_mfma_f32_16x16x32_bf16 v[92:95], v[152:155], v[184:187], v[92:95]
	v_mfma_f32_16x16x32_bf16 v[88:91], v[160:163], v[184:187], v[88:91]
	v_mfma_f32_16x16x32_bf16 v[76:79], v[152:155], v[192:195], v[76:79]
	v_mfma_f32_16x16x32_bf16 v[72:75], v[160:163], v[192:195], v[72:75]
	v_mfma_f32_16x16x32_bf16 v[124:127], v[156:159], v[172:175], v[124:127]
	v_mfma_f32_16x16x32_bf16 v[120:123], v[164:167], v[172:175], v[120:123]
	v_mfma_f32_16x16x32_bf16 v[108:111], v[156:159], v[180:183], v[108:111]
	v_mfma_f32_16x16x32_bf16 v[104:107], v[164:167], v[180:183], v[104:107]
	v_mfma_f32_16x16x32_bf16 v[92:95], v[156:159], v[188:191], v[92:95]
	v_mfma_f32_16x16x32_bf16 v[88:91], v[164:167], v[188:191], v[88:91]
	v_mfma_f32_16x16x32_bf16 v[76:79], v[156:159], v[196:199], v[76:79]
	v_mfma_f32_16x16x32_bf16 v[72:75], v[164:167], v[196:199], v[72:75]
	s_setprio 0
	s_barrier
	s_add_i32 s80, s66, s11
	v_lshl_add_u64 v[216:217], s[60:61], 0, v[130:131]
	s_mov_b32 m0, s80
	ds_read_b128 v[200:203], v151
	ds_read_b128 v[204:207], v151 offset:1024
	ds_read_b128 v[208:211], v151 offset:2048
	ds_read_b128 v[212:215], v151 offset:3072
	global_load_lds_dwordx4 v[216:217], off
	v_lshl_add_u64 v[218:219], s[60:61], 0, v[134:135]
	s_add_i32 m0, s80, 0x2000
	s_nop 0
	global_load_lds_dwordx4 v[218:219], off
	s_barrier
	s_waitcnt lgkmcnt(0)
	s_setprio 1
	s_waitcnt lgkmcnt(0)
	v_mfma_f32_16x16x32_bf16 v[116:119], v[200:203], v[168:171], v[116:119]
	v_mfma_f32_16x16x32_bf16 v[112:115], v[208:211], v[168:171], v[112:115]
	v_mfma_f32_16x16x32_bf16 v[100:103], v[200:203], v[176:179], v[100:103]
	v_mfma_f32_16x16x32_bf16 v[96:99], v[208:211], v[176:179], v[96:99]
	v_mfma_f32_16x16x32_bf16 v[84:87], v[200:203], v[184:187], v[84:87]
	v_mfma_f32_16x16x32_bf16 v[80:83], v[208:211], v[184:187], v[80:83]
	v_mfma_f32_16x16x32_bf16 v[68:71], v[200:203], v[192:195], v[68:71]
	v_mfma_f32_16x16x32_bf16 v[64:67], v[208:211], v[192:195], v[64:67]
	v_mfma_f32_16x16x32_bf16 v[116:119], v[204:207], v[172:175], v[116:119]
	v_mfma_f32_16x16x32_bf16 v[112:115], v[212:215], v[172:175], v[112:115]
	v_mfma_f32_16x16x32_bf16 v[100:103], v[204:207], v[180:183], v[100:103]
	v_mfma_f32_16x16x32_bf16 v[96:99], v[212:215], v[180:183], v[96:99]
	v_mfma_f32_16x16x32_bf16 v[84:87], v[204:207], v[188:191], v[84:87]
	v_mfma_f32_16x16x32_bf16 v[80:83], v[212:215], v[188:191], v[80:83]
	v_mfma_f32_16x16x32_bf16 v[68:71], v[204:207], v[196:199], v[68:71]
	v_mfma_f32_16x16x32_bf16 v[64:67], v[212:215], v[196:199], v[64:67]
	s_setprio 0
	s_mov_b32 m0, s41
	v_lshl_add_u64 v[220:221], s[62:63], 0, v[128:129]
	s_barrier
	ds_read_b128 v[168:171], v150 offset:16384
	ds_read_b128 v[172:175], v150 offset:17408
	ds_read_b128 v[176:179], v150 offset:18432
	ds_read_b128 v[180:183], v150 offset:19456
	ds_read_b128 v[184:187], v150 offset:20480
	ds_read_b128 v[188:191], v150 offset:21504
	ds_read_b128 v[192:195], v150 offset:22528
	ds_read_b128 v[196:199], v150 offset:23552
	global_load_lds_dwordx4 v[220:221], off
	v_lshl_add_u64 v[222:223], s[62:63], 0, v[132:133]
	s_mov_b32 m0, s50
	s_nop 0
	global_load_lds_dwordx4 v[222:223], off
	s_barrier
	s_waitcnt lgkmcnt(0)
	s_setprio 1
	s_waitcnt lgkmcnt(0)
	v_mfma_f32_16x16x32_bf16 v[60:63], v[152:155], v[168:171], v[60:63]
	v_mfma_f32_16x16x32_bf16 v[56:59], v[160:163], v[168:171], v[56:59]
	v_mfma_f32_16x16x32_bf16 v[44:47], v[152:155], v[176:179], v[44:47]
	v_mfma_f32_16x16x32_bf16 v[40:43], v[160:163], v[176:179], v[40:43]
	v_mfma_f32_16x16x32_bf16 v[28:31], v[152:155], v[184:187], v[28:31]
	v_mfma_f32_16x16x32_bf16 v[24:27], v[160:163], v[184:187], v[24:27]
	v_mfma_f32_16x16x32_bf16 v[12:15], v[152:155], v[192:195], v[12:15]
	v_mfma_f32_16x16x32_bf16 v[8:11], v[160:163], v[192:195], v[8:11]
	v_mfma_f32_16x16x32_bf16 v[60:63], v[156:159], v[172:175], v[60:63]
	v_mfma_f32_16x16x32_bf16 v[56:59], v[164:167], v[172:175], v[56:59]
	v_mfma_f32_16x16x32_bf16 v[44:47], v[156:159], v[180:183], v[44:47]
	v_mfma_f32_16x16x32_bf16 v[40:43], v[164:167], v[180:183], v[40:43]
	v_mfma_f32_16x16x32_bf16 v[28:31], v[156:159], v[188:191], v[28:31]
	v_mfma_f32_16x16x32_bf16 v[24:27], v[164:167], v[188:191], v[24:27]
	v_mfma_f32_16x16x32_bf16 v[12:15], v[156:159], v[196:199], v[12:15]
	v_mfma_f32_16x16x32_bf16 v[8:11], v[164:167], v[196:199], v[8:11]
	s_setprio 0
	s_barrier
; #define PG8_STAGE(bufoff, gbase, voff) do { _Pragma("unroll") for (int _i = 0; _i < 2; ++_i) \
;         __builtin_amdgcn_global_load_lds((const unsigned*)((const char*)(gbase) + (voff)[_i]), (LAS unsigned*)(lds + (bufoff) + ldsw + _i * 8192), 16, 0, 0); } while (0)
; #define PG8_LDA(dst, b, h) do { _Pragma("unroll") for (int m = 0; m < 4; ++m) _Pragma("unroll") for (int k = 0; k < 2; ++k) dst[m][k] = *(const LAS bf16x8*)(lds + PG8_SA(b, h) + aoff + m * 2048 + k * 1024); } while (0)
; #define PG8_LDB(dst, b, h) do { _Pragma("unroll") for (int n = 0; n < 2; ++n) _Pragma("unroll") for (int k = 0; k < 2; ++k) dst[n][k] = *(const LAS bf16x8*)(lds + PG8_SB(b, h) + boff + n * 2048 + k * 1024); } while (0)
; #define PG8_MMA(ai, bj, At, Bt) do { __builtin_amdgcn_s_setprio(1); _Pragma("unroll") for (int m = 0; m < 4; ++m) _Pragma("unroll") for (int n = 0; n < 2; ++n) _Pragma("unroll") for (int k = 0; k < 2; ++k) \
;         acc[ai][bj][m][n] = __builtin_amdgcn_mfma_f32_16x16x32_bf16(Bt[n][k], At[m][k], acc[ai][bj][m][n], 0, 0, 0); __builtin_amdgcn_s_setprio(0); } while (0)
; #define PG8_WAIT_V(n) asm volatile("s_waitcnt vmcnt(" #n ")" ::: "memory")
; #define PG8_WAIT_L(n) asm volatile("s_waitcnt lgkmcnt(" #n ")" ::: "memory")
; #define PG8_BAR __builtin_amdgcn_s_barrier()
; #define PG8_SCHED __builtin_amdgcn_sched_barrier(0)
; template <class Epi>
; DI void gemm_phase(int wv, LAS unsigned char* lds, const Gemm g, const StaticOrder& S, const Epi& E) {
;     ...
;             PG8_STAGE(PG8_SB(0, 1), b2 + hstep, voffB);
;             PG8_WAIT_V(6); PG8_BAR; PG8_MMA(1, 1, At, B1); PG8_BAR;
;             PG8_LDB(B0, 1, 0); PG8_SCHED; PG8_LDA(At, 1, 0); PG8_STAGE(PG8_SA(0, 1), a2 + hstep, voffA);
;             PG8_WAIT_L(8); PG8_BAR; PG8_WAIT_L(0); PG8_MMA(0, 0, At, B0); PG8_BAR; PG8_SCHED;
;             PG8_LDB(B1, 1, 1); PG8_STAGE(PG8_SB(1, 0), b3, voffB);
;             PG8_BAR; PG8_WAIT_L(0); PG8_MMA(0, 1, At, B1); PG8_BAR;
;             PG8_LDA(At, 1, 1); PG8_STAGE(PG8_SA(1, 0), a3, voffA);
	s_add_u32 s80, s60, 0x40000
	s_addc_u32 s81, s61, 0
	s_add_i32 s82, s67, s11
	v_lshl_add_u64 v[152:153], s[80:81], 0, v[130:131]
	s_mov_b32 m0, s82
	s_nop 0
	global_load_lds_dwordx4 v[152:153], off
	v_lshl_add_u64 v[152:153], s[80:81], 0, v[134:135]
	s_add_i32 m0, s82, 0x2000
	s_nop 0
	global_load_lds_dwordx4 v[152:153], off
	s_waitcnt vmcnt(6)
	s_barrier
	s_setprio 1
	v_mfma_f32_16x16x32_bf16 v[52:55], v[200:203], v[168:171], v[52:55]
	v_mfma_f32_16x16x32_bf16 v[48:51], v[208:211], v[168:171], v[48:51]
	v_mfma_f32_16x16x32_bf16 v[36:39], v[200:203], v[176:179], v[36:39]
	v_mfma_f32_16x16x32_bf16 v[32:35], v[208:211], v[176:179], v[32:35]
	v_mfma_f32_16x16x32_bf16 v[20:23], v[200:203], v[184:187], v[20:23]
	v_mfma_f32_16x16x32_bf16 v[16:19], v[208:211], v[184:187], v[16:19]
	v_mfma_f32_16x16x32_bf16 v[4:7], v[200:203], v[192:195], v[4:7]
	v_mfma_f32_16x16x32_bf16 v[0:3], v[208:211], v[192:195], v[0:3]
	v_mfma_f32_16x16x32_bf16 v[52:55], v[204:207], v[172:175], v[52:55]
	v_mfma_f32_16x16x32_bf16 v[48:51], v[212:215], v[172:175], v[48:51]
	v_mfma_f32_16x16x32_bf16 v[36:39], v[204:207], v[180:183], v[36:39]
	v_mfma_f32_16x16x32_bf16 v[32:35], v[212:215], v[180:183], v[32:35]
	v_mfma_f32_16x16x32_bf16 v[20:23], v[204:207], v[188:191], v[20:23]
	v_mfma_f32_16x16x32_bf16 v[16:19], v[212:215], v[188:191], v[16:19]
	v_mfma_f32_16x16x32_bf16 v[4:7], v[204:207], v[196:199], v[4:7]
	v_mfma_f32_16x16x32_bf16 v[0:3], v[212:215], v[196:199], v[0:3]
	s_setprio 0
	s_add_i32 s80, 0, 0x18000
	v_add_u32_e32 v164, s80, v148
	s_barrier
	ds_read_b128 v[152:155], v164
	ds_read_b128 v[156:159], v164 offset:1024
	ds_read_b128 v[160:163], v164 offset:2048
	ds_read_b128 v[164:167], v164 offset:3072
	s_add_u32 s62, s62, 0x40000
	s_addc_u32 s63, s63, 0
	s_mov_b32 m0, s51
	v_lshl_add_u64 v[200:201], s[62:63], 0, v[128:129]
	ds_read_b128 v[168:171], v150 offset:32768
	ds_read_b128 v[172:175], v150 offset:33792
	ds_read_b128 v[176:179], v150 offset:34816
	ds_read_b128 v[180:183], v150 offset:35840
	ds_read_b128 v[184:187], v150 offset:36864
	ds_read_b128 v[188:191], v150 offset:37888
	ds_read_b128 v[192:195], v150 offset:38912
	ds_read_b128 v[196:199], v150 offset:39936
	global_load_lds_dwordx4 v[200:201], off
	v_lshl_add_u64 v[200:201], s[62:63], 0, v[132:133]
	s_mov_b32 m0, s52
	s_nop 0
	global_load_lds_dwordx4 v[200:201], off
	s_waitcnt lgkmcnt(8)
	s_barrier
	s_waitcnt lgkmcnt(0)
	s_setprio 1
	s_waitcnt lgkmcnt(0)
	v_mfma_f32_16x16x32_bf16 v[124:127], v[152:155], v[168:171], v[124:127]
	v_mfma_f32_16x16x32_bf16 v[120:123], v[160:163], v[168:171], v[120:123]
	v_mfma_f32_16x16x32_bf16 v[108:111], v[152:155], v[176:179], v[108:111]
	v_mfma_f32_16x16x32_bf16 v[104:107], v[160:163], v[176:179], v[104:107]
	v_mfma_f32_16x16x32_bf16 v[92:95], v[152:155], v[184:187], v[92:95]
	v_mfma_f32_16x16x32_bf16 v[88:91], v[160:163], v[184:187], v[88:91]
	v_mfma_f32_16x16x32_bf16 v[76:79], v[152:155], v[192:195], v[76:79]
	v_mfma_f32_16x16x32_bf16 v[72:75], v[160:163], v[192:195], v[72:75]
	v_mfma_f32_16x16x32_bf16 v[124:127], v[156:159], v[172:175], v[124:127]
	v_mfma_f32_16x16x32_bf16 v[120:123], v[164:167], v[172:175], v[120:123]
	v_mfma_f32_16x16x32_bf16 v[108:111], v[156:159], v[180:183], v[108:111]
	v_mfma_f32_16x16x32_bf16 v[104:107], v[164:167], v[180:183], v[104:107]
	v_mfma_f32_16x16x32_bf16 v[92:95], v[156:159], v[188:191], v[92:95]
	v_mfma_f32_16x16x32_bf16 v[88:91], v[164:167], v[188:191], v[88:91]
	v_mfma_f32_16x16x32_bf16 v[76:79], v[156:159], v[196:199], v[76:79]
	v_mfma_f32_16x16x32_bf16 v[72:75], v[164:167], v[196:199], v[72:75]
	s_setprio 0
	s_barrier
	s_add_i32 s62, 0, 0x1c000
	s_add_i32 s63, s80, s11
	v_add_u32_e32 v212, s62, v148
	v_lshl_add_u64 v[216:217], v[216:217], 0, s[20:21]
	s_mov_b32 m0, s63
	ds_read_b128 v[200:203], v212
	ds_read_b128 v[204:207], v212 offset:1024
	ds_read_b128 v[208:211], v212 offset:2048
	ds_read_b128 v[212:215], v212 offset:3072
	global_load_lds_dwordx4 v[216:217], off
	v_lshl_add_u64 v[216:217], v[218:219], 0, s[20:21]
	s_add_i32 m0, s63, 0x2000
	s_nop 0
	global_load_lds_dwordx4 v[216:217], off
	s_barrier
	s_waitcnt lgkmcnt(0)
	s_setprio 1
	s_waitcnt lgkmcnt(0)
	v_mfma_f32_16x16x32_bf16 v[116:119], v[200:203], v[168:171], v[116:119]
	v_mfma_f32_16x16x32_bf16 v[112:115], v[208:211], v[168:171], v[112:115]
	v_mfma_f32_16x16x32_bf16 v[100:103], v[200:203], v[176:179], v[100:103]
	v_mfma_f32_16x16x32_bf16 v[96:99], v[208:211], v[176:179], v[96:99]
	v_mfma_f32_16x16x32_bf16 v[84:87], v[200:203], v[184:187], v[84:87]
	v_mfma_f32_16x16x32_bf16 v[80:83], v[208:211], v[184:187], v[80:83]
	v_mfma_f32_16x16x32_bf16 v[68:71], v[200:203], v[192:195], v[68:71]
	v_mfma_f32_16x16x32_bf16 v[64:67], v[208:211], v[192:195], v[64:67]
	v_mfma_f32_16x16x32_bf16 v[116:119], v[204:207], v[172:175], v[116:119]
	v_mfma_f32_16x16x32_bf16 v[112:115], v[212:215], v[172:175], v[112:115]
	v_mfma_f32_16x16x32_bf16 v[100:103], v[204:207], v[180:183], v[100:103]
	v_mfma_f32_16x16x32_bf16 v[96:99], v[212:215], v[180:183], v[96:99]
	v_mfma_f32_16x16x32_bf16 v[84:87], v[204:207], v[188:191], v[84:87]
	v_mfma_f32_16x16x32_bf16 v[80:83], v[212:215], v[188:191], v[80:83]
	v_mfma_f32_16x16x32_bf16 v[68:71], v[204:207], v[196:199], v[68:71]
	v_mfma_f32_16x16x32_bf16 v[64:67], v[212:215], v[196:199], v[64:67]
	s_setprio 0
	s_mov_b32 m0, s64
	v_lshl_add_u64 v[216:217], v[220:221], 0, s[20:21]
	s_barrier
	ds_read_b128 v[168:171], v150 offset:49152
	ds_read_b128 v[172:175], v150 offset:50176
	ds_read_b128 v[176:179], v150 offset:51200
	ds_read_b128 v[180:183], v150 offset:52224
	ds_read_b128 v[184:187], v150 offset:53248
	ds_read_b128 v[188:191], v150 offset:54272
	ds_read_b128 v[192:195], v150 offset:55296
	ds_read_b128 v[196:199], v150 offset:56320
	global_load_lds_dwordx4 v[216:217], off
	v_lshl_add_u64 v[216:217], v[222:223], 0, s[20:21]
	s_mov_b32 m0, s65
	s_nop 0
	global_load_lds_dwordx4 v[216:217], off
	s_barrier
; DI unsigned pack2(float lo, float hi) { f32x2 v = {lo, hi}; bf16v2 r = __builtin_convertvector(v, bf16v2); return __builtin_bit_cast(unsigned, r); }
; DI float sigmoidf_(float x) { return frcp(1.f + fexp2(-x * LOG2E)); }
; #define PG8_STAGE(bufoff, gbase, voff) do { _Pragma("unroll") for (int _i = 0; _i < 2; ++_i) \
;         __builtin_amdgcn_global_load_lds((const unsigned*)((const char*)(gbase) + (voff)[_i]), (LAS unsigned*)(lds + (bufoff) + ldsw + _i * 8192), 16, 0, 0); } while (0)
; #define PG8_MMA(ai, bj, At, Bt) do { __builtin_amdgcn_s_setprio(1); _Pragma("unroll") for (int m = 0; m < 4; ++m) _Pragma("unroll") for (int n = 0; n < 2; ++n) _Pragma("unroll") for (int k = 0; k < 2; ++k) \
;         acc[ai][bj][m][n] = __builtin_amdgcn_mfma_f32_16x16x32_bf16(Bt[n][k], At[m][k], acc[ai][bj][m][n], 0, 0, 0); __builtin_amdgcn_s_setprio(0); } while (0)
; #define PG8_WAIT_V(n) asm volatile("s_waitcnt vmcnt(" #n ")" ::: "memory")
; #define PG8_WAIT_L(n) asm volatile("s_waitcnt lgkmcnt(" #n ")" ::: "memory")
; #define PG8_BAR __builtin_amdgcn_s_barrier()
; #define PG8_SCHED __builtin_amdgcn_sched_barrier(0)
; template <class Epi>
; DI void gemm_phase(int wv, LAS unsigned char* lds, const Gemm g, const StaticOrder& S, const Epi& E) {
;     ...
;             PG8_BAR; PG8_WAIT_L(0); PG8_MMA(1, 0, At, B0); PG8_BAR; PG8_SCHED;
;             PG8_STAGE(PG8_SB(1, 1), b3 + hstep, voffB);
;             PG8_WAIT_V(6); PG8_BAR; PG8_MMA(1, 1, At, B1); PG8_BAR;
;     DI void operator()(const AccT& acc, const Unit& u, int wr, int wc, int fr, int fq) const {
;     ...
;                 const size_t row = (size_t)u.pm * 256 + ai * 128 + wr * 64 + m * 16 + fr;
;                 float o[8];
; #pragma unroll
;                 for (int n = 0; n < 2; ++n) {
;                     const f32x4 g = acc[ai][0][m][n], up = acc[ai][1][m][n];
; #pragma unroll
;                     for (int e = 0; e < 4; ++e) o[4 * n + e] = g[e] * sigmoidf_(g[e]) * up[e];
;                 }
;                 u32x4 pk = {pack2(o[0], o[1]), pack2(o[2], o[3]), pack2(o[4], o[5]), pack2(o[6], o[7])};
;                 *(u32x4*)(O + row * DFF + u.pn * 128 + wc * 32 + 8 * fq) = pk;
	s_waitcnt lgkmcnt(0)
	s_setprio 1
	s_waitcnt lgkmcnt(0)
	v_mfma_f32_16x16x32_bf16 v[60:63], v[152:155], v[168:171], v[60:63]
	v_mfma_f32_16x16x32_bf16 v[56:59], v[160:163], v[168:171], v[56:59]
	v_mfma_f32_16x16x32_bf16 v[44:47], v[152:155], v[176:179], v[44:47]
	v_mfma_f32_16x16x32_bf16 v[40:43], v[160:163], v[176:179], v[40:43]
	v_mfma_f32_16x16x32_bf16 v[28:31], v[152:155], v[184:187], v[28:31]
	v_mfma_f32_16x16x32_bf16 v[24:27], v[160:163], v[184:187], v[24:27]
	v_mfma_f32_16x16x32_bf16 v[12:15], v[152:155], v[192:195], v[12:15]
	v_mfma_f32_16x16x32_bf16 v[8:11], v[160:163], v[192:195], v[8:11]
	v_mfma_f32_16x16x32_bf16 v[60:63], v[156:159], v[172:175], v[60:63]
	v_mfma_f32_16x16x32_bf16 v[56:59], v[164:167], v[172:175], v[56:59]
	v_mfma_f32_16x16x32_bf16 v[44:47], v[156:159], v[180:183], v[44:47]
	v_mfma_f32_16x16x32_bf16 v[40:43], v[164:167], v[180:183], v[40:43]
	v_mfma_f32_16x16x32_bf16 v[28:31], v[156:159], v[188:191], v[28:31]
	v_mfma_f32_16x16x32_bf16 v[24:27], v[164:167], v[188:191], v[24:27]
	v_mfma_f32_16x16x32_bf16 v[12:15], v[156:159], v[196:199], v[12:15]
	v_mfma_f32_16x16x32_bf16 v[8:11], v[164:167], v[196:199], v[8:11]
	s_setprio 0
	s_barrier
	s_add_u32 s60, s60, 0x40080
	s_addc_u32 s61, s61, 0
	s_add_i32 s62, s62, s11
	v_lshl_add_u64 v[152:153], s[60:61], 0, v[130:131]
	s_mov_b32 m0, s62
	s_nop 0
	global_load_lds_dwordx4 v[152:153], off
	v_lshl_add_u64 v[152:153], s[60:61], 0, v[134:135]
	s_add_i32 m0, s62, 0x2000
	s_nop 0
	global_load_lds_dwordx4 v[152:153], off
	s_waitcnt vmcnt(6)
	s_barrier
	s_setprio 1
	v_mfma_f32_16x16x32_bf16 v[52:55], v[200:203], v[168:171], v[52:55]
	v_mfma_f32_16x16x32_bf16 v[48:51], v[208:211], v[168:171], v[48:51]
	v_mfma_f32_16x16x32_bf16 v[36:39], v[200:203], v[176:179], v[36:39]
	v_mfma_f32_16x16x32_bf16 v[32:35], v[208:211], v[176:179], v[32:35]
	v_mfma_f32_16x16x32_bf16 v[20:23], v[200:203], v[184:187], v[20:23]
	v_mfma_f32_16x16x32_bf16 v[16:19], v[208:211], v[184:187], v[16:19]
	v_mfma_f32_16x16x32_bf16 v[4:7], v[200:203], v[192:195], v[4:7]
	v_mfma_f32_16x16x32_bf16 v[0:3], v[208:211], v[192:195], v[0:3]
	v_mfma_f32_16x16x32_bf16 v[52:55], v[204:207], v[172:175], v[52:55]
	v_mfma_f32_16x16x32_bf16 v[48:51], v[212:215], v[172:175], v[48:51]
	v_mfma_f32_16x16x32_bf16 v[36:39], v[204:207], v[180:183], v[36:39]
	v_mfma_f32_16x16x32_bf16 v[32:35], v[212:215], v[180:183], v[32:35]
	v_mfma_f32_16x16x32_bf16 v[20:23], v[204:207], v[188:191], v[20:23]
	v_mfma_f32_16x16x32_bf16 v[16:19], v[212:215], v[188:191], v[16:19]
	v_mfma_f32_16x16x32_bf16 v[4:7], v[204:207], v[196:199], v[4:7]
	v_mfma_f32_16x16x32_bf16 v[0:3], v[212:215], v[196:199], v[0:3]
	s_setprio 0
	s_add_i32 s79, s79, 2
	s_add_u32 s58, s58, 0x100
	s_addc_u32 s59, s59, 0
	s_add_u32 s77, s77, 0x100
	s_addc_u32 s78, s78, 0
	s_cmp_gt_u32 s79, 13
	s_barrier
	s_cbranch_scc0 .LBB0_1530
	s_mov_b32 s98, 0xbfb8aa3b
	v_pk_mul_f32 v[152:153], v[124:125], s[98:99] op_sel_hi:[1,0]
	v_exp_f32_e32 v152, v152
	v_exp_f32_e32 v153, v153
	s_ashr_i32 s57, s56, 31
	s_lshl_b64 s[56:57], s[56:57], 8
	v_pk_add_f32 v[152:153], v[152:153], 1.0 op_sel_hi:[1,0]
	v_rcp_f32_e32 v152, v152
	v_rcp_f32_e32 v153, v153
	v_lshl_add_u64 v[154:155], v[138:139], 0, s[56:57]
	s_lshl_b32 s56, s75, 7
	s_ashr_i32 s57, s56, 31
	v_pk_mul_f32 v[124:125], v[124:125], v[152:153]
	v_pk_mul_f32 v[152:153], v[126:127], s[98:99] op_sel_hi:[1,0]
	v_exp_f32_e32 v152, v152
	v_exp_f32_e32 v153, v153
	v_pk_mul_f32 v[116:117], v[124:125], v[116:117]
	s_mov_b32 s75, s28
	v_pk_add_f32 v[124:125], v[152:153], 1.0 op_sel_hi:[1,0]
	v_pk_mul_f32 v[152:153], v[120:121], s[98:99] op_sel_hi:[1,0]
	v_rcp_f32_e32 v124, v124
	v_rcp_f32_e32 v125, v125
	v_exp_f32_e32 v152, v152
	v_exp_f32_e32 v153, v153
	s_mov_b64 s[60:61], s[54:55]
	v_pk_mul_f32 v[124:125], v[126:127], v[124:125]
	v_pk_add_f32 v[126:127], v[152:153], 1.0 op_sel_hi:[1,0]
	v_pk_mul_f32 v[152:153], v[122:123], s[98:99] op_sel_hi:[1,0]
	v_exp_f32_e32 v152, v152
	v_exp_f32_e32 v153, v153
	v_rcp_f32_e32 v126, v126
	v_rcp_f32_e32 v127, v127
	v_pk_add_f32 v[152:153], v[152:153], 1.0 op_sel_hi:[1,0]
	v_rcp_f32_e32 v152, v152
	v_rcp_f32_e32 v153, v153
	v_pk_mul_f32 v[120:121], v[120:121], v[126:127]
	v_pk_mul_f32 v[118:119], v[124:125], v[118:119]
	v_pk_mul_f32 v[112:113], v[120:121], v[112:113]
	v_pk_mul_f32 v[120:121], v[122:123], v[152:153]
	s_nop 0
	v_pk_mul_f32 v[120:121], v[120:121], v[114:115]
	v_cvt_pk_bf16_f32 v114, v116, v117
	v_cvt_pk_bf16_f32 v116, v112, v113
	v_mov_b64_e32 v[112:113], s[22:23]
	v_mad_u64_u32 v[112:113], s[58:59], v154, s68, v[112:113]
	v_cvt_pk_bf16_f32 v115, v118, v119
	v_mov_b32_e32 v118, v113
	v_mad_u64_u32 v[118:119], s[58:59], v155, s68, v[118:119]
	v_mov_b32_e32 v113, v118
	v_pk_mul_f32 v[118:119], v[108:109], s[98:99] op_sel_hi:[1,0]
	v_exp_f32_e32 v118, v118
	v_exp_f32_e32 v119, v119
	v_lshl_add_u64 v[112:113], s[56:57], 1, v[112:113]
	v_lshl_add_u64 v[112:113], v[112:113], 0, s[18:19]
	v_cvt_pk_bf16_f32 v117, v120, v121
	v_pk_add_f32 v[118:119], v[118:119], 1.0 op_sel_hi:[1,0]
	v_lshl_add_u64 v[112:113], v[112:113], 0, v[136:137]
	v_rcp_f32_e32 v118, v118
	v_rcp_f32_e32 v119, v119
	global_store_dwordx4 v[112:113], v[114:117], off
	s_mov_b32 s56, s30
	s_mov_b64 s[58:59], s[38:39]
	v_pk_mul_f32 v[114:115], v[110:111], s[98:99] op_sel_hi:[1,0]
	v_exp_f32_e32 v114, v114
	v_exp_f32_e32 v115, v115
	v_pk_mul_f32 v[108:109], v[108:109], v[118:119]
	s_nop 0
	v_pk_mul_f32 v[100:101], v[108:109], v[100:101]
	v_pk_add_f32 v[108:109], v[114:115], 1.0 op_sel_hi:[1,0]
	v_pk_mul_f32 v[114:115], v[104:105], s[98:99] op_sel_hi:[1,0]
	v_rcp_f32_e32 v108, v108
	v_rcp_f32_e32 v109, v109
	v_exp_f32_e32 v114, v114
; DI unsigned pack2(float lo, float hi) { f32x2 v = {lo, hi}; bf16v2 r = __builtin_convertvector(v, bf16v2); return __builtin_bit_cast(unsigned, r); }
; DI float sigmoidf_(float x) { return frcp(1.f + fexp2(-x * LOG2E)); }
;     DI void operator()(const AccT& acc, const Unit& u, int wr, int wc, int fr, int fq) const {
;     ...
;                 const size_t row = (size_t)u.pm * 256 + ai * 128 + wr * 64 + m * 16 + fr;
;                 float o[8];
; #pragma unroll
;                 for (int n = 0; n < 2; ++n) {
;                     const f32x4 g = acc[ai][0][m][n], up = acc[ai][1][m][n];
; #pragma unroll
;                     for (int e = 0; e < 4; ++e) o[4 * n + e] = g[e] * sigmoidf_(g[e]) * up[e];
;                 }
;                 u32x4 pk = {pack2(o[0], o[1]), pack2(o[2], o[3]), pack2(o[4], o[5]), pack2(o[6], o[7])};
;                 *(u32x4*)(O + row * DFF + u.pn * 128 + wc * 32 + 8 * fq) = pk;
	v_exp_f32_e32 v115, v115
	v_pk_mul_f32 v[108:109], v[110:111], v[108:109]
	v_pk_add_f32 v[110:111], v[114:115], 1.0 op_sel_hi:[1,0]
	v_pk_mul_f32 v[114:115], v[106:107], s[98:99] op_sel_hi:[1,0]
	v_exp_f32_e32 v114, v114
	v_exp_f32_e32 v115, v115
	v_rcp_f32_e32 v110, v110
	v_rcp_f32_e32 v111, v111
	v_pk_add_f32 v[114:115], v[114:115], 1.0 op_sel_hi:[1,0]
	v_rcp_f32_e32 v114, v114
	v_rcp_f32_e32 v115, v115
	v_pk_mul_f32 v[104:105], v[104:105], v[110:111]
	v_pk_mul_f32 v[102:103], v[108:109], v[102:103]
	v_pk_mul_f32 v[104:105], v[104:105], v[96:97]
	v_pk_mul_f32 v[96:97], v[106:107], v[114:115]
	s_nop 0
	v_pk_mul_f32 v[106:107], v[96:97], v[98:99]
	v_mul_f32_e32 v99, 0xbfb8aa3b, v92
	v_cvt_pk_bf16_f32 v96, v100, v101
	v_exp_f32_e32 v100, v99
	v_mul_f32_e32 v99, 0xbfb8aa3b, v93
	v_exp_f32_e32 v101, v99
	v_cvt_pk_bf16_f32 v97, v102, v103
	v_add_co_u32_e32 v102, vcc, s53, v112
	v_cvt_pk_bf16_f32 v98, v104, v105
	v_cvt_pk_bf16_f32 v99, v106, v107
	v_pk_add_f32 v[100:101], v[100:101], 1.0 op_sel_hi:[1,0]
	v_addc_co_u32_e32 v103, vcc, 0, v113, vcc
	v_rcp_f32_e32 v100, v100
	v_rcp_f32_e32 v101, v101
	global_store_dwordx4 v[102:103], v[96:99], off
	v_pk_mul_f32 v[92:93], v[92:93], v[100:101]
	s_nop 0
	v_pk_mul_f32 v[96:97], v[94:95], s[98:99] op_sel_hi:[1,0]
	v_exp_f32_e32 v96, v96
	v_exp_f32_e32 v97, v97
	v_pk_mul_f32 v[84:85], v[92:93], v[84:85]
	v_pk_add_f32 v[92:93], v[96:97], 1.0 op_sel_hi:[1,0]
	v_pk_mul_f32 v[96:97], v[88:89], s[98:99] op_sel_hi:[1,0]
	v_rcp_f32_e32 v92, v92
	v_rcp_f32_e32 v93, v93
	v_exp_f32_e32 v96, v96
	v_exp_f32_e32 v97, v97
	v_pk_mul_f32 v[92:93], v[94:95], v[92:93]
	v_pk_add_f32 v[94:95], v[96:97], 1.0 op_sel_hi:[1,0]
	v_pk_mul_f32 v[96:97], v[90:91], s[98:99] op_sel_hi:[1,0]
	v_exp_f32_e32 v96, v96
	v_exp_f32_e32 v97, v97
	v_rcp_f32_e32 v94, v94
	v_rcp_f32_e32 v95, v95
	v_pk_add_f32 v[96:97], v[96:97], 1.0 op_sel_hi:[1,0]
	v_rcp_f32_e32 v96, v96
	v_rcp_f32_e32 v97, v97
	v_pk_mul_f32 v[88:89], v[88:89], v[94:95]
	v_pk_mul_f32 v[86:87], v[92:93], v[86:87]
	v_pk_mul_f32 v[88:89], v[88:89], v[80:81]
	v_pk_mul_f32 v[80:81], v[90:91], v[96:97]
	s_nop 0
	v_pk_mul_f32 v[90:91], v[80:81], v[82:83]
	v_mul_f32_e32 v83, 0xbfb8aa3b, v76
	v_cvt_pk_bf16_f32 v80, v84, v85
	v_exp_f32_e32 v84, v83
	v_mul_f32_e32 v83, 0xbfb8aa3b, v77
	v_exp_f32_e32 v85, v83
	v_cvt_pk_bf16_f32 v81, v86, v87
	v_add_co_u32_e32 v86, vcc, s69, v112
	v_cvt_pk_bf16_f32 v82, v88, v89
	v_cvt_pk_bf16_f32 v83, v90, v91
	v_pk_add_f32 v[84:85], v[84:85], 1.0 op_sel_hi:[1,0]
	v_addc_co_u32_e32 v87, vcc, 0, v113, vcc
	v_rcp_f32_e32 v84, v84
	v_rcp_f32_e32 v85, v85
	global_store_dwordx4 v[86:87], v[80:83], off
	v_pk_mul_f32 v[76:77], v[76:77], v[84:85]
	s_nop 0
	v_pk_mul_f32 v[80:81], v[78:79], s[98:99] op_sel_hi:[1,0]
	v_exp_f32_e32 v80, v80
	v_exp_f32_e32 v81, v81
	v_pk_mul_f32 v[68:69], v[76:77], v[68:69]
	v_pk_add_f32 v[76:77], v[80:81], 1.0 op_sel_hi:[1,0]
	v_pk_mul_f32 v[80:81], v[72:73], s[98:99] op_sel_hi:[1,0]
	v_rcp_f32_e32 v76, v76
	v_rcp_f32_e32 v77, v77
	v_exp_f32_e32 v80, v80
	v_exp_f32_e32 v81, v81
	v_pk_mul_f32 v[76:77], v[78:79], v[76:77]
	v_pk_add_f32 v[78:79], v[80:81], 1.0 op_sel_hi:[1,0]
	v_pk_mul_f32 v[80:81], v[74:75], s[98:99] op_sel_hi:[1,0]
	v_exp_f32_e32 v80, v80
	v_exp_f32_e32 v81, v81
	v_rcp_f32_e32 v78, v78
	v_rcp_f32_e32 v79, v79
	v_pk_add_f32 v[80:81], v[80:81], 1.0 op_sel_hi:[1,0]
	v_rcp_f32_e32 v80, v80
	v_rcp_f32_e32 v81, v81
	v_pk_mul_f32 v[72:73], v[72:73], v[78:79]
	v_pk_mul_f32 v[70:71], v[76:77], v[70:71]
	v_pk_mul_f32 v[72:73], v[72:73], v[64:65]
	v_pk_mul_f32 v[64:65], v[74:75], v[80:81]
	s_nop 0
	v_pk_mul_f32 v[74:75], v[64:65], v[66:67]
	v_mul_f32_e32 v67, 0xbfb8aa3b, v60
	v_cvt_pk_bf16_f32 v64, v68, v69
	v_exp_f32_e32 v68, v67
	v_mul_f32_e32 v67, 0xbfb8aa3b, v61
	v_exp_f32_e32 v69, v67
	v_cvt_pk_bf16_f32 v65, v70, v71
	v_add_co_u32_e32 v70, vcc, s70, v112
	v_cvt_pk_bf16_f32 v66, v72, v73
	v_cvt_pk_bf16_f32 v67, v74, v75
	v_pk_add_f32 v[68:69], v[68:69], 1.0 op_sel_hi:[1,0]
	v_addc_co_u32_e32 v71, vcc, 0, v113, vcc
	v_rcp_f32_e32 v68, v68
	v_rcp_f32_e32 v69, v69
	global_store_dwordx4 v[70:71], v[64:67], off
	v_pk_mul_f32 v[60:61], v[60:61], v[68:69]
	s_nop 0
	v_pk_mul_f32 v[64:65], v[62:63], s[98:99] op_sel_hi:[1,0]
	v_exp_f32_e32 v64, v64
	v_exp_f32_e32 v65, v65
	v_pk_mul_f32 v[52:53], v[60:61], v[52:53]
	v_pk_add_f32 v[60:61], v[64:65], 1.0 op_sel_hi:[1,0]
	v_pk_mul_f32 v[64:65], v[56:57], s[98:99] op_sel_hi:[1,0]
	v_rcp_f32_e32 v60, v60
	v_rcp_f32_e32 v61, v61
	v_exp_f32_e32 v64, v64
	v_exp_f32_e32 v65, v65
	v_pk_mul_f32 v[60:61], v[62:63], v[60:61]
	v_pk_add_f32 v[62:63], v[64:65], 1.0 op_sel_hi:[1,0]
	v_pk_mul_f32 v[64:65], v[58:59], s[98:99] op_sel_hi:[1,0]
	v_exp_f32_e32 v64, v64
	v_exp_f32_e32 v65, v65
	v_rcp_f32_e32 v62, v62
	v_rcp_f32_e32 v63, v63
	v_pk_add_f32 v[64:65], v[64:65], 1.0 op_sel_hi:[1,0]
	v_rcp_f32_e32 v64, v64
	v_rcp_f32_e32 v65, v65
	v_pk_mul_f32 v[56:57], v[56:57], v[62:63]
	v_pk_mul_f32 v[54:55], v[60:61], v[54:55]
; DI unsigned pack2(float lo, float hi) { f32x2 v = {lo, hi}; bf16v2 r = __builtin_convertvector(v, bf16v2); return __builtin_bit_cast(unsigned, r); }
; DI float sigmoidf_(float x) { return frcp(1.f + fexp2(-x * LOG2E)); }
; #define PG8_WAIT_V(n) asm volatile("s_waitcnt vmcnt(" #n ")" ::: "memory")
; #define PG8_BAR __builtin_amdgcn_s_barrier()
; template <class Epi>
; DI void gemm_phase(int wv, LAS unsigned char* lds, const Gemm g, const StaticOrder& S, const Epi& E) {
;     ...
;         E(acc, cur, wr, wc, fr, fq);
;         if (!has_next) break;
; #pragma unroll
;         for (int a = 0; a < 2; ++a)
; #pragma unroll
;             for (int b = 0; b < 2; ++b)
; #pragma unroll
;                 for (int m = 0; m < 4; ++m)
; #pragma unroll
;                     for (int n = 0; n < 2; ++n) acc[a][b][m][n] = (f32x4){0.f, 0.f, 0.f, 0.f};
;         cur = nxt; cA = nA; cB = nB; ++ui;
;     }
;     PG8_WAIT_V(0);
;     if (wr == 0) PG8_BAR;
;     PG8_BAR;
;     DI void operator()(const AccT& acc, const Unit& u, int wr, int wc, int fr, int fq) const {
;     ...
;                 const size_t row = (size_t)u.pm * 256 + ai * 128 + wr * 64 + m * 16 + fr;
;                 float o[8];
; #pragma unroll
;                 for (int n = 0; n < 2; ++n) {
;                     const f32x4 g = acc[ai][0][m][n], up = acc[ai][1][m][n];
; #pragma unroll
;                     for (int e = 0; e < 4; ++e) o[4 * n + e] = g[e] * sigmoidf_(g[e]) * up[e];
;                 }
;                 u32x4 pk = {pack2(o[0], o[1]), pack2(o[2], o[3]), pack2(o[4], o[5]), pack2(o[6], o[7])};
;                 *(u32x4*)(O + row * DFF + u.pn * 128 + wc * 32 + 8 * fq) = pk;
;             }
	v_pk_mul_f32 v[56:57], v[56:57], v[48:49]
	v_pk_mul_f32 v[48:49], v[58:59], v[64:65]
	s_nop 0
	v_pk_mul_f32 v[58:59], v[48:49], v[50:51]
	v_mul_f32_e32 v51, 0xbfb8aa3b, v44
	v_cvt_pk_bf16_f32 v48, v52, v53
	v_exp_f32_e32 v52, v51
	v_mul_f32_e32 v51, 0xbfb8aa3b, v45
	v_exp_f32_e32 v53, v51
	v_cvt_pk_bf16_f32 v49, v54, v55
	v_add_co_u32_e32 v54, vcc, s71, v112
	v_cvt_pk_bf16_f32 v50, v56, v57
	v_cvt_pk_bf16_f32 v51, v58, v59
	v_pk_add_f32 v[52:53], v[52:53], 1.0 op_sel_hi:[1,0]
	v_addc_co_u32_e32 v55, vcc, 0, v113, vcc
	v_rcp_f32_e32 v52, v52
	v_rcp_f32_e32 v53, v53
	global_store_dwordx4 v[54:55], v[48:51], off
	v_pk_mul_f32 v[44:45], v[44:45], v[52:53]
	s_nop 0
	v_pk_mul_f32 v[48:49], v[46:47], s[98:99] op_sel_hi:[1,0]
	v_exp_f32_e32 v48, v48
	v_exp_f32_e32 v49, v49
	v_pk_mul_f32 v[36:37], v[44:45], v[36:37]
	v_pk_add_f32 v[44:45], v[48:49], 1.0 op_sel_hi:[1,0]
	v_pk_mul_f32 v[48:49], v[40:41], s[98:99] op_sel_hi:[1,0]
	v_rcp_f32_e32 v44, v44
	v_rcp_f32_e32 v45, v45
	v_exp_f32_e32 v48, v48
	v_exp_f32_e32 v49, v49
	v_pk_mul_f32 v[44:45], v[46:47], v[44:45]
	v_pk_add_f32 v[46:47], v[48:49], 1.0 op_sel_hi:[1,0]
	v_pk_mul_f32 v[48:49], v[42:43], s[98:99] op_sel_hi:[1,0]
	v_exp_f32_e32 v48, v48
	v_exp_f32_e32 v49, v49
	v_rcp_f32_e32 v46, v46
	v_rcp_f32_e32 v47, v47
	v_pk_add_f32 v[48:49], v[48:49], 1.0 op_sel_hi:[1,0]
	v_rcp_f32_e32 v48, v48
	v_rcp_f32_e32 v49, v49
	v_pk_mul_f32 v[40:41], v[40:41], v[46:47]
	v_pk_mul_f32 v[38:39], v[44:45], v[38:39]
	v_pk_mul_f32 v[40:41], v[40:41], v[32:33]
	v_pk_mul_f32 v[32:33], v[42:43], v[48:49]
	s_nop 0
	v_pk_mul_f32 v[42:43], v[32:33], v[34:35]
	v_mul_f32_e32 v35, 0xbfb8aa3b, v28
	v_cvt_pk_bf16_f32 v32, v36, v37
	v_exp_f32_e32 v36, v35
	v_mul_f32_e32 v35, 0xbfb8aa3b, v29
	v_exp_f32_e32 v37, v35
	v_cvt_pk_bf16_f32 v33, v38, v39
	v_add_co_u32_e32 v38, vcc, s72, v112
	v_cvt_pk_bf16_f32 v34, v40, v41
	v_cvt_pk_bf16_f32 v35, v42, v43
	v_pk_add_f32 v[36:37], v[36:37], 1.0 op_sel_hi:[1,0]
	v_addc_co_u32_e32 v39, vcc, 0, v113, vcc
	v_rcp_f32_e32 v36, v36
	v_rcp_f32_e32 v37, v37
	global_store_dwordx4 v[38:39], v[32:35], off
	v_pk_mul_f32 v[28:29], v[28:29], v[36:37]
	s_nop 0
	v_pk_mul_f32 v[32:33], v[30:31], s[98:99] op_sel_hi:[1,0]
	v_exp_f32_e32 v32, v32
	v_exp_f32_e32 v33, v33
	v_pk_mul_f32 v[20:21], v[28:29], v[20:21]
	v_pk_add_f32 v[28:29], v[32:33], 1.0 op_sel_hi:[1,0]
	v_pk_mul_f32 v[32:33], v[24:25], s[98:99] op_sel_hi:[1,0]
	v_rcp_f32_e32 v28, v28
	v_rcp_f32_e32 v29, v29
	v_exp_f32_e32 v32, v32
	v_exp_f32_e32 v33, v33
	v_pk_mul_f32 v[28:29], v[30:31], v[28:29]
	v_pk_add_f32 v[30:31], v[32:33], 1.0 op_sel_hi:[1,0]
	v_pk_mul_f32 v[32:33], v[26:27], s[98:99] op_sel_hi:[1,0]
	v_exp_f32_e32 v32, v32
	v_exp_f32_e32 v33, v33
	v_rcp_f32_e32 v30, v30
	v_rcp_f32_e32 v31, v31
	v_pk_add_f32 v[32:33], v[32:33], 1.0 op_sel_hi:[1,0]
	v_rcp_f32_e32 v32, v32
	v_rcp_f32_e32 v33, v33
	v_pk_mul_f32 v[24:25], v[24:25], v[30:31]
	v_pk_mul_f32 v[22:23], v[28:29], v[22:23]
	v_pk_mul_f32 v[24:25], v[24:25], v[16:17]
	v_pk_mul_f32 v[16:17], v[26:27], v[32:33]
	s_nop 0
	v_pk_mul_f32 v[26:27], v[16:17], v[18:19]
	v_mul_f32_e32 v19, 0xbfb8aa3b, v12
	v_cvt_pk_bf16_f32 v16, v20, v21
	v_exp_f32_e32 v20, v19
	v_mul_f32_e32 v19, 0xbfb8aa3b, v13
	v_exp_f32_e32 v21, v19
	v_cvt_pk_bf16_f32 v17, v22, v23
	v_add_co_u32_e32 v22, vcc, s73, v112
	v_cvt_pk_bf16_f32 v18, v24, v25
	v_cvt_pk_bf16_f32 v19, v26, v27
	v_pk_add_f32 v[20:21], v[20:21], 1.0 op_sel_hi:[1,0]
	v_addc_co_u32_e32 v23, vcc, 0, v113, vcc
	v_rcp_f32_e32 v20, v20
	v_rcp_f32_e32 v21, v21
	global_store_dwordx4 v[22:23], v[16:19], off
	v_pk_mul_f32 v[12:13], v[12:13], v[20:21]
	s_nop 0
	v_pk_mul_f32 v[16:17], v[14:15], s[98:99] op_sel_hi:[1,0]
	v_exp_f32_e32 v16, v16
	v_exp_f32_e32 v17, v17
	v_pk_mul_f32 v[4:5], v[12:13], v[4:5]
	v_pk_add_f32 v[12:13], v[16:17], 1.0 op_sel_hi:[1,0]
	v_pk_mul_f32 v[16:17], v[8:9], s[98:99] op_sel_hi:[1,0]
	v_rcp_f32_e32 v12, v12
	v_rcp_f32_e32 v13, v13
	v_exp_f32_e32 v16, v16
	v_exp_f32_e32 v17, v17
	v_pk_mul_f32 v[12:13], v[14:15], v[12:13]
	v_pk_add_f32 v[14:15], v[16:17], 1.0 op_sel_hi:[1,0]
	v_pk_mul_f32 v[16:17], v[10:11], s[98:99] op_sel_hi:[1,0]
	v_exp_f32_e32 v16, v16
	v_exp_f32_e32 v17, v17
	v_rcp_f32_e32 v14, v14
	v_rcp_f32_e32 v15, v15
	v_pk_add_f32 v[16:17], v[16:17], 1.0 op_sel_hi:[1,0]
	v_rcp_f32_e32 v16, v16
	v_rcp_f32_e32 v17, v17
	v_pk_mul_f32 v[8:9], v[8:9], v[14:15]
	v_pk_mul_f32 v[6:7], v[12:13], v[6:7]
	v_pk_mul_f32 v[8:9], v[8:9], v[0:1]
	v_pk_mul_f32 v[0:1], v[10:11], v[16:17]
	s_nop 0
	v_pk_mul_f32 v[10:11], v[0:1], v[2:3]
	v_cvt_pk_bf16_f32 v0, v4, v5
	v_add_co_u32_e32 v4, vcc, 0xf2000, v112
	v_cvt_pk_bf16_f32 v1, v6, v7
	s_nop 0
	v_addc_co_u32_e32 v5, vcc, 0, v113, vcc
	v_cvt_pk_bf16_f32 v2, v8, v9
	v_cvt_pk_bf16_f32 v3, v10, v11
	s_and_b64 vcc, exec, s[16:17]
	global_store_dwordx4 v[4:5], v[0:3], off
	s_cbranch_vccz .LBB0_1523
	s_waitcnt vmcnt(0)
	s_cmpk_gt_u32 s8, 0xff
	s_cbranch_scc1 .LBB0_1534
	s_barrier

; #define PG8_STAGE(bufoff, gbase, voff) do { _Pragma("unroll") for (int _i = 0; _i < 2; ++_i) \
;         __builtin_amdgcn_global_load_lds((const unsigned*)((const char*)(gbase) + (voff)[_i]), (LAS unsigned*)(lds + (bufoff) + ldsw + _i * 8192), 16, 0, 0); } while (0)
; #define PG8_LDA(dst, b, h) do { _Pragma("unroll") for (int m = 0; m < 4; ++m) _Pragma("unroll") for (int k = 0; k < 2; ++k) dst[m][k] = *(const LAS bf16x8*)(lds + PG8_SA(b, h) + aoff + m * 2048 + k * 1024); } while (0)
; #define PG8_LDB(dst, b, h) do { _Pragma("unroll") for (int n = 0; n < 2; ++n) _Pragma("unroll") for (int k = 0; k < 2; ++k) dst[n][k] = *(const LAS bf16x8*)(lds + PG8_SB(b, h) + boff + n * 2048 + k * 1024); } while (0)
; #define PG8_MMA(ai, bj, At, Bt) do { __builtin_amdgcn_s_setprio(1); _Pragma("unroll") for (int m = 0; m < 4; ++m) _Pragma("unroll") for (int n = 0; n < 2; ++n) _Pragma("unroll") for (int k = 0; k < 2; ++k) \
;         acc[ai][bj][m][n] = __builtin_amdgcn_mfma_f32_16x16x32_bf16(Bt[n][k], At[m][k], acc[ai][bj][m][n], 0, 0, 0); __builtin_amdgcn_s_setprio(0); } while (0)
; #define PG8_WAIT_L(n) asm volatile("s_waitcnt lgkmcnt(" #n ")" ::: "memory")
; #define PG8_BAR __builtin_amdgcn_s_barrier()
; #define PG8_SCHED __builtin_amdgcn_sched_barrier(0)
; template <class Epi>
; DI void gemm_phase(int wv, LAS unsigned char* lds, const Gemm g, const StaticOrder& S, const Epi& E) {
;     ...
;             const bool last = (t == nt - 2);
;             const char* a1 = cA + (size_t)(t + 1) * kstep;
;             const char* a2 = last ? nA : cA + (size_t)(t + 2) * kstep; const char* b2 = last ? nB : cB + (size_t)(t + 2) * kstep;
;             const char* a3 = a2 + kstep; const char* b3 = b2 + kstep;
;             PG8_LDB(B0, 0, 0); PG8_SCHED; PG8_LDA(At, 0, 0); PG8_STAGE(PG8_SA(1, 1), a1 + hstep, voffA);
;             PG8_WAIT_L(8); PG8_BAR; PG8_WAIT_L(0); PG8_MMA(0, 0, At, B0); PG8_BAR; PG8_SCHED;
;             PG8_LDB(B1, 0, 1); PG8_STAGE(PG8_SB(0, 0), b2, voffB);
;             PG8_BAR; PG8_WAIT_L(0); PG8_MMA(0, 1, At, B1); PG8_BAR;
;             PG8_LDA(At, 0, 1); PG8_STAGE(PG8_SA(0, 0), a2, voffA);
;             PG8_BAR; PG8_WAIT_L(0); PG8_MMA(1, 0, At, B0); PG8_BAR; PG8_SCHED;
.LBB0_1878:
	ds_read_b128 v[152:155], v149
	ds_read_b128 v[156:159], v149 offset:1024
	ds_read_b128 v[160:163], v149 offset:2048
	ds_read_b128 v[164:167], v149 offset:3072
	s_add_u32 s56, s54, 0xfffc0080
	s_addc_u32 s57, s55, -1
	s_cmp_eq_u32 s77, 12
	s_cselect_b32 s59, s27, s57
	s_cselect_b32 s58, s53, s56
	s_cselect_b32 s57, s25, s76
	s_cselect_b32 s56, s74, s75
	v_lshl_add_u64 v[200:201], s[54:55], 0, v[140:141]
	s_add_i32 m0, s41, 0xc000
	ds_read_b128 v[168:171], v150
	ds_read_b128 v[172:175], v150 offset:1024
	ds_read_b128 v[176:179], v150 offset:2048
	ds_read_b128 v[180:183], v150 offset:3072
	ds_read_b128 v[184:187], v150 offset:4096
	ds_read_b128 v[188:191], v150 offset:5120
	ds_read_b128 v[192:195], v150 offset:6144
	ds_read_b128 v[196:199], v150 offset:7168
	global_load_lds_dwordx4 v[200:201], off
	v_lshl_add_u64 v[200:201], s[54:55], 0, v[142:143]
	s_add_i32 m0, s41, 0xe000
	s_nop 0
	global_load_lds_dwordx4 v[200:201], off
	s_waitcnt lgkmcnt(8)
	s_barrier
	s_waitcnt lgkmcnt(0)
	s_setprio 1
	s_waitcnt lgkmcnt(0)
	v_mfma_f32_16x16x32_bf16 v[124:127], v[152:155], v[168:171], v[124:127]
	v_mfma_f32_16x16x32_bf16 v[120:123], v[160:163], v[168:171], v[120:123]
	v_mfma_f32_16x16x32_bf16 v[108:111], v[152:155], v[176:179], v[108:111]
	v_mfma_f32_16x16x32_bf16 v[104:107], v[160:163], v[176:179], v[104:107]
	v_mfma_f32_16x16x32_bf16 v[92:95], v[152:155], v[184:187], v[92:95]
	v_mfma_f32_16x16x32_bf16 v[88:91], v[160:163], v[184:187], v[88:91]
	v_mfma_f32_16x16x32_bf16 v[76:79], v[152:155], v[192:195], v[76:79]
	v_mfma_f32_16x16x32_bf16 v[72:75], v[160:163], v[192:195], v[72:75]
	v_mfma_f32_16x16x32_bf16 v[124:127], v[156:159], v[172:175], v[124:127]
	v_mfma_f32_16x16x32_bf16 v[120:123], v[164:167], v[172:175], v[120:123]
	v_mfma_f32_16x16x32_bf16 v[108:111], v[156:159], v[180:183], v[108:111]
	v_mfma_f32_16x16x32_bf16 v[104:107], v[164:167], v[180:183], v[104:107]
	v_mfma_f32_16x16x32_bf16 v[92:95], v[156:159], v[188:191], v[92:95]
	v_mfma_f32_16x16x32_bf16 v[88:91], v[164:167], v[188:191], v[88:91]
	v_mfma_f32_16x16x32_bf16 v[76:79], v[156:159], v[196:199], v[76:79]
	v_mfma_f32_16x16x32_bf16 v[72:75], v[164:167], v[196:199], v[72:75]
	s_setprio 0
	s_barrier
	s_add_i32 s78, s64, s11
	v_lshl_add_u64 v[216:217], s[56:57], 0, v[130:131]
	s_mov_b32 m0, s78
	ds_read_b128 v[200:203], v151
	ds_read_b128 v[204:207], v151 offset:1024
	ds_read_b128 v[208:211], v151 offset:2048
	ds_read_b128 v[212:215], v151 offset:3072
	global_load_lds_dwordx4 v[216:217], off
	v_lshl_add_u64 v[218:219], s[56:57], 0, v[134:135]
	s_add_i32 m0, s78, 0x2000
	s_nop 0
	global_load_lds_dwordx4 v[218:219], off
	s_barrier
	s_waitcnt lgkmcnt(0)
	s_setprio 1
	s_waitcnt lgkmcnt(0)
	v_mfma_f32_16x16x32_bf16 v[116:119], v[200:203], v[168:171], v[116:119]
	v_mfma_f32_16x16x32_bf16 v[112:115], v[208:211], v[168:171], v[112:115]
	v_mfma_f32_16x16x32_bf16 v[100:103], v[200:203], v[176:179], v[100:103]
	v_mfma_f32_16x16x32_bf16 v[96:99], v[208:211], v[176:179], v[96:99]
	v_mfma_f32_16x16x32_bf16 v[84:87], v[200:203], v[184:187], v[84:87]
	v_mfma_f32_16x16x32_bf16 v[80:83], v[208:211], v[184:187], v[80:83]
	v_mfma_f32_16x16x32_bf16 v[68:71], v[200:203], v[192:195], v[68:71]
	v_mfma_f32_16x16x32_bf16 v[64:67], v[208:211], v[192:195], v[64:67]
	v_mfma_f32_16x16x32_bf16 v[116:119], v[204:207], v[172:175], v[116:119]
	v_mfma_f32_16x16x32_bf16 v[112:115], v[212:215], v[172:175], v[112:115]
	v_mfma_f32_16x16x32_bf16 v[100:103], v[204:207], v[180:183], v[100:103]
	v_mfma_f32_16x16x32_bf16 v[96:99], v[212:215], v[180:183], v[96:99]
	v_mfma_f32_16x16x32_bf16 v[84:87], v[204:207], v[188:191], v[84:87]
	v_mfma_f32_16x16x32_bf16 v[80:83], v[212:215], v[188:191], v[80:83]
	v_mfma_f32_16x16x32_bf16 v[68:71], v[204:207], v[196:199], v[68:71]
	v_mfma_f32_16x16x32_bf16 v[64:67], v[212:215], v[196:199], v[64:67]
	s_setprio 0
	s_mov_b32 m0, s41
	v_lshl_add_u64 v[220:221], s[58:59], 0, v[128:129]
	s_barrier
	ds_read_b128 v[168:171], v150 offset:16384
	ds_read_b128 v[172:175], v150 offset:17408
	ds_read_b128 v[176:179], v150 offset:18432
	ds_read_b128 v[180:183], v150 offset:19456
	ds_read_b128 v[184:187], v150 offset:20480
	ds_read_b128 v[188:191], v150 offset:21504
	ds_read_b128 v[192:195], v150 offset:22528
	ds_read_b128 v[196:199], v150 offset:23552
	global_load_lds_dwordx4 v[220:221], off
	v_lshl_add_u64 v[222:223], s[58:59], 0, v[132:133]
	s_mov_b32 m0, s50
	s_nop 0
	global_load_lds_dwordx4 v[222:223], off
	s_barrier
	s_waitcnt lgkmcnt(0)
	s_setprio 1
	s_waitcnt lgkmcnt(0)
	v_mfma_f32_16x16x32_bf16 v[60:63], v[152:155], v[168:171], v[60:63]
	v_mfma_f32_16x16x32_bf16 v[56:59], v[160:163], v[168:171], v[56:59]
	v_mfma_f32_16x16x32_bf16 v[44:47], v[152:155], v[176:179], v[44:47]
	v_mfma_f32_16x16x32_bf16 v[40:43], v[160:163], v[176:179], v[40:43]
	v_mfma_f32_16x16x32_bf16 v[28:31], v[152:155], v[184:187], v[28:31]
	v_mfma_f32_16x16x32_bf16 v[24:27], v[160:163], v[184:187], v[24:27]
	v_mfma_f32_16x16x32_bf16 v[12:15], v[152:155], v[192:195], v[12:15]
	v_mfma_f32_16x16x32_bf16 v[8:11], v[160:163], v[192:195], v[8:11]
	v_mfma_f32_16x16x32_bf16 v[60:63], v[156:159], v[172:175], v[60:63]
	v_mfma_f32_16x16x32_bf16 v[56:59], v[164:167], v[172:175], v[56:59]
	v_mfma_f32_16x16x32_bf16 v[44:47], v[156:159], v[180:183], v[44:47]
	v_mfma_f32_16x16x32_bf16 v[40:43], v[164:167], v[180:183], v[40:43]
	v_mfma_f32_16x16x32_bf16 v[28:31], v[156:159], v[188:191], v[28:31]
	v_mfma_f32_16x16x32_bf16 v[24:27], v[164:167], v[188:191], v[24:27]
	v_mfma_f32_16x16x32_bf16 v[12:15], v[156:159], v[196:199], v[12:15]
	v_mfma_f32_16x16x32_bf16 v[8:11], v[164:167], v[196:199], v[8:11]
	s_setprio 0
	s_barrier
; #define PG8_STAGE(bufoff, gbase, voff) do { _Pragma("unroll") for (int _i = 0; _i < 2; ++_i) \
;         __builtin_amdgcn_global_load_lds((const unsigned*)((const char*)(gbase) + (voff)[_i]), (LAS unsigned*)(lds + (bufoff) + ldsw + _i * 8192), 16, 0, 0); } while (0)
; #define PG8_LDA(dst, b, h) do { _Pragma("unroll") for (int m = 0; m < 4; ++m) _Pragma("unroll") for (int k = 0; k < 2; ++k) dst[m][k] = *(const LAS bf16x8*)(lds + PG8_SA(b, h) + aoff + m * 2048 + k * 1024); } while (0)
; #define PG8_LDB(dst, b, h) do { _Pragma("unroll") for (int n = 0; n < 2; ++n) _Pragma("unroll") for (int k = 0; k < 2; ++k) dst[n][k] = *(const LAS bf16x8*)(lds + PG8_SB(b, h) + boff + n * 2048 + k * 1024); } while (0)
; #define PG8_MMA(ai, bj, At, Bt) do { __builtin_amdgcn_s_setprio(1); _Pragma("unroll") for (int m = 0; m < 4; ++m) _Pragma("unroll") for (int n = 0; n < 2; ++n) _Pragma("unroll") for (int k = 0; k < 2; ++k) \
;         acc[ai][bj][m][n] = __builtin_amdgcn_mfma_f32_16x16x32_bf16(Bt[n][k], At[m][k], acc[ai][bj][m][n], 0, 0, 0); __builtin_amdgcn_s_setprio(0); } while (0)
; #define PG8_WAIT_V(n) asm volatile("s_waitcnt vmcnt(" #n ")" ::: "memory")
; #define PG8_WAIT_L(n) asm volatile("s_waitcnt lgkmcnt(" #n ")" ::: "memory")
; #define PG8_BAR __builtin_amdgcn_s_barrier()
; #define PG8_SCHED __builtin_amdgcn_sched_barrier(0)
; template <class Epi>
; DI void gemm_phase(int wv, LAS unsigned char* lds, const Gemm g, const StaticOrder& S, const Epi& E) {
;     ...
;             PG8_STAGE(PG8_SB(0, 1), b2 + hstep, voffB);
;             PG8_WAIT_V(6); PG8_BAR; PG8_MMA(1, 1, At, B1); PG8_BAR;
;             PG8_LDB(B0, 1, 0); PG8_SCHED; PG8_LDA(At, 1, 0); PG8_STAGE(PG8_SA(0, 1), a2 + hstep, voffA);
;             PG8_WAIT_L(8); PG8_BAR; PG8_WAIT_L(0); PG8_MMA(0, 0, At, B0); PG8_BAR; PG8_SCHED;
;             PG8_LDB(B1, 1, 1); PG8_STAGE(PG8_SB(1, 0), b3, voffB);
;             PG8_BAR; PG8_WAIT_L(0); PG8_MMA(0, 1, At, B1); PG8_BAR;
;             PG8_LDA(At, 1, 1); PG8_STAGE(PG8_SA(1, 0), a3, voffA);
	s_add_u32 s78, s56, 0x40000
	s_addc_u32 s79, s57, 0
	s_add_i32 s80, s65, s11
	v_lshl_add_u64 v[152:153], s[78:79], 0, v[130:131]
	s_mov_b32 m0, s80
	s_nop 0
	global_load_lds_dwordx4 v[152:153], off
	v_lshl_add_u64 v[152:153], s[78:79], 0, v[134:135]
	s_add_i32 m0, s80, 0x2000
	s_nop 0
	global_load_lds_dwordx4 v[152:153], off
	s_waitcnt vmcnt(6)
	s_barrier
	s_setprio 1
	v_mfma_f32_16x16x32_bf16 v[52:55], v[200:203], v[168:171], v[52:55]
	v_mfma_f32_16x16x32_bf16 v[48:51], v[208:211], v[168:171], v[48:51]
	v_mfma_f32_16x16x32_bf16 v[36:39], v[200:203], v[176:179], v[36:39]
	v_mfma_f32_16x16x32_bf16 v[32:35], v[208:211], v[176:179], v[32:35]
	v_mfma_f32_16x16x32_bf16 v[20:23], v[200:203], v[184:187], v[20:23]
	v_mfma_f32_16x16x32_bf16 v[16:19], v[208:211], v[184:187], v[16:19]
	v_mfma_f32_16x16x32_bf16 v[4:7], v[200:203], v[192:195], v[4:7]
	v_mfma_f32_16x16x32_bf16 v[0:3], v[208:211], v[192:195], v[0:3]
	v_mfma_f32_16x16x32_bf16 v[52:55], v[204:207], v[172:175], v[52:55]
	v_mfma_f32_16x16x32_bf16 v[48:51], v[212:215], v[172:175], v[48:51]
	v_mfma_f32_16x16x32_bf16 v[36:39], v[204:207], v[180:183], v[36:39]
	v_mfma_f32_16x16x32_bf16 v[32:35], v[212:215], v[180:183], v[32:35]
	v_mfma_f32_16x16x32_bf16 v[20:23], v[204:207], v[188:191], v[20:23]
	v_mfma_f32_16x16x32_bf16 v[16:19], v[212:215], v[188:191], v[16:19]
	v_mfma_f32_16x16x32_bf16 v[4:7], v[204:207], v[196:199], v[4:7]
	v_mfma_f32_16x16x32_bf16 v[0:3], v[212:215], v[196:199], v[0:3]
	s_setprio 0
	s_add_i32 s78, 0, 0x18000
	v_add_u32_e32 v164, s78, v148
	s_barrier
	ds_read_b128 v[152:155], v164
	ds_read_b128 v[156:159], v164 offset:1024
	ds_read_b128 v[160:163], v164 offset:2048
	ds_read_b128 v[164:167], v164 offset:3072
	s_add_u32 s58, s58, 0x40000
	s_addc_u32 s59, s59, 0
	s_mov_b32 m0, s51
	v_lshl_add_u64 v[200:201], s[58:59], 0, v[128:129]
	ds_read_b128 v[168:171], v150 offset:32768
	ds_read_b128 v[172:175], v150 offset:33792
	ds_read_b128 v[176:179], v150 offset:34816
	ds_read_b128 v[180:183], v150 offset:35840
	ds_read_b128 v[184:187], v150 offset:36864
	ds_read_b128 v[188:191], v150 offset:37888
	ds_read_b128 v[192:195], v150 offset:38912
	ds_read_b128 v[196:199], v150 offset:39936
	global_load_lds_dwordx4 v[200:201], off
	v_lshl_add_u64 v[200:201], s[58:59], 0, v[132:133]
	s_mov_b32 m0, s60
	s_nop 0
	global_load_lds_dwordx4 v[200:201], off
	s_waitcnt lgkmcnt(8)
	s_barrier
	s_waitcnt lgkmcnt(0)
	s_setprio 1
	s_waitcnt lgkmcnt(0)
	v_mfma_f32_16x16x32_bf16 v[124:127], v[152:155], v[168:171], v[124:127]
	v_mfma_f32_16x16x32_bf16 v[120:123], v[160:163], v[168:171], v[120:123]
	v_mfma_f32_16x16x32_bf16 v[108:111], v[152:155], v[176:179], v[108:111]
	v_mfma_f32_16x16x32_bf16 v[104:107], v[160:163], v[176:179], v[104:107]
	v_mfma_f32_16x16x32_bf16 v[92:95], v[152:155], v[184:187], v[92:95]
	v_mfma_f32_16x16x32_bf16 v[88:91], v[160:163], v[184:187], v[88:91]
	v_mfma_f32_16x16x32_bf16 v[76:79], v[152:155], v[192:195], v[76:79]
	v_mfma_f32_16x16x32_bf16 v[72:75], v[160:163], v[192:195], v[72:75]
	v_mfma_f32_16x16x32_bf16 v[124:127], v[156:159], v[172:175], v[124:127]
	v_mfma_f32_16x16x32_bf16 v[120:123], v[164:167], v[172:175], v[120:123]
	v_mfma_f32_16x16x32_bf16 v[108:111], v[156:159], v[180:183], v[108:111]
	v_mfma_f32_16x16x32_bf16 v[104:107], v[164:167], v[180:183], v[104:107]
	v_mfma_f32_16x16x32_bf16 v[92:95], v[156:159], v[188:191], v[92:95]
	v_mfma_f32_16x16x32_bf16 v[88:91], v[164:167], v[188:191], v[88:91]
	v_mfma_f32_16x16x32_bf16 v[76:79], v[156:159], v[196:199], v[76:79]
	v_mfma_f32_16x16x32_bf16 v[72:75], v[164:167], v[196:199], v[72:75]
	s_setprio 0
	s_barrier
	s_add_i32 s58, 0, 0x1c000
	s_add_i32 s59, s78, s11
	v_add_u32_e32 v212, s58, v148
	v_lshl_add_u64 v[216:217], v[216:217], 0, s[18:19]
	s_mov_b32 m0, s59
	ds_read_b128 v[200:203], v212
	ds_read_b128 v[204:207], v212 offset:1024
	ds_read_b128 v[208:211], v212 offset:2048
	ds_read_b128 v[212:215], v212 offset:3072
	global_load_lds_dwordx4 v[216:217], off
	v_lshl_add_u64 v[216:217], v[218:219], 0, s[18:19]
	s_add_i32 m0, s59, 0x2000
	s_nop 0
	global_load_lds_dwordx4 v[216:217], off
	s_barrier
	s_waitcnt lgkmcnt(0)
	s_setprio 1
	s_waitcnt lgkmcnt(0)
	v_mfma_f32_16x16x32_bf16 v[116:119], v[200:203], v[168:171], v[116:119]
	v_mfma_f32_16x16x32_bf16 v[112:115], v[208:211], v[168:171], v[112:115]
	v_mfma_f32_16x16x32_bf16 v[100:103], v[200:203], v[176:179], v[100:103]
	v_mfma_f32_16x16x32_bf16 v[96:99], v[208:211], v[176:179], v[96:99]
	v_mfma_f32_16x16x32_bf16 v[84:87], v[200:203], v[184:187], v[84:87]
	v_mfma_f32_16x16x32_bf16 v[80:83], v[208:211], v[184:187], v[80:83]
	v_mfma_f32_16x16x32_bf16 v[68:71], v[200:203], v[192:195], v[68:71]
	v_mfma_f32_16x16x32_bf16 v[64:67], v[208:211], v[192:195], v[64:67]
	v_mfma_f32_16x16x32_bf16 v[116:119], v[204:207], v[172:175], v[116:119]
	v_mfma_f32_16x16x32_bf16 v[112:115], v[212:215], v[172:175], v[112:115]
	v_mfma_f32_16x16x32_bf16 v[100:103], v[204:207], v[180:183], v[100:103]
	v_mfma_f32_16x16x32_bf16 v[96:99], v[212:215], v[180:183], v[96:99]
	v_mfma_f32_16x16x32_bf16 v[84:87], v[204:207], v[188:191], v[84:87]
	v_mfma_f32_16x16x32_bf16 v[80:83], v[212:215], v[188:191], v[80:83]
	v_mfma_f32_16x16x32_bf16 v[68:71], v[204:207], v[196:199], v[68:71]
	v_mfma_f32_16x16x32_bf16 v[64:67], v[212:215], v[196:199], v[64:67]
	s_setprio 0
	s_mov_b32 m0, s62
	v_lshl_add_u64 v[216:217], v[220:221], 0, s[18:19]
	s_barrier
	ds_read_b128 v[168:171], v150 offset:49152
	ds_read_b128 v[172:175], v150 offset:50176
	ds_read_b128 v[176:179], v150 offset:51200
	ds_read_b128 v[180:183], v150 offset:52224
	ds_read_b128 v[184:187], v150 offset:53248
	ds_read_b128 v[188:191], v150 offset:54272
	ds_read_b128 v[192:195], v150 offset:55296
	ds_read_b128 v[196:199], v150 offset:56320
	global_load_lds_dwordx4 v[216:217], off
	v_lshl_add_u64 v[216:217], v[222:223], 0, s[18:19]
	s_mov_b32 m0, s63
	s_nop 0
	global_load_lds_dwordx4 v[216:217], off
	s_barrier
; DI unsigned pack2(float lo, float hi) { f32x2 v = {lo, hi}; bf16v2 r = __builtin_convertvector(v, bf16v2); return __builtin_bit_cast(unsigned, r); }
; DI float sigmoidf_(float x) { return frcp(1.f + fexp2(-x * LOG2E)); }
; #define PG8_STAGE(bufoff, gbase, voff) do { _Pragma("unroll") for (int _i = 0; _i < 2; ++_i) \
;         __builtin_amdgcn_global_load_lds((const unsigned*)((const char*)(gbase) + (voff)[_i]), (LAS unsigned*)(lds + (bufoff) + ldsw + _i * 8192), 16, 0, 0); } while (0)
; #define PG8_MMA(ai, bj, At, Bt) do { __builtin_amdgcn_s_setprio(1); _Pragma("unroll") for (int m = 0; m < 4; ++m) _Pragma("unroll") for (int n = 0; n < 2; ++n) _Pragma("unroll") for (int k = 0; k < 2; ++k) \
;         acc[ai][bj][m][n] = __builtin_amdgcn_mfma_f32_16x16x32_bf16(Bt[n][k], At[m][k], acc[ai][bj][m][n], 0, 0, 0); __builtin_amdgcn_s_setprio(0); } while (0)
; #define PG8_WAIT_V(n) asm volatile("s_waitcnt vmcnt(" #n ")" ::: "memory")
; #define PG8_WAIT_L(n) asm volatile("s_waitcnt lgkmcnt(" #n ")" ::: "memory")
; #define PG8_BAR __builtin_amdgcn_s_barrier()
; #define PG8_SCHED __builtin_amdgcn_sched_barrier(0)
; template <class Epi>
; DI void gemm_phase(int wv, LAS unsigned char* lds, const Gemm g, const StaticOrder& S, const Epi& E) {
;     ...
;             PG8_BAR; PG8_WAIT_L(0); PG8_MMA(1, 0, At, B0); PG8_BAR; PG8_SCHED;
;             PG8_STAGE(PG8_SB(1, 1), b3 + hstep, voffB);
;             PG8_WAIT_V(6); PG8_BAR; PG8_MMA(1, 1, At, B1); PG8_BAR;
;     DI void operator()(const AccT& acc, const Unit& u, int wr, int wc, int fr, int fq) const {
;     ...
;                 const size_t row = (size_t)u.pm * 256 + ai * 128 + wr * 64 + m * 16 + fr;
;                 float o[8];
; #pragma unroll
;                 for (int n = 0; n < 2; ++n) {
;                     const f32x4 g = acc[ai][0][m][n], up = acc[ai][1][m][n];
; #pragma unroll
;                     for (int e = 0; e < 4; ++e) o[4 * n + e] = g[e] * sigmoidf_(g[e]) * up[e];
;                 }
;                 u32x4 pk = {pack2(o[0], o[1]), pack2(o[2], o[3]), pack2(o[4], o[5]), pack2(o[6], o[7])};
;                 *(u32x4*)(O + row * DFF + u.pn * 128 + wc * 32 + 8 * fq) = pk;
	s_waitcnt lgkmcnt(0)
	s_setprio 1
	s_waitcnt lgkmcnt(0)
	v_mfma_f32_16x16x32_bf16 v[60:63], v[152:155], v[168:171], v[60:63]
	v_mfma_f32_16x16x32_bf16 v[56:59], v[160:163], v[168:171], v[56:59]
	v_mfma_f32_16x16x32_bf16 v[44:47], v[152:155], v[176:179], v[44:47]
	v_mfma_f32_16x16x32_bf16 v[40:43], v[160:163], v[176:179], v[40:43]
	v_mfma_f32_16x16x32_bf16 v[28:31], v[152:155], v[184:187], v[28:31]
	v_mfma_f32_16x16x32_bf16 v[24:27], v[160:163], v[184:187], v[24:27]
	v_mfma_f32_16x16x32_bf16 v[12:15], v[152:155], v[192:195], v[12:15]
	v_mfma_f32_16x16x32_bf16 v[8:11], v[160:163], v[192:195], v[8:11]
	v_mfma_f32_16x16x32_bf16 v[60:63], v[156:159], v[172:175], v[60:63]
	v_mfma_f32_16x16x32_bf16 v[56:59], v[164:167], v[172:175], v[56:59]
	v_mfma_f32_16x16x32_bf16 v[44:47], v[156:159], v[180:183], v[44:47]
	v_mfma_f32_16x16x32_bf16 v[40:43], v[164:167], v[180:183], v[40:43]
	v_mfma_f32_16x16x32_bf16 v[28:31], v[156:159], v[188:191], v[28:31]
	v_mfma_f32_16x16x32_bf16 v[24:27], v[164:167], v[188:191], v[24:27]
	v_mfma_f32_16x16x32_bf16 v[12:15], v[156:159], v[196:199], v[12:15]
	v_mfma_f32_16x16x32_bf16 v[8:11], v[164:167], v[196:199], v[8:11]
	s_setprio 0
	s_barrier
	s_add_u32 s56, s56, 0x40080
	s_addc_u32 s57, s57, 0
	s_add_i32 s58, s58, s11
	v_lshl_add_u64 v[152:153], s[56:57], 0, v[130:131]
	s_mov_b32 m0, s58
	s_nop 0
	global_load_lds_dwordx4 v[152:153], off
	v_lshl_add_u64 v[152:153], s[56:57], 0, v[134:135]
	s_add_i32 m0, s58, 0x2000
	s_nop 0
	global_load_lds_dwordx4 v[152:153], off
	s_waitcnt vmcnt(6)
	s_barrier
	s_setprio 1
	v_mfma_f32_16x16x32_bf16 v[52:55], v[200:203], v[168:171], v[52:55]
	v_mfma_f32_16x16x32_bf16 v[48:51], v[208:211], v[168:171], v[48:51]
	v_mfma_f32_16x16x32_bf16 v[36:39], v[200:203], v[176:179], v[36:39]
	v_mfma_f32_16x16x32_bf16 v[32:35], v[208:211], v[176:179], v[32:35]
	v_mfma_f32_16x16x32_bf16 v[20:23], v[200:203], v[184:187], v[20:23]
	v_mfma_f32_16x16x32_bf16 v[16:19], v[208:211], v[184:187], v[16:19]
	v_mfma_f32_16x16x32_bf16 v[4:7], v[200:203], v[192:195], v[4:7]
	v_mfma_f32_16x16x32_bf16 v[0:3], v[208:211], v[192:195], v[0:3]
	v_mfma_f32_16x16x32_bf16 v[52:55], v[204:207], v[172:175], v[52:55]
	v_mfma_f32_16x16x32_bf16 v[48:51], v[212:215], v[172:175], v[48:51]
	v_mfma_f32_16x16x32_bf16 v[36:39], v[204:207], v[180:183], v[36:39]
	v_mfma_f32_16x16x32_bf16 v[32:35], v[212:215], v[180:183], v[32:35]
	v_mfma_f32_16x16x32_bf16 v[20:23], v[204:207], v[188:191], v[20:23]
	v_mfma_f32_16x16x32_bf16 v[16:19], v[212:215], v[188:191], v[16:19]
	v_mfma_f32_16x16x32_bf16 v[4:7], v[204:207], v[196:199], v[4:7]
	v_mfma_f32_16x16x32_bf16 v[0:3], v[212:215], v[196:199], v[0:3]
	s_setprio 0
	s_add_i32 s77, s77, 2
	s_add_u32 s54, s54, 0x100
	s_addc_u32 s55, s55, 0
	s_add_u32 s75, s75, 0x100
	s_addc_u32 s76, s76, 0
	s_cmp_gt_u32 s77, 13
	s_barrier
	s_cbranch_scc0 .LBB0_1878
	s_mov_b32 s98, 0xbfb8aa3b
	v_pk_mul_f32 v[152:153], v[124:125], s[98:99] op_sel_hi:[1,0]
	v_exp_f32_e32 v152, v152
	v_exp_f32_e32 v153, v153
	s_ashr_i32 s53, s52, 31
	s_lshl_b64 s[52:53], s[52:53], 8
	v_pk_add_f32 v[152:153], v[152:153], 1.0 op_sel_hi:[1,0]
	v_rcp_f32_e32 v152, v152
	v_rcp_f32_e32 v153, v153
	v_lshl_add_u64 v[154:155], v[138:139], 0, s[52:53]
	s_lshl_b32 s52, s73, 7
	s_ashr_i32 s53, s52, 31
	v_pk_mul_f32 v[124:125], v[124:125], v[152:153]
	v_pk_mul_f32 v[152:153], v[126:127], s[98:99] op_sel_hi:[1,0]
	v_exp_f32_e32 v152, v152
	v_exp_f32_e32 v153, v153
	v_pk_mul_f32 v[116:117], v[124:125], v[116:117]
	s_mov_b32 s73, s24
	v_pk_add_f32 v[124:125], v[152:153], 1.0 op_sel_hi:[1,0]
	v_pk_mul_f32 v[152:153], v[120:121], s[98:99] op_sel_hi:[1,0]
	v_rcp_f32_e32 v124, v124
	v_rcp_f32_e32 v125, v125
	v_exp_f32_e32 v152, v152
	v_exp_f32_e32 v153, v153
	s_mov_b64 s[56:57], s[30:31]
	v_pk_mul_f32 v[124:125], v[126:127], v[124:125]
	v_pk_add_f32 v[126:127], v[152:153], 1.0 op_sel_hi:[1,0]
	v_pk_mul_f32 v[152:153], v[122:123], s[98:99] op_sel_hi:[1,0]
	v_exp_f32_e32 v152, v152
	v_exp_f32_e32 v153, v153
	v_rcp_f32_e32 v126, v126
	v_rcp_f32_e32 v127, v127
	v_pk_add_f32 v[152:153], v[152:153], 1.0 op_sel_hi:[1,0]
	v_rcp_f32_e32 v152, v152
	v_rcp_f32_e32 v153, v153
	v_pk_mul_f32 v[120:121], v[120:121], v[126:127]
	v_pk_mul_f32 v[118:119], v[124:125], v[118:119]
	v_pk_mul_f32 v[112:113], v[120:121], v[112:113]
	v_pk_mul_f32 v[120:121], v[122:123], v[152:153]
	s_nop 0
	v_pk_mul_f32 v[120:121], v[120:121], v[114:115]
	v_cvt_pk_bf16_f32 v114, v116, v117
	v_cvt_pk_bf16_f32 v116, v112, v113
	v_mov_b64_e32 v[112:113], s[38:39]
	v_mad_u64_u32 v[112:113], s[54:55], v154, s66, v[112:113]
	v_cvt_pk_bf16_f32 v115, v118, v119
	v_mov_b32_e32 v118, v113
	v_mad_u64_u32 v[118:119], s[54:55], v155, s66, v[118:119]
	v_mov_b32_e32 v113, v118
	v_pk_mul_f32 v[118:119], v[108:109], s[98:99] op_sel_hi:[1,0]
	v_exp_f32_e32 v118, v118
	v_exp_f32_e32 v119, v119
	v_lshl_add_u64 v[112:113], s[52:53], 1, v[112:113]
	v_lshl_add_u64 v[112:113], v[112:113], 0, s[16:17]
	v_cvt_pk_bf16_f32 v117, v120, v121
	v_pk_add_f32 v[118:119], v[118:119], 1.0 op_sel_hi:[1,0]
	v_lshl_add_u64 v[112:113], v[112:113], 0, v[136:137]
	v_rcp_f32_e32 v118, v118
	v_rcp_f32_e32 v119, v119
	global_store_dwordx4 v[112:113], v[114:117], off
	s_mov_b32 s52, s26
	s_mov_b64 s[54:55], s[28:29]
	v_pk_mul_f32 v[114:115], v[110:111], s[98:99] op_sel_hi:[1,0]
	v_exp_f32_e32 v114, v114
	v_exp_f32_e32 v115, v115
	v_pk_mul_f32 v[108:109], v[108:109], v[118:119]
	s_nop 0
	v_pk_mul_f32 v[100:101], v[108:109], v[100:101]
	v_pk_add_f32 v[108:109], v[114:115], 1.0 op_sel_hi:[1,0]
	v_pk_mul_f32 v[114:115], v[104:105], s[98:99] op_sel_hi:[1,0]
	v_rcp_f32_e32 v108, v108
	v_rcp_f32_e32 v109, v109
	v_exp_f32_e32 v114, v114
; DI unsigned pack2(float lo, float hi) { f32x2 v = {lo, hi}; bf16v2 r = __builtin_convertvector(v, bf16v2); return __builtin_bit_cast(unsigned, r); }
; DI float sigmoidf_(float x) { return frcp(1.f + fexp2(-x * LOG2E)); }
;     DI void operator()(const AccT& acc, const Unit& u, int wr, int wc, int fr, int fq) const {
;     ...
;                 const size_t row = (size_t)u.pm * 256 + ai * 128 + wr * 64 + m * 16 + fr;
;                 float o[8];
; #pragma unroll
;                 for (int n = 0; n < 2; ++n) {
;                     const f32x4 g = acc[ai][0][m][n], up = acc[ai][1][m][n];
; #pragma unroll
;                     for (int e = 0; e < 4; ++e) o[4 * n + e] = g[e] * sigmoidf_(g[e]) * up[e];
;                 }
;                 u32x4 pk = {pack2(o[0], o[1]), pack2(o[2], o[3]), pack2(o[4], o[5]), pack2(o[6], o[7])};
;                 *(u32x4*)(O + row * DFF + u.pn * 128 + wc * 32 + 8 * fq) = pk;
	v_exp_f32_e32 v115, v115
	v_pk_mul_f32 v[108:109], v[110:111], v[108:109]
	v_pk_add_f32 v[110:111], v[114:115], 1.0 op_sel_hi:[1,0]
	v_pk_mul_f32 v[114:115], v[106:107], s[98:99] op_sel_hi:[1,0]
	v_exp_f32_e32 v114, v114
	v_exp_f32_e32 v115, v115
	v_rcp_f32_e32 v110, v110
	v_rcp_f32_e32 v111, v111
	v_pk_add_f32 v[114:115], v[114:115], 1.0 op_sel_hi:[1,0]
	v_rcp_f32_e32 v114, v114
	v_rcp_f32_e32 v115, v115
	v_pk_mul_f32 v[104:105], v[104:105], v[110:111]
	v_pk_mul_f32 v[102:103], v[108:109], v[102:103]
	v_pk_mul_f32 v[104:105], v[104:105], v[96:97]
	v_pk_mul_f32 v[96:97], v[106:107], v[114:115]
	s_nop 0
	v_pk_mul_f32 v[106:107], v[96:97], v[98:99]
	v_mul_f32_e32 v99, 0xbfb8aa3b, v92
	v_cvt_pk_bf16_f32 v96, v100, v101
	v_exp_f32_e32 v100, v99
	v_mul_f32_e32 v99, 0xbfb8aa3b, v93
	v_exp_f32_e32 v101, v99
	v_cvt_pk_bf16_f32 v97, v102, v103
	v_add_co_u32_e32 v102, vcc, s61, v112
	v_cvt_pk_bf16_f32 v98, v104, v105
	v_cvt_pk_bf16_f32 v99, v106, v107
	v_pk_add_f32 v[100:101], v[100:101], 1.0 op_sel_hi:[1,0]
	v_addc_co_u32_e32 v103, vcc, 0, v113, vcc
	v_rcp_f32_e32 v100, v100
	v_rcp_f32_e32 v101, v101
	global_store_dwordx4 v[102:103], v[96:99], off
	v_pk_mul_f32 v[92:93], v[92:93], v[100:101]
	s_nop 0
	v_pk_mul_f32 v[96:97], v[94:95], s[98:99] op_sel_hi:[1,0]
	v_exp_f32_e32 v96, v96
	v_exp_f32_e32 v97, v97
	v_pk_mul_f32 v[84:85], v[92:93], v[84:85]
	v_pk_add_f32 v[92:93], v[96:97], 1.0 op_sel_hi:[1,0]
	v_pk_mul_f32 v[96:97], v[88:89], s[98:99] op_sel_hi:[1,0]
	v_rcp_f32_e32 v92, v92
	v_rcp_f32_e32 v93, v93
	v_exp_f32_e32 v96, v96
	v_exp_f32_e32 v97, v97
	v_pk_mul_f32 v[92:93], v[94:95], v[92:93]
	v_pk_add_f32 v[94:95], v[96:97], 1.0 op_sel_hi:[1,0]
	v_pk_mul_f32 v[96:97], v[90:91], s[98:99] op_sel_hi:[1,0]
	v_exp_f32_e32 v96, v96
	v_exp_f32_e32 v97, v97
	v_rcp_f32_e32 v94, v94
	v_rcp_f32_e32 v95, v95
	v_pk_add_f32 v[96:97], v[96:97], 1.0 op_sel_hi:[1,0]
	v_rcp_f32_e32 v96, v96
	v_rcp_f32_e32 v97, v97
	v_pk_mul_f32 v[88:89], v[88:89], v[94:95]
	v_pk_mul_f32 v[86:87], v[92:93], v[86:87]
	v_pk_mul_f32 v[88:89], v[88:89], v[80:81]
	v_pk_mul_f32 v[80:81], v[90:91], v[96:97]
	s_nop 0
	v_pk_mul_f32 v[90:91], v[80:81], v[82:83]
	v_mul_f32_e32 v83, 0xbfb8aa3b, v76
	v_cvt_pk_bf16_f32 v80, v84, v85
	v_exp_f32_e32 v84, v83
	v_mul_f32_e32 v83, 0xbfb8aa3b, v77
	v_exp_f32_e32 v85, v83
	v_cvt_pk_bf16_f32 v81, v86, v87
	v_add_co_u32_e32 v86, vcc, s67, v112
	v_cvt_pk_bf16_f32 v82, v88, v89
	v_cvt_pk_bf16_f32 v83, v90, v91
	v_pk_add_f32 v[84:85], v[84:85], 1.0 op_sel_hi:[1,0]
	v_addc_co_u32_e32 v87, vcc, 0, v113, vcc
	v_rcp_f32_e32 v84, v84
	v_rcp_f32_e32 v85, v85
	global_store_dwordx4 v[86:87], v[80:83], off
	v_pk_mul_f32 v[76:77], v[76:77], v[84:85]
	s_nop 0
	v_pk_mul_f32 v[80:81], v[78:79], s[98:99] op_sel_hi:[1,0]
	v_exp_f32_e32 v80, v80
	v_exp_f32_e32 v81, v81
	v_pk_mul_f32 v[68:69], v[76:77], v[68:69]
	v_pk_add_f32 v[76:77], v[80:81], 1.0 op_sel_hi:[1,0]
	v_pk_mul_f32 v[80:81], v[72:73], s[98:99] op_sel_hi:[1,0]
	v_rcp_f32_e32 v76, v76
	v_rcp_f32_e32 v77, v77
	v_exp_f32_e32 v80, v80
	v_exp_f32_e32 v81, v81
	v_pk_mul_f32 v[76:77], v[78:79], v[76:77]
	v_pk_add_f32 v[78:79], v[80:81], 1.0 op_sel_hi:[1,0]
	v_pk_mul_f32 v[80:81], v[74:75], s[98:99] op_sel_hi:[1,0]
	v_exp_f32_e32 v80, v80
	v_exp_f32_e32 v81, v81
	v_rcp_f32_e32 v78, v78
	v_rcp_f32_e32 v79, v79
	v_pk_add_f32 v[80:81], v[80:81], 1.0 op_sel_hi:[1,0]
	v_rcp_f32_e32 v80, v80
	v_rcp_f32_e32 v81, v81
	v_pk_mul_f32 v[72:73], v[72:73], v[78:79]
	v_pk_mul_f32 v[70:71], v[76:77], v[70:71]
	v_pk_mul_f32 v[72:73], v[72:73], v[64:65]
	v_pk_mul_f32 v[64:65], v[74:75], v[80:81]
	s_nop 0
	v_pk_mul_f32 v[74:75], v[64:65], v[66:67]
	v_mul_f32_e32 v67, 0xbfb8aa3b, v60
	v_cvt_pk_bf16_f32 v64, v68, v69
	v_exp_f32_e32 v68, v67
	v_mul_f32_e32 v67, 0xbfb8aa3b, v61
	v_exp_f32_e32 v69, v67
	v_cvt_pk_bf16_f32 v65, v70, v71
	v_add_co_u32_e32 v70, vcc, s68, v112
	v_cvt_pk_bf16_f32 v66, v72, v73
	v_cvt_pk_bf16_f32 v67, v74, v75
	v_pk_add_f32 v[68:69], v[68:69], 1.0 op_sel_hi:[1,0]
	v_addc_co_u32_e32 v71, vcc, 0, v113, vcc
	v_rcp_f32_e32 v68, v68
	v_rcp_f32_e32 v69, v69
	global_store_dwordx4 v[70:71], v[64:67], off
	v_pk_mul_f32 v[60:61], v[60:61], v[68:69]
	s_nop 0
	v_pk_mul_f32 v[64:65], v[62:63], s[98:99] op_sel_hi:[1,0]
	v_exp_f32_e32 v64, v64
	v_exp_f32_e32 v65, v65
	v_pk_mul_f32 v[52:53], v[60:61], v[52:53]
	v_pk_add_f32 v[60:61], v[64:65], 1.0 op_sel_hi:[1,0]
	v_pk_mul_f32 v[64:65], v[56:57], s[98:99] op_sel_hi:[1,0]
	v_rcp_f32_e32 v60, v60
	v_rcp_f32_e32 v61, v61
	v_exp_f32_e32 v64, v64
	v_exp_f32_e32 v65, v65
	v_pk_mul_f32 v[60:61], v[62:63], v[60:61]
	v_pk_add_f32 v[62:63], v[64:65], 1.0 op_sel_hi:[1,0]
	v_pk_mul_f32 v[64:65], v[58:59], s[98:99] op_sel_hi:[1,0]
	v_exp_f32_e32 v64, v64
	v_exp_f32_e32 v65, v65
	v_rcp_f32_e32 v62, v62
	v_rcp_f32_e32 v63, v63
	v_pk_add_f32 v[64:65], v[64:65], 1.0 op_sel_hi:[1,0]
	v_rcp_f32_e32 v64, v64
	v_rcp_f32_e32 v65, v65
	v_pk_mul_f32 v[56:57], v[56:57], v[62:63]
	v_pk_mul_f32 v[54:55], v[60:61], v[54:55]
; DI unsigned pack2(float lo, float hi) { f32x2 v = {lo, hi}; bf16v2 r = __builtin_convertvector(v, bf16v2); return __builtin_bit_cast(unsigned, r); }
; DI float sigmoidf_(float x) { return frcp(1.f + fexp2(-x * LOG2E)); }
; #define PG8_WAIT_V(n) asm volatile("s_waitcnt vmcnt(" #n ")" ::: "memory")
; #define PG8_BAR __builtin_amdgcn_s_barrier()
; template <class Epi>
; DI void gemm_phase(int wv, LAS unsigned char* lds, const Gemm g, const StaticOrder& S, const Epi& E) {
;     ...
;         E(acc, cur, wr, wc, fr, fq);
;         if (!has_next) break;
; #pragma unroll
;         for (int a = 0; a < 2; ++a)
; #pragma unroll
;             for (int b = 0; b < 2; ++b)
; #pragma unroll
;                 for (int m = 0; m < 4; ++m)
; #pragma unroll
;                     for (int n = 0; n < 2; ++n) acc[a][b][m][n] = (f32x4){0.f, 0.f, 0.f, 0.f};
;         cur = nxt; cA = nA; cB = nB; ++ui;
;     }
;     PG8_WAIT_V(0);
;     if (wr == 0) PG8_BAR;
;     PG8_BAR;
;     DI void operator()(const AccT& acc, const Unit& u, int wr, int wc, int fr, int fq) const {
;     ...
;                 const size_t row = (size_t)u.pm * 256 + ai * 128 + wr * 64 + m * 16 + fr;
;                 float o[8];
; #pragma unroll
;                 for (int n = 0; n < 2; ++n) {
;                     const f32x4 g = acc[ai][0][m][n], up = acc[ai][1][m][n];
; #pragma unroll
;                     for (int e = 0; e < 4; ++e) o[4 * n + e] = g[e] * sigmoidf_(g[e]) * up[e];
;                 }
;                 u32x4 pk = {pack2(o[0], o[1]), pack2(o[2], o[3]), pack2(o[4], o[5]), pack2(o[6], o[7])};
;                 *(u32x4*)(O + row * DFF + u.pn * 128 + wc * 32 + 8 * fq) = pk;
;             }
	v_pk_mul_f32 v[56:57], v[56:57], v[48:49]
	v_pk_mul_f32 v[48:49], v[58:59], v[64:65]
	s_nop 0
	v_pk_mul_f32 v[58:59], v[48:49], v[50:51]
	v_mul_f32_e32 v51, 0xbfb8aa3b, v44
	v_cvt_pk_bf16_f32 v48, v52, v53
	v_exp_f32_e32 v52, v51
	v_mul_f32_e32 v51, 0xbfb8aa3b, v45
	v_exp_f32_e32 v53, v51
	v_cvt_pk_bf16_f32 v49, v54, v55
	v_add_co_u32_e32 v54, vcc, s69, v112
	v_cvt_pk_bf16_f32 v50, v56, v57
	v_cvt_pk_bf16_f32 v51, v58, v59
	v_pk_add_f32 v[52:53], v[52:53], 1.0 op_sel_hi:[1,0]
	v_addc_co_u32_e32 v55, vcc, 0, v113, vcc
	v_rcp_f32_e32 v52, v52
	v_rcp_f32_e32 v53, v53
	global_store_dwordx4 v[54:55], v[48:51], off
	v_pk_mul_f32 v[44:45], v[44:45], v[52:53]
	s_nop 0
	v_pk_mul_f32 v[48:49], v[46:47], s[98:99] op_sel_hi:[1,0]
	v_exp_f32_e32 v48, v48
	v_exp_f32_e32 v49, v49
	v_pk_mul_f32 v[36:37], v[44:45], v[36:37]
	v_pk_add_f32 v[44:45], v[48:49], 1.0 op_sel_hi:[1,0]
	v_pk_mul_f32 v[48:49], v[40:41], s[98:99] op_sel_hi:[1,0]
	v_rcp_f32_e32 v44, v44
	v_rcp_f32_e32 v45, v45
	v_exp_f32_e32 v48, v48
	v_exp_f32_e32 v49, v49
	v_pk_mul_f32 v[44:45], v[46:47], v[44:45]
	v_pk_add_f32 v[46:47], v[48:49], 1.0 op_sel_hi:[1,0]
	v_pk_mul_f32 v[48:49], v[42:43], s[98:99] op_sel_hi:[1,0]
	v_exp_f32_e32 v48, v48
	v_exp_f32_e32 v49, v49
	v_rcp_f32_e32 v46, v46
	v_rcp_f32_e32 v47, v47
	v_pk_add_f32 v[48:49], v[48:49], 1.0 op_sel_hi:[1,0]
	v_rcp_f32_e32 v48, v48
	v_rcp_f32_e32 v49, v49
	v_pk_mul_f32 v[40:41], v[40:41], v[46:47]
	v_pk_mul_f32 v[38:39], v[44:45], v[38:39]
	v_pk_mul_f32 v[40:41], v[40:41], v[32:33]
	v_pk_mul_f32 v[32:33], v[42:43], v[48:49]
	s_nop 0
	v_pk_mul_f32 v[42:43], v[32:33], v[34:35]
	v_mul_f32_e32 v35, 0xbfb8aa3b, v28
	v_cvt_pk_bf16_f32 v32, v36, v37
	v_exp_f32_e32 v36, v35
	v_mul_f32_e32 v35, 0xbfb8aa3b, v29
	v_exp_f32_e32 v37, v35
	v_cvt_pk_bf16_f32 v33, v38, v39
	v_add_co_u32_e32 v38, vcc, s70, v112
	v_cvt_pk_bf16_f32 v34, v40, v41
	v_cvt_pk_bf16_f32 v35, v42, v43
	v_pk_add_f32 v[36:37], v[36:37], 1.0 op_sel_hi:[1,0]
	v_addc_co_u32_e32 v39, vcc, 0, v113, vcc
	v_rcp_f32_e32 v36, v36
	v_rcp_f32_e32 v37, v37
	global_store_dwordx4 v[38:39], v[32:35], off
	v_pk_mul_f32 v[28:29], v[28:29], v[36:37]
	s_nop 0
	v_pk_mul_f32 v[32:33], v[30:31], s[98:99] op_sel_hi:[1,0]
	v_exp_f32_e32 v32, v32
	v_exp_f32_e32 v33, v33
	v_pk_mul_f32 v[20:21], v[28:29], v[20:21]
	v_pk_add_f32 v[28:29], v[32:33], 1.0 op_sel_hi:[1,0]
	v_pk_mul_f32 v[32:33], v[24:25], s[98:99] op_sel_hi:[1,0]
	v_rcp_f32_e32 v28, v28
	v_rcp_f32_e32 v29, v29
	v_exp_f32_e32 v32, v32
	v_exp_f32_e32 v33, v33
	v_pk_mul_f32 v[28:29], v[30:31], v[28:29]
	v_pk_add_f32 v[30:31], v[32:33], 1.0 op_sel_hi:[1,0]
	v_pk_mul_f32 v[32:33], v[26:27], s[98:99] op_sel_hi:[1,0]
	v_exp_f32_e32 v32, v32
	v_exp_f32_e32 v33, v33
	v_rcp_f32_e32 v30, v30
	v_rcp_f32_e32 v31, v31
	v_pk_add_f32 v[32:33], v[32:33], 1.0 op_sel_hi:[1,0]
	v_rcp_f32_e32 v32, v32
	v_rcp_f32_e32 v33, v33
	v_pk_mul_f32 v[24:25], v[24:25], v[30:31]
	v_pk_mul_f32 v[22:23], v[28:29], v[22:23]
	v_pk_mul_f32 v[24:25], v[24:25], v[16:17]
	v_pk_mul_f32 v[16:17], v[26:27], v[32:33]
	s_nop 0
	v_pk_mul_f32 v[26:27], v[16:17], v[18:19]
	v_mul_f32_e32 v19, 0xbfb8aa3b, v12
	v_cvt_pk_bf16_f32 v16, v20, v21
	v_exp_f32_e32 v20, v19
	v_mul_f32_e32 v19, 0xbfb8aa3b, v13
	v_exp_f32_e32 v21, v19
	v_cvt_pk_bf16_f32 v17, v22, v23
	v_add_co_u32_e32 v22, vcc, s71, v112
	v_cvt_pk_bf16_f32 v18, v24, v25
	v_cvt_pk_bf16_f32 v19, v26, v27
	v_pk_add_f32 v[20:21], v[20:21], 1.0 op_sel_hi:[1,0]
	v_addc_co_u32_e32 v23, vcc, 0, v113, vcc
	v_rcp_f32_e32 v20, v20
	v_rcp_f32_e32 v21, v21
	global_store_dwordx4 v[22:23], v[16:19], off
	v_pk_mul_f32 v[12:13], v[12:13], v[20:21]
	s_nop 0
	v_pk_mul_f32 v[16:17], v[14:15], s[98:99] op_sel_hi:[1,0]
	v_exp_f32_e32 v16, v16
	v_exp_f32_e32 v17, v17
	v_pk_mul_f32 v[4:5], v[12:13], v[4:5]
	v_pk_add_f32 v[12:13], v[16:17], 1.0 op_sel_hi:[1,0]
	v_pk_mul_f32 v[16:17], v[8:9], s[98:99] op_sel_hi:[1,0]
	v_rcp_f32_e32 v12, v12
	v_rcp_f32_e32 v13, v13
	v_exp_f32_e32 v16, v16
	v_exp_f32_e32 v17, v17
	v_pk_mul_f32 v[12:13], v[14:15], v[12:13]
	v_pk_add_f32 v[14:15], v[16:17], 1.0 op_sel_hi:[1,0]
	v_pk_mul_f32 v[16:17], v[10:11], s[98:99] op_sel_hi:[1,0]
	v_exp_f32_e32 v16, v16
	v_exp_f32_e32 v17, v17
	v_rcp_f32_e32 v14, v14
	v_rcp_f32_e32 v15, v15
	v_pk_add_f32 v[16:17], v[16:17], 1.0 op_sel_hi:[1,0]
	v_rcp_f32_e32 v16, v16
	v_rcp_f32_e32 v17, v17
	v_pk_mul_f32 v[8:9], v[8:9], v[14:15]
	v_pk_mul_f32 v[6:7], v[12:13], v[6:7]
	v_pk_mul_f32 v[8:9], v[8:9], v[0:1]
	v_pk_mul_f32 v[0:1], v[10:11], v[16:17]
	s_nop 0
	v_pk_mul_f32 v[10:11], v[0:1], v[2:3]
	v_cvt_pk_bf16_f32 v0, v4, v5
	v_add_co_u32_e32 v4, vcc, 0xf2000, v112
	v_cvt_pk_bf16_f32 v1, v6, v7
	s_nop 0
	v_addc_co_u32_e32 v5, vcc, 0, v113, vcc
	v_cvt_pk_bf16_f32 v2, v8, v9
	v_cvt_pk_bf16_f32 v3, v10, v11
	s_and_b64 vcc, exec, s[14:15]
	global_store_dwordx4 v[4:5], v[0:3], off
	s_cbranch_vccz .LBB0_1871
	s_waitcnt vmcnt(0)
	s_cmpk_gt_u32 s8, 0xff
	s_cbranch_scc1 .LBB0_1882
	s_barrier

; #define PG8_STAGE(bufoff, gbase, voff) do { _Pragma("unroll") for (int _i = 0; _i < 2; ++_i) \
;         __builtin_amdgcn_global_load_lds((const unsigned*)((const char*)(gbase) + (voff)[_i]), (LAS unsigned*)(lds + (bufoff) + ldsw + _i * 8192), 16, 0, 0); } while (0)
; #define PG8_LDA(dst, b, h) do { _Pragma("unroll") for (int m = 0; m < 4; ++m) _Pragma("unroll") for (int k = 0; k < 2; ++k) dst[m][k] = *(const LAS bf16x8*)(lds + PG8_SA(b, h) + aoff + m * 2048 + k * 1024); } while (0)
; #define PG8_LDB(dst, b, h) do { _Pragma("unroll") for (int n = 0; n < 2; ++n) _Pragma("unroll") for (int k = 0; k < 2; ++k) dst[n][k] = *(const LAS bf16x8*)(lds + PG8_SB(b, h) + boff + n * 2048 + k * 1024); } while (0)
; #define PG8_MMA(ai, bj, At, Bt) do { __builtin_amdgcn_s_setprio(1); _Pragma("unroll") for (int m = 0; m < 4; ++m) _Pragma("unroll") for (int n = 0; n < 2; ++n) _Pragma("unroll") for (int k = 0; k < 2; ++k) \
;         acc[ai][bj][m][n] = __builtin_amdgcn_mfma_f32_16x16x32_bf16(Bt[n][k], At[m][k], acc[ai][bj][m][n], 0, 0, 0); __builtin_amdgcn_s_setprio(0); } while (0)
; #define PG8_WAIT_L(n) asm volatile("s_waitcnt lgkmcnt(" #n ")" ::: "memory")
; #define PG8_BAR __builtin_amdgcn_s_barrier()
; #define PG8_SCHED __builtin_amdgcn_sched_barrier(0)
; template <class Epi>
; DI void gemm_phase(int wv, LAS unsigned char* lds, const Gemm g, const StaticOrder& S, const Epi& E) {
;     ...
;             const bool last = (t == nt - 2);
;             const char* a1 = cA + (size_t)(t + 1) * kstep;
;             const char* a2 = last ? nA : cA + (size_t)(t + 2) * kstep; const char* b2 = last ? nB : cB + (size_t)(t + 2) * kstep;
;             const char* a3 = a2 + kstep; const char* b3 = b2 + kstep;
;             PG8_LDB(B0, 0, 0); PG8_SCHED; PG8_LDA(At, 0, 0); PG8_STAGE(PG8_SA(1, 1), a1 + hstep, voffA);
;             PG8_WAIT_L(8); PG8_BAR; PG8_WAIT_L(0); PG8_MMA(0, 0, At, B0); PG8_BAR; PG8_SCHED;
;             PG8_LDB(B1, 0, 1); PG8_STAGE(PG8_SB(0, 0), b2, voffB);
;             PG8_BAR; PG8_WAIT_L(0); PG8_MMA(0, 1, At, B1); PG8_BAR;
;             PG8_LDA(At, 0, 1); PG8_STAGE(PG8_SA(0, 0), a2, voffA);
;             PG8_BAR; PG8_WAIT_L(0); PG8_MMA(1, 0, At, B0); PG8_BAR; PG8_SCHED;
.LBB0_3137:
	ds_read_b128 v[152:155], v149
	ds_read_b128 v[156:159], v149 offset:1024
	ds_read_b128 v[160:163], v149 offset:2048
	ds_read_b128 v[164:167], v149 offset:3072
	s_add_u32 s28, s26, 0xfffc0080
	s_addc_u32 s29, s27, -1
	s_cmp_eq_u32 s67, 12
	s_cselect_b32 s31, s15, s29
	s_cselect_b32 s30, s25, s28
	s_cselect_b32 s29, s13, s66
	s_cselect_b32 s28, s64, s65
	v_lshl_add_u64 v[200:201], s[26:27], 0, v[140:141]
	s_add_i32 m0, s47, 0xc000
	ds_read_b128 v[168:171], v150
	ds_read_b128 v[172:175], v150 offset:1024
	ds_read_b128 v[176:179], v150 offset:2048
	ds_read_b128 v[180:183], v150 offset:3072
	ds_read_b128 v[184:187], v150 offset:4096
	ds_read_b128 v[188:191], v150 offset:5120
	ds_read_b128 v[192:195], v150 offset:6144
	ds_read_b128 v[196:199], v150 offset:7168
	global_load_lds_dwordx4 v[200:201], off
	v_lshl_add_u64 v[200:201], s[26:27], 0, v[142:143]
	s_add_i32 m0, s47, 0xe000
	s_nop 0
	global_load_lds_dwordx4 v[200:201], off
	s_waitcnt lgkmcnt(8)
	s_barrier
	s_waitcnt lgkmcnt(0)
	s_setprio 1
	s_waitcnt lgkmcnt(0)
	v_mfma_f32_16x16x32_bf16 v[124:127], v[152:155], v[168:171], v[124:127]
	v_mfma_f32_16x16x32_bf16 v[120:123], v[160:163], v[168:171], v[120:123]
	v_mfma_f32_16x16x32_bf16 v[108:111], v[152:155], v[176:179], v[108:111]
	v_mfma_f32_16x16x32_bf16 v[104:107], v[160:163], v[176:179], v[104:107]
	v_mfma_f32_16x16x32_bf16 v[92:95], v[152:155], v[184:187], v[92:95]
	v_mfma_f32_16x16x32_bf16 v[88:91], v[160:163], v[184:187], v[88:91]
	v_mfma_f32_16x16x32_bf16 v[76:79], v[152:155], v[192:195], v[76:79]
	v_mfma_f32_16x16x32_bf16 v[72:75], v[160:163], v[192:195], v[72:75]
	v_mfma_f32_16x16x32_bf16 v[124:127], v[156:159], v[172:175], v[124:127]
	v_mfma_f32_16x16x32_bf16 v[120:123], v[164:167], v[172:175], v[120:123]
	v_mfma_f32_16x16x32_bf16 v[108:111], v[156:159], v[180:183], v[108:111]
	v_mfma_f32_16x16x32_bf16 v[104:107], v[164:167], v[180:183], v[104:107]
	v_mfma_f32_16x16x32_bf16 v[92:95], v[156:159], v[188:191], v[92:95]
	v_mfma_f32_16x16x32_bf16 v[88:91], v[164:167], v[188:191], v[88:91]
	v_mfma_f32_16x16x32_bf16 v[76:79], v[156:159], v[196:199], v[76:79]
	v_mfma_f32_16x16x32_bf16 v[72:75], v[164:167], v[196:199], v[72:75]
	s_setprio 0
	s_barrier
	s_add_i32 s68, s54, s46
	v_lshl_add_u64 v[216:217], s[28:29], 0, v[130:131]
	s_mov_b32 m0, s68
	ds_read_b128 v[200:203], v151
	ds_read_b128 v[204:207], v151 offset:1024
	ds_read_b128 v[208:211], v151 offset:2048
	ds_read_b128 v[212:215], v151 offset:3072
	global_load_lds_dwordx4 v[216:217], off
	v_lshl_add_u64 v[218:219], s[28:29], 0, v[134:135]
	s_add_i32 m0, s68, 0x2000
	s_nop 0
	global_load_lds_dwordx4 v[218:219], off
	s_barrier
	s_waitcnt lgkmcnt(0)
	s_setprio 1
	s_waitcnt lgkmcnt(0)
	v_mfma_f32_16x16x32_bf16 v[116:119], v[200:203], v[168:171], v[116:119]
	v_mfma_f32_16x16x32_bf16 v[112:115], v[208:211], v[168:171], v[112:115]
	v_mfma_f32_16x16x32_bf16 v[100:103], v[200:203], v[176:179], v[100:103]
	v_mfma_f32_16x16x32_bf16 v[96:99], v[208:211], v[176:179], v[96:99]
	v_mfma_f32_16x16x32_bf16 v[84:87], v[200:203], v[184:187], v[84:87]
	v_mfma_f32_16x16x32_bf16 v[80:83], v[208:211], v[184:187], v[80:83]
	v_mfma_f32_16x16x32_bf16 v[68:71], v[200:203], v[192:195], v[68:71]
	v_mfma_f32_16x16x32_bf16 v[64:67], v[208:211], v[192:195], v[64:67]
	v_mfma_f32_16x16x32_bf16 v[116:119], v[204:207], v[172:175], v[116:119]
	v_mfma_f32_16x16x32_bf16 v[112:115], v[212:215], v[172:175], v[112:115]
	v_mfma_f32_16x16x32_bf16 v[100:103], v[204:207], v[180:183], v[100:103]
	v_mfma_f32_16x16x32_bf16 v[96:99], v[212:215], v[180:183], v[96:99]
	v_mfma_f32_16x16x32_bf16 v[84:87], v[204:207], v[188:191], v[84:87]
	v_mfma_f32_16x16x32_bf16 v[80:83], v[212:215], v[188:191], v[80:83]
	v_mfma_f32_16x16x32_bf16 v[68:71], v[204:207], v[196:199], v[68:71]
	v_mfma_f32_16x16x32_bf16 v[64:67], v[212:215], v[196:199], v[64:67]
	s_setprio 0
	s_mov_b32 m0, s47
	v_lshl_add_u64 v[220:221], s[30:31], 0, v[128:129]
	s_barrier
	ds_read_b128 v[168:171], v150 offset:16384
	ds_read_b128 v[172:175], v150 offset:17408
	ds_read_b128 v[176:179], v150 offset:18432
	ds_read_b128 v[180:183], v150 offset:19456
	ds_read_b128 v[184:187], v150 offset:20480
	ds_read_b128 v[188:191], v150 offset:21504
	ds_read_b128 v[192:195], v150 offset:22528
	ds_read_b128 v[196:199], v150 offset:23552
	global_load_lds_dwordx4 v[220:221], off
	v_lshl_add_u64 v[222:223], s[30:31], 0, v[132:133]
	s_mov_b32 m0, s48
	s_nop 0
	global_load_lds_dwordx4 v[222:223], off
	s_barrier
	s_waitcnt lgkmcnt(0)
	s_setprio 1
	s_waitcnt lgkmcnt(0)
	v_mfma_f32_16x16x32_bf16 v[60:63], v[152:155], v[168:171], v[60:63]
	v_mfma_f32_16x16x32_bf16 v[56:59], v[160:163], v[168:171], v[56:59]
	v_mfma_f32_16x16x32_bf16 v[44:47], v[152:155], v[176:179], v[44:47]
	v_mfma_f32_16x16x32_bf16 v[40:43], v[160:163], v[176:179], v[40:43]
	v_mfma_f32_16x16x32_bf16 v[28:31], v[152:155], v[184:187], v[28:31]
	v_mfma_f32_16x16x32_bf16 v[24:27], v[160:163], v[184:187], v[24:27]
	v_mfma_f32_16x16x32_bf16 v[12:15], v[152:155], v[192:195], v[12:15]
	v_mfma_f32_16x16x32_bf16 v[8:11], v[160:163], v[192:195], v[8:11]
	v_mfma_f32_16x16x32_bf16 v[60:63], v[156:159], v[172:175], v[60:63]
	v_mfma_f32_16x16x32_bf16 v[56:59], v[164:167], v[172:175], v[56:59]
	v_mfma_f32_16x16x32_bf16 v[44:47], v[156:159], v[180:183], v[44:47]
	v_mfma_f32_16x16x32_bf16 v[40:43], v[164:167], v[180:183], v[40:43]
	v_mfma_f32_16x16x32_bf16 v[28:31], v[156:159], v[188:191], v[28:31]
	v_mfma_f32_16x16x32_bf16 v[24:27], v[164:167], v[188:191], v[24:27]
	v_mfma_f32_16x16x32_bf16 v[12:15], v[156:159], v[196:199], v[12:15]
	v_mfma_f32_16x16x32_bf16 v[8:11], v[164:167], v[196:199], v[8:11]
	s_setprio 0
	s_barrier
; #define PG8_STAGE(bufoff, gbase, voff) do { _Pragma("unroll") for (int _i = 0; _i < 2; ++_i) \
;         __builtin_amdgcn_global_load_lds((const unsigned*)((const char*)(gbase) + (voff)[_i]), (LAS unsigned*)(lds + (bufoff) + ldsw + _i * 8192), 16, 0, 0); } while (0)
; #define PG8_LDA(dst, b, h) do { _Pragma("unroll") for (int m = 0; m < 4; ++m) _Pragma("unroll") for (int k = 0; k < 2; ++k) dst[m][k] = *(const LAS bf16x8*)(lds + PG8_SA(b, h) + aoff + m * 2048 + k * 1024); } while (0)
; #define PG8_LDB(dst, b, h) do { _Pragma("unroll") for (int n = 0; n < 2; ++n) _Pragma("unroll") for (int k = 0; k < 2; ++k) dst[n][k] = *(const LAS bf16x8*)(lds + PG8_SB(b, h) + boff + n * 2048 + k * 1024); } while (0)
; #define PG8_MMA(ai, bj, At, Bt) do { __builtin_amdgcn_s_setprio(1); _Pragma("unroll") for (int m = 0; m < 4; ++m) _Pragma("unroll") for (int n = 0; n < 2; ++n) _Pragma("unroll") for (int k = 0; k < 2; ++k) \
;         acc[ai][bj][m][n] = __builtin_amdgcn_mfma_f32_16x16x32_bf16(Bt[n][k], At[m][k], acc[ai][bj][m][n], 0, 0, 0); __builtin_amdgcn_s_setprio(0); } while (0)
; #define PG8_WAIT_V(n) asm volatile("s_waitcnt vmcnt(" #n ")" ::: "memory")
; #define PG8_WAIT_L(n) asm volatile("s_waitcnt lgkmcnt(" #n ")" ::: "memory")
; #define PG8_BAR __builtin_amdgcn_s_barrier()
; #define PG8_SCHED __builtin_amdgcn_sched_barrier(0)
; template <class Epi>
; DI void gemm_phase(int wv, LAS unsigned char* lds, const Gemm g, const StaticOrder& S, const Epi& E) {
;     ...
;             PG8_STAGE(PG8_SB(0, 1), b2 + hstep, voffB);
;             PG8_WAIT_V(6); PG8_BAR; PG8_MMA(1, 1, At, B1); PG8_BAR;
;             PG8_LDB(B0, 1, 0); PG8_SCHED; PG8_LDA(At, 1, 0); PG8_STAGE(PG8_SA(0, 1), a2 + hstep, voffA);
;             PG8_WAIT_L(8); PG8_BAR; PG8_WAIT_L(0); PG8_MMA(0, 0, At, B0); PG8_BAR; PG8_SCHED;
;             PG8_LDB(B1, 1, 1); PG8_STAGE(PG8_SB(1, 0), b3, voffB);
;             PG8_BAR; PG8_WAIT_L(0); PG8_MMA(0, 1, At, B1); PG8_BAR;
;             PG8_LDA(At, 1, 1); PG8_STAGE(PG8_SA(1, 0), a3, voffA);
	s_add_u32 s68, s28, 0x40000
	s_addc_u32 s69, s29, 0
	s_add_i32 s70, s55, s46
	v_lshl_add_u64 v[152:153], s[68:69], 0, v[130:131]
	s_mov_b32 m0, s70
	s_nop 0
	global_load_lds_dwordx4 v[152:153], off
	v_lshl_add_u64 v[152:153], s[68:69], 0, v[134:135]
	s_add_i32 m0, s70, 0x2000
	s_nop 0
	global_load_lds_dwordx4 v[152:153], off
	s_waitcnt vmcnt(6)
	s_barrier
	s_setprio 1
	v_mfma_f32_16x16x32_bf16 v[52:55], v[200:203], v[168:171], v[52:55]
	v_mfma_f32_16x16x32_bf16 v[48:51], v[208:211], v[168:171], v[48:51]
	v_mfma_f32_16x16x32_bf16 v[36:39], v[200:203], v[176:179], v[36:39]
	v_mfma_f32_16x16x32_bf16 v[32:35], v[208:211], v[176:179], v[32:35]
	v_mfma_f32_16x16x32_bf16 v[20:23], v[200:203], v[184:187], v[20:23]
	v_mfma_f32_16x16x32_bf16 v[16:19], v[208:211], v[184:187], v[16:19]
	v_mfma_f32_16x16x32_bf16 v[4:7], v[200:203], v[192:195], v[4:7]
	v_mfma_f32_16x16x32_bf16 v[0:3], v[208:211], v[192:195], v[0:3]
	v_mfma_f32_16x16x32_bf16 v[52:55], v[204:207], v[172:175], v[52:55]
	v_mfma_f32_16x16x32_bf16 v[48:51], v[212:215], v[172:175], v[48:51]
	v_mfma_f32_16x16x32_bf16 v[36:39], v[204:207], v[180:183], v[36:39]
	v_mfma_f32_16x16x32_bf16 v[32:35], v[212:215], v[180:183], v[32:35]
	v_mfma_f32_16x16x32_bf16 v[20:23], v[204:207], v[188:191], v[20:23]
	v_mfma_f32_16x16x32_bf16 v[16:19], v[212:215], v[188:191], v[16:19]
	v_mfma_f32_16x16x32_bf16 v[4:7], v[204:207], v[196:199], v[4:7]
	v_mfma_f32_16x16x32_bf16 v[0:3], v[212:215], v[196:199], v[0:3]
	s_setprio 0
	s_add_i32 s68, 0, 0x18000
	v_add_u32_e32 v164, s68, v148
	s_barrier
	ds_read_b128 v[152:155], v164
	ds_read_b128 v[156:159], v164 offset:1024
	ds_read_b128 v[160:163], v164 offset:2048
	ds_read_b128 v[164:167], v164 offset:3072
	s_add_u32 s30, s30, 0x40000
	s_addc_u32 s31, s31, 0
	s_mov_b32 m0, s49
	v_lshl_add_u64 v[200:201], s[30:31], 0, v[128:129]
	ds_read_b128 v[168:171], v150 offset:32768
	ds_read_b128 v[172:175], v150 offset:33792
	ds_read_b128 v[176:179], v150 offset:34816
	ds_read_b128 v[180:183], v150 offset:35840
	ds_read_b128 v[184:187], v150 offset:36864
	ds_read_b128 v[188:191], v150 offset:37888
	ds_read_b128 v[192:195], v150 offset:38912
	ds_read_b128 v[196:199], v150 offset:39936
	global_load_lds_dwordx4 v[200:201], off
	v_lshl_add_u64 v[200:201], s[30:31], 0, v[132:133]
	s_mov_b32 m0, s50
	s_nop 0
	global_load_lds_dwordx4 v[200:201], off
	s_waitcnt lgkmcnt(8)
	s_barrier
	s_waitcnt lgkmcnt(0)
	s_setprio 1
	s_waitcnt lgkmcnt(0)
	v_mfma_f32_16x16x32_bf16 v[124:127], v[152:155], v[168:171], v[124:127]
	v_mfma_f32_16x16x32_bf16 v[120:123], v[160:163], v[168:171], v[120:123]
	v_mfma_f32_16x16x32_bf16 v[108:111], v[152:155], v[176:179], v[108:111]
	v_mfma_f32_16x16x32_bf16 v[104:107], v[160:163], v[176:179], v[104:107]
	v_mfma_f32_16x16x32_bf16 v[92:95], v[152:155], v[184:187], v[92:95]
	v_mfma_f32_16x16x32_bf16 v[88:91], v[160:163], v[184:187], v[88:91]
	v_mfma_f32_16x16x32_bf16 v[76:79], v[152:155], v[192:195], v[76:79]
	v_mfma_f32_16x16x32_bf16 v[72:75], v[160:163], v[192:195], v[72:75]
	v_mfma_f32_16x16x32_bf16 v[124:127], v[156:159], v[172:175], v[124:127]
	v_mfma_f32_16x16x32_bf16 v[120:123], v[164:167], v[172:175], v[120:123]
	v_mfma_f32_16x16x32_bf16 v[108:111], v[156:159], v[180:183], v[108:111]
	v_mfma_f32_16x16x32_bf16 v[104:107], v[164:167], v[180:183], v[104:107]
	v_mfma_f32_16x16x32_bf16 v[92:95], v[156:159], v[188:191], v[92:95]
	v_mfma_f32_16x16x32_bf16 v[88:91], v[164:167], v[188:191], v[88:91]
	v_mfma_f32_16x16x32_bf16 v[76:79], v[156:159], v[196:199], v[76:79]
	v_mfma_f32_16x16x32_bf16 v[72:75], v[164:167], v[196:199], v[72:75]
	s_setprio 0
	s_barrier
	s_add_i32 s30, 0, 0x1c000
	s_add_i32 s31, s68, s46
	v_add_u32_e32 v212, s30, v148
	v_lshl_add_u64 v[216:217], v[216:217], 0, s[10:11]
	s_mov_b32 m0, s31
	ds_read_b128 v[200:203], v212
	ds_read_b128 v[204:207], v212 offset:1024
	ds_read_b128 v[208:211], v212 offset:2048
	ds_read_b128 v[212:215], v212 offset:3072
	global_load_lds_dwordx4 v[216:217], off
	v_lshl_add_u64 v[216:217], v[218:219], 0, s[10:11]
	s_add_i32 m0, s31, 0x2000
	s_nop 0
	global_load_lds_dwordx4 v[216:217], off
	s_barrier
	s_waitcnt lgkmcnt(0)
	s_setprio 1
	s_waitcnt lgkmcnt(0)
	v_mfma_f32_16x16x32_bf16 v[116:119], v[200:203], v[168:171], v[116:119]
	v_mfma_f32_16x16x32_bf16 v[112:115], v[208:211], v[168:171], v[112:115]
	v_mfma_f32_16x16x32_bf16 v[100:103], v[200:203], v[176:179], v[100:103]
	v_mfma_f32_16x16x32_bf16 v[96:99], v[208:211], v[176:179], v[96:99]
	v_mfma_f32_16x16x32_bf16 v[84:87], v[200:203], v[184:187], v[84:87]
	v_mfma_f32_16x16x32_bf16 v[80:83], v[208:211], v[184:187], v[80:83]
	v_mfma_f32_16x16x32_bf16 v[68:71], v[200:203], v[192:195], v[68:71]
	v_mfma_f32_16x16x32_bf16 v[64:67], v[208:211], v[192:195], v[64:67]
	v_mfma_f32_16x16x32_bf16 v[116:119], v[204:207], v[172:175], v[116:119]
	v_mfma_f32_16x16x32_bf16 v[112:115], v[212:215], v[172:175], v[112:115]
	v_mfma_f32_16x16x32_bf16 v[100:103], v[204:207], v[180:183], v[100:103]
	v_mfma_f32_16x16x32_bf16 v[96:99], v[212:215], v[180:183], v[96:99]
	v_mfma_f32_16x16x32_bf16 v[84:87], v[204:207], v[188:191], v[84:87]
	v_mfma_f32_16x16x32_bf16 v[80:83], v[212:215], v[188:191], v[80:83]
	v_mfma_f32_16x16x32_bf16 v[68:71], v[204:207], v[196:199], v[68:71]
	v_mfma_f32_16x16x32_bf16 v[64:67], v[212:215], v[196:199], v[64:67]
	s_setprio 0
	s_mov_b32 m0, s52
	v_lshl_add_u64 v[216:217], v[220:221], 0, s[10:11]
	s_barrier
	ds_read_b128 v[168:171], v150 offset:49152
	ds_read_b128 v[172:175], v150 offset:50176
	ds_read_b128 v[176:179], v150 offset:51200
	ds_read_b128 v[180:183], v150 offset:52224
	ds_read_b128 v[184:187], v150 offset:53248
	ds_read_b128 v[188:191], v150 offset:54272
	ds_read_b128 v[192:195], v150 offset:55296
	ds_read_b128 v[196:199], v150 offset:56320
	global_load_lds_dwordx4 v[216:217], off
	v_lshl_add_u64 v[216:217], v[222:223], 0, s[10:11]
	s_mov_b32 m0, s53
	s_nop 0
	global_load_lds_dwordx4 v[216:217], off
	s_barrier
; DI unsigned pack2(float lo, float hi) { f32x2 v = {lo, hi}; bf16v2 r = __builtin_convertvector(v, bf16v2); return __builtin_bit_cast(unsigned, r); }
; DI float sigmoidf_(float x) { return frcp(1.f + fexp2(-x * LOG2E)); }
; #define PG8_STAGE(bufoff, gbase, voff) do { _Pragma("unroll") for (int _i = 0; _i < 2; ++_i) \
;         __builtin_amdgcn_global_load_lds((const unsigned*)((const char*)(gbase) + (voff)[_i]), (LAS unsigned*)(lds + (bufoff) + ldsw + _i * 8192), 16, 0, 0); } while (0)
; #define PG8_MMA(ai, bj, At, Bt) do { __builtin_amdgcn_s_setprio(1); _Pragma("unroll") for (int m = 0; m < 4; ++m) _Pragma("unroll") for (int n = 0; n < 2; ++n) _Pragma("unroll") for (int k = 0; k < 2; ++k) \
;         acc[ai][bj][m][n] = __builtin_amdgcn_mfma_f32_16x16x32_bf16(Bt[n][k], At[m][k], acc[ai][bj][m][n], 0, 0, 0); __builtin_amdgcn_s_setprio(0); } while (0)
; #define PG8_WAIT_V(n) asm volatile("s_waitcnt vmcnt(" #n ")" ::: "memory")
; #define PG8_WAIT_L(n) asm volatile("s_waitcnt lgkmcnt(" #n ")" ::: "memory")
; #define PG8_BAR __builtin_amdgcn_s_barrier()
; #define PG8_SCHED __builtin_amdgcn_sched_barrier(0)
; template <class Epi>
; DI void gemm_phase(int wv, LAS unsigned char* lds, const Gemm g, const StaticOrder& S, const Epi& E) {
;     ...
;             PG8_BAR; PG8_WAIT_L(0); PG8_MMA(1, 0, At, B0); PG8_BAR; PG8_SCHED;
;             PG8_STAGE(PG8_SB(1, 1), b3 + hstep, voffB);
;             PG8_WAIT_V(6); PG8_BAR; PG8_MMA(1, 1, At, B1); PG8_BAR;
;     DI void operator()(const AccT& acc, const Unit& u, int wr, int wc, int fr, int fq) const {
;     ...
;                 const size_t row = (size_t)u.pm * 256 + ai * 128 + wr * 64 + m * 16 + fr;
;                 float o[8];
; #pragma unroll
;                 for (int n = 0; n < 2; ++n) {
;                     const f32x4 g = acc[ai][0][m][n], up = acc[ai][1][m][n];
; #pragma unroll
;                     for (int e = 0; e < 4; ++e) o[4 * n + e] = g[e] * sigmoidf_(g[e]) * up[e];
;                 }
;                 u32x4 pk = {pack2(o[0], o[1]), pack2(o[2], o[3]), pack2(o[4], o[5]), pack2(o[6], o[7])};
;                 *(u32x4*)(O + row * DFF + u.pn * 128 + wc * 32 + 8 * fq) = pk;
	s_waitcnt lgkmcnt(0)
	s_setprio 1
	s_waitcnt lgkmcnt(0)
	v_mfma_f32_16x16x32_bf16 v[60:63], v[152:155], v[168:171], v[60:63]
	v_mfma_f32_16x16x32_bf16 v[56:59], v[160:163], v[168:171], v[56:59]
	v_mfma_f32_16x16x32_bf16 v[44:47], v[152:155], v[176:179], v[44:47]
	v_mfma_f32_16x16x32_bf16 v[40:43], v[160:163], v[176:179], v[40:43]
	v_mfma_f32_16x16x32_bf16 v[28:31], v[152:155], v[184:187], v[28:31]
	v_mfma_f32_16x16x32_bf16 v[24:27], v[160:163], v[184:187], v[24:27]
	v_mfma_f32_16x16x32_bf16 v[12:15], v[152:155], v[192:195], v[12:15]
	v_mfma_f32_16x16x32_bf16 v[8:11], v[160:163], v[192:195], v[8:11]
	v_mfma_f32_16x16x32_bf16 v[60:63], v[156:159], v[172:175], v[60:63]
	v_mfma_f32_16x16x32_bf16 v[56:59], v[164:167], v[172:175], v[56:59]
	v_mfma_f32_16x16x32_bf16 v[44:47], v[156:159], v[180:183], v[44:47]
	v_mfma_f32_16x16x32_bf16 v[40:43], v[164:167], v[180:183], v[40:43]
	v_mfma_f32_16x16x32_bf16 v[28:31], v[156:159], v[188:191], v[28:31]
	v_mfma_f32_16x16x32_bf16 v[24:27], v[164:167], v[188:191], v[24:27]
	v_mfma_f32_16x16x32_bf16 v[12:15], v[156:159], v[196:199], v[12:15]
	v_mfma_f32_16x16x32_bf16 v[8:11], v[164:167], v[196:199], v[8:11]
	s_setprio 0
	s_barrier
	s_add_u32 s28, s28, 0x40080
	s_addc_u32 s29, s29, 0
	s_add_i32 s30, s30, s46
	v_lshl_add_u64 v[152:153], s[28:29], 0, v[130:131]
	s_mov_b32 m0, s30
	s_nop 0
	global_load_lds_dwordx4 v[152:153], off
	v_lshl_add_u64 v[152:153], s[28:29], 0, v[134:135]
	s_add_i32 m0, s30, 0x2000
	s_nop 0
	global_load_lds_dwordx4 v[152:153], off
	s_waitcnt vmcnt(6)
	s_barrier
	s_setprio 1
	v_mfma_f32_16x16x32_bf16 v[52:55], v[200:203], v[168:171], v[52:55]
	v_mfma_f32_16x16x32_bf16 v[48:51], v[208:211], v[168:171], v[48:51]
	v_mfma_f32_16x16x32_bf16 v[36:39], v[200:203], v[176:179], v[36:39]
	v_mfma_f32_16x16x32_bf16 v[32:35], v[208:211], v[176:179], v[32:35]
	v_mfma_f32_16x16x32_bf16 v[20:23], v[200:203], v[184:187], v[20:23]
	v_mfma_f32_16x16x32_bf16 v[16:19], v[208:211], v[184:187], v[16:19]
	v_mfma_f32_16x16x32_bf16 v[4:7], v[200:203], v[192:195], v[4:7]
	v_mfma_f32_16x16x32_bf16 v[0:3], v[208:211], v[192:195], v[0:3]
	v_mfma_f32_16x16x32_bf16 v[52:55], v[204:207], v[172:175], v[52:55]
	v_mfma_f32_16x16x32_bf16 v[48:51], v[212:215], v[172:175], v[48:51]
	v_mfma_f32_16x16x32_bf16 v[36:39], v[204:207], v[180:183], v[36:39]
	v_mfma_f32_16x16x32_bf16 v[32:35], v[212:215], v[180:183], v[32:35]
	v_mfma_f32_16x16x32_bf16 v[20:23], v[204:207], v[188:191], v[20:23]
	v_mfma_f32_16x16x32_bf16 v[16:19], v[212:215], v[188:191], v[16:19]
	v_mfma_f32_16x16x32_bf16 v[4:7], v[204:207], v[196:199], v[4:7]
	v_mfma_f32_16x16x32_bf16 v[0:3], v[212:215], v[196:199], v[0:3]
	s_setprio 0
	s_add_i32 s67, s67, 2
	s_add_u32 s26, s26, 0x100
	s_addc_u32 s27, s27, 0
	s_add_u32 s65, s65, 0x100
	s_addc_u32 s66, s66, 0
	s_cmp_gt_u32 s67, 13
	s_barrier
	s_cbranch_scc0 .LBB0_3137
	s_mov_b32 s98, 0xbfb8aa3b
	v_pk_mul_f32 v[152:153], v[124:125], s[98:99] op_sel_hi:[1,0]
	v_exp_f32_e32 v152, v152
	v_exp_f32_e32 v153, v153
	s_ashr_i32 s25, s24, 31
	s_lshl_b64 s[24:25], s[24:25], 8
	v_pk_add_f32 v[152:153], v[152:153], 1.0 op_sel_hi:[1,0]
	v_rcp_f32_e32 v152, v152
	v_rcp_f32_e32 v153, v153
	v_lshl_add_u64 v[154:155], v[138:139], 0, s[24:25]
	s_lshl_b32 s24, s63, 7
	s_ashr_i32 s25, s24, 31
	v_pk_mul_f32 v[124:125], v[124:125], v[152:153]
	v_pk_mul_f32 v[152:153], v[126:127], s[98:99] op_sel_hi:[1,0]
	v_exp_f32_e32 v152, v152
	v_exp_f32_e32 v153, v153
	v_pk_mul_f32 v[116:117], v[124:125], v[116:117]
	s_mov_b32 s63, s12
	v_pk_add_f32 v[124:125], v[152:153], 1.0 op_sel_hi:[1,0]
	v_pk_mul_f32 v[152:153], v[120:121], s[98:99] op_sel_hi:[1,0]
	v_rcp_f32_e32 v124, v124
	v_rcp_f32_e32 v125, v125
	v_exp_f32_e32 v152, v152
	v_exp_f32_e32 v153, v153
	s_mov_b64 s[28:29], s[18:19]
	v_pk_mul_f32 v[124:125], v[126:127], v[124:125]
	v_pk_add_f32 v[126:127], v[152:153], 1.0 op_sel_hi:[1,0]
	v_pk_mul_f32 v[152:153], v[122:123], s[98:99] op_sel_hi:[1,0]
	v_exp_f32_e32 v152, v152
	v_exp_f32_e32 v153, v153
	v_rcp_f32_e32 v126, v126
	v_rcp_f32_e32 v127, v127
	v_pk_add_f32 v[152:153], v[152:153], 1.0 op_sel_hi:[1,0]
	v_rcp_f32_e32 v152, v152
	v_rcp_f32_e32 v153, v153
	v_pk_mul_f32 v[120:121], v[120:121], v[126:127]
	v_pk_mul_f32 v[118:119], v[124:125], v[118:119]
	v_pk_mul_f32 v[112:113], v[120:121], v[112:113]
	v_pk_mul_f32 v[120:121], v[122:123], v[152:153]
	s_nop 0
	v_pk_mul_f32 v[120:121], v[120:121], v[114:115]
	v_cvt_pk_bf16_f32 v114, v116, v117
	v_cvt_pk_bf16_f32 v116, v112, v113
	v_mov_b64_e32 v[112:113], s[38:39]
	v_mad_u64_u32 v[112:113], s[26:27], v154, s56, v[112:113]
	v_cvt_pk_bf16_f32 v115, v118, v119
	v_mov_b32_e32 v118, v113
	v_mad_u64_u32 v[118:119], s[26:27], v155, s56, v[118:119]
	v_mov_b32_e32 v113, v118
	v_pk_mul_f32 v[118:119], v[108:109], s[98:99] op_sel_hi:[1,0]
	v_exp_f32_e32 v118, v118
	v_exp_f32_e32 v119, v119
	v_lshl_add_u64 v[112:113], s[24:25], 1, v[112:113]
	v_lshl_add_u64 v[112:113], v[112:113], 0, s[8:9]
	v_cvt_pk_bf16_f32 v117, v120, v121
	v_pk_add_f32 v[118:119], v[118:119], 1.0 op_sel_hi:[1,0]
	v_lshl_add_u64 v[112:113], v[112:113], 0, v[136:137]
	v_rcp_f32_e32 v118, v118
	v_rcp_f32_e32 v119, v119
	global_store_dwordx4 v[112:113], v[114:117], off
	s_mov_b32 s24, s14
	s_mov_b64 s[26:27], s[16:17]
	v_pk_mul_f32 v[114:115], v[110:111], s[98:99] op_sel_hi:[1,0]
	v_exp_f32_e32 v114, v114
	v_exp_f32_e32 v115, v115
	v_pk_mul_f32 v[108:109], v[108:109], v[118:119]
	s_nop 0
	v_pk_mul_f32 v[100:101], v[108:109], v[100:101]
	v_pk_add_f32 v[108:109], v[114:115], 1.0 op_sel_hi:[1,0]
	v_pk_mul_f32 v[114:115], v[104:105], s[98:99] op_sel_hi:[1,0]
	v_rcp_f32_e32 v108, v108
	v_rcp_f32_e32 v109, v109
	v_exp_f32_e32 v114, v114
; DI unsigned pack2(float lo, float hi) { f32x2 v = {lo, hi}; bf16v2 r = __builtin_convertvector(v, bf16v2); return __builtin_bit_cast(unsigned, r); }
; DI float sigmoidf_(float x) { return frcp(1.f + fexp2(-x * LOG2E)); }
;     DI void operator()(const AccT& acc, const Unit& u, int wr, int wc, int fr, int fq) const {
;     ...
;                 const size_t row = (size_t)u.pm * 256 + ai * 128 + wr * 64 + m * 16 + fr;
;                 float o[8];
; #pragma unroll
;                 for (int n = 0; n < 2; ++n) {
;                     const f32x4 g = acc[ai][0][m][n], up = acc[ai][1][m][n];
; #pragma unroll
;                     for (int e = 0; e < 4; ++e) o[4 * n + e] = g[e] * sigmoidf_(g[e]) * up[e];
;                 }
;                 u32x4 pk = {pack2(o[0], o[1]), pack2(o[2], o[3]), pack2(o[4], o[5]), pack2(o[6], o[7])};
;                 *(u32x4*)(O + row * DFF + u.pn * 128 + wc * 32 + 8 * fq) = pk;
	v_exp_f32_e32 v115, v115
	v_pk_mul_f32 v[108:109], v[110:111], v[108:109]
	v_pk_add_f32 v[110:111], v[114:115], 1.0 op_sel_hi:[1,0]
	v_pk_mul_f32 v[114:115], v[106:107], s[98:99] op_sel_hi:[1,0]
	v_exp_f32_e32 v114, v114
	v_exp_f32_e32 v115, v115
	v_rcp_f32_e32 v110, v110
	v_rcp_f32_e32 v111, v111
	v_pk_add_f32 v[114:115], v[114:115], 1.0 op_sel_hi:[1,0]
	v_rcp_f32_e32 v114, v114
	v_rcp_f32_e32 v115, v115
	v_pk_mul_f32 v[104:105], v[104:105], v[110:111]
	v_pk_mul_f32 v[102:103], v[108:109], v[102:103]
	v_pk_mul_f32 v[104:105], v[104:105], v[96:97]
	v_pk_mul_f32 v[96:97], v[106:107], v[114:115]
	s_nop 0
	v_pk_mul_f32 v[106:107], v[96:97], v[98:99]
	v_mul_f32_e32 v99, 0xbfb8aa3b, v92
	v_cvt_pk_bf16_f32 v96, v100, v101
	v_exp_f32_e32 v100, v99
	v_mul_f32_e32 v99, 0xbfb8aa3b, v93
	v_exp_f32_e32 v101, v99
	v_cvt_pk_bf16_f32 v97, v102, v103
	v_add_co_u32_e32 v102, vcc, s51, v112
	v_cvt_pk_bf16_f32 v98, v104, v105
	v_cvt_pk_bf16_f32 v99, v106, v107
	v_pk_add_f32 v[100:101], v[100:101], 1.0 op_sel_hi:[1,0]
	v_addc_co_u32_e32 v103, vcc, 0, v113, vcc
	v_rcp_f32_e32 v100, v100
	v_rcp_f32_e32 v101, v101
	global_store_dwordx4 v[102:103], v[96:99], off
	v_pk_mul_f32 v[92:93], v[92:93], v[100:101]
	s_nop 0
	v_pk_mul_f32 v[96:97], v[94:95], s[98:99] op_sel_hi:[1,0]
	v_exp_f32_e32 v96, v96
	v_exp_f32_e32 v97, v97
	v_pk_mul_f32 v[84:85], v[92:93], v[84:85]
	v_pk_add_f32 v[92:93], v[96:97], 1.0 op_sel_hi:[1,0]
	v_pk_mul_f32 v[96:97], v[88:89], s[98:99] op_sel_hi:[1,0]
	v_rcp_f32_e32 v92, v92
	v_rcp_f32_e32 v93, v93
	v_exp_f32_e32 v96, v96
	v_exp_f32_e32 v97, v97
	v_pk_mul_f32 v[92:93], v[94:95], v[92:93]
	v_pk_add_f32 v[94:95], v[96:97], 1.0 op_sel_hi:[1,0]
	v_pk_mul_f32 v[96:97], v[90:91], s[98:99] op_sel_hi:[1,0]
	v_exp_f32_e32 v96, v96
	v_exp_f32_e32 v97, v97
	v_rcp_f32_e32 v94, v94
	v_rcp_f32_e32 v95, v95
	v_pk_add_f32 v[96:97], v[96:97], 1.0 op_sel_hi:[1,0]
	v_rcp_f32_e32 v96, v96
	v_rcp_f32_e32 v97, v97
	v_pk_mul_f32 v[88:89], v[88:89], v[94:95]
	v_pk_mul_f32 v[86:87], v[92:93], v[86:87]
	v_pk_mul_f32 v[88:89], v[88:89], v[80:81]
	v_pk_mul_f32 v[80:81], v[90:91], v[96:97]
	s_nop 0
	v_pk_mul_f32 v[90:91], v[80:81], v[82:83]
	v_mul_f32_e32 v83, 0xbfb8aa3b, v76
	v_cvt_pk_bf16_f32 v80, v84, v85
	v_exp_f32_e32 v84, v83
	v_mul_f32_e32 v83, 0xbfb8aa3b, v77
	v_exp_f32_e32 v85, v83
	v_cvt_pk_bf16_f32 v81, v86, v87
	v_add_co_u32_e32 v86, vcc, s57, v112
	v_cvt_pk_bf16_f32 v82, v88, v89
	v_cvt_pk_bf16_f32 v83, v90, v91
	v_pk_add_f32 v[84:85], v[84:85], 1.0 op_sel_hi:[1,0]
	v_addc_co_u32_e32 v87, vcc, 0, v113, vcc
	v_rcp_f32_e32 v84, v84
	v_rcp_f32_e32 v85, v85
	global_store_dwordx4 v[86:87], v[80:83], off
	v_pk_mul_f32 v[76:77], v[76:77], v[84:85]
	s_nop 0
	v_pk_mul_f32 v[80:81], v[78:79], s[98:99] op_sel_hi:[1,0]
	v_exp_f32_e32 v80, v80
	v_exp_f32_e32 v81, v81
	v_pk_mul_f32 v[68:69], v[76:77], v[68:69]
	v_pk_add_f32 v[76:77], v[80:81], 1.0 op_sel_hi:[1,0]
	v_pk_mul_f32 v[80:81], v[72:73], s[98:99] op_sel_hi:[1,0]
	v_rcp_f32_e32 v76, v76
	v_rcp_f32_e32 v77, v77
	v_exp_f32_e32 v80, v80
	v_exp_f32_e32 v81, v81
	v_pk_mul_f32 v[76:77], v[78:79], v[76:77]
	v_pk_add_f32 v[78:79], v[80:81], 1.0 op_sel_hi:[1,0]
	v_pk_mul_f32 v[80:81], v[74:75], s[98:99] op_sel_hi:[1,0]
	v_exp_f32_e32 v80, v80
	v_exp_f32_e32 v81, v81
	v_rcp_f32_e32 v78, v78
	v_rcp_f32_e32 v79, v79
	v_pk_add_f32 v[80:81], v[80:81], 1.0 op_sel_hi:[1,0]
	v_rcp_f32_e32 v80, v80
	v_rcp_f32_e32 v81, v81
	v_pk_mul_f32 v[72:73], v[72:73], v[78:79]
	v_pk_mul_f32 v[70:71], v[76:77], v[70:71]
	v_pk_mul_f32 v[72:73], v[72:73], v[64:65]
	v_pk_mul_f32 v[64:65], v[74:75], v[80:81]
	s_nop 0
	v_pk_mul_f32 v[74:75], v[64:65], v[66:67]
	v_mul_f32_e32 v67, 0xbfb8aa3b, v60
	v_cvt_pk_bf16_f32 v64, v68, v69
	v_exp_f32_e32 v68, v67
	v_mul_f32_e32 v67, 0xbfb8aa3b, v61
	v_exp_f32_e32 v69, v67
	v_cvt_pk_bf16_f32 v65, v70, v71
	v_add_co_u32_e32 v70, vcc, s58, v112
	v_cvt_pk_bf16_f32 v66, v72, v73
	v_cvt_pk_bf16_f32 v67, v74, v75
	v_pk_add_f32 v[68:69], v[68:69], 1.0 op_sel_hi:[1,0]
	v_addc_co_u32_e32 v71, vcc, 0, v113, vcc
	v_rcp_f32_e32 v68, v68
	v_rcp_f32_e32 v69, v69
	global_store_dwordx4 v[70:71], v[64:67], off
	v_pk_mul_f32 v[60:61], v[60:61], v[68:69]
	s_nop 0
	v_pk_mul_f32 v[64:65], v[62:63], s[98:99] op_sel_hi:[1,0]
	v_exp_f32_e32 v64, v64
	v_exp_f32_e32 v65, v65
	v_pk_mul_f32 v[52:53], v[60:61], v[52:53]
	v_pk_add_f32 v[60:61], v[64:65], 1.0 op_sel_hi:[1,0]
	v_pk_mul_f32 v[64:65], v[56:57], s[98:99] op_sel_hi:[1,0]
	v_rcp_f32_e32 v60, v60
	v_rcp_f32_e32 v61, v61
	v_exp_f32_e32 v64, v64
	v_exp_f32_e32 v65, v65
	v_pk_mul_f32 v[60:61], v[62:63], v[60:61]
	v_pk_add_f32 v[62:63], v[64:65], 1.0 op_sel_hi:[1,0]
	v_pk_mul_f32 v[64:65], v[58:59], s[98:99] op_sel_hi:[1,0]
	v_exp_f32_e32 v64, v64
	v_exp_f32_e32 v65, v65
	v_rcp_f32_e32 v62, v62
	v_rcp_f32_e32 v63, v63
	v_pk_add_f32 v[64:65], v[64:65], 1.0 op_sel_hi:[1,0]
	v_rcp_f32_e32 v64, v64
	v_rcp_f32_e32 v65, v65
	v_pk_mul_f32 v[56:57], v[56:57], v[62:63]
	v_pk_mul_f32 v[54:55], v[60:61], v[54:55]
; DI unsigned pack2(float lo, float hi) { f32x2 v = {lo, hi}; bf16v2 r = __builtin_convertvector(v, bf16v2); return __builtin_bit_cast(unsigned, r); }
; DI float sigmoidf_(float x) { return frcp(1.f + fexp2(-x * LOG2E)); }
; #define PG8_WAIT_V(n) asm volatile("s_waitcnt vmcnt(" #n ")" ::: "memory")
; #define PG8_BAR __builtin_amdgcn_s_barrier()
; template <class Epi>
; DI void gemm_phase(int wv, LAS unsigned char* lds, const Gemm g, const StaticOrder& S, const Epi& E) {
;     ...
;         E(acc, cur, wr, wc, fr, fq);
;         if (!has_next) break;
; #pragma unroll
;         for (int a = 0; a < 2; ++a)
; #pragma unroll
;             for (int b = 0; b < 2; ++b)
; #pragma unroll
;                 for (int m = 0; m < 4; ++m)
; #pragma unroll
;                     for (int n = 0; n < 2; ++n) acc[a][b][m][n] = (f32x4){0.f, 0.f, 0.f, 0.f};
;         cur = nxt; cA = nA; cB = nB; ++ui;
;     }
;     PG8_WAIT_V(0);
;     if (wr == 0) PG8_BAR;
;     PG8_BAR;
;     DI void operator()(const AccT& acc, const Unit& u, int wr, int wc, int fr, int fq) const {
;     ...
;                 const size_t row = (size_t)u.pm * 256 + ai * 128 + wr * 64 + m * 16 + fr;
;                 float o[8];
; #pragma unroll
;                 for (int n = 0; n < 2; ++n) {
;                     const f32x4 g = acc[ai][0][m][n], up = acc[ai][1][m][n];
; #pragma unroll
;                     for (int e = 0; e < 4; ++e) o[4 * n + e] = g[e] * sigmoidf_(g[e]) * up[e];
;                 }
;                 u32x4 pk = {pack2(o[0], o[1]), pack2(o[2], o[3]), pack2(o[4], o[5]), pack2(o[6], o[7])};
;                 *(u32x4*)(O + row * DFF + u.pn * 128 + wc * 32 + 8 * fq) = pk;
;             }
	v_pk_mul_f32 v[56:57], v[56:57], v[48:49]
	v_pk_mul_f32 v[48:49], v[58:59], v[64:65]
	s_nop 0
	v_pk_mul_f32 v[58:59], v[48:49], v[50:51]
	v_mul_f32_e32 v51, 0xbfb8aa3b, v44
	v_cvt_pk_bf16_f32 v48, v52, v53
	v_exp_f32_e32 v52, v51
	v_mul_f32_e32 v51, 0xbfb8aa3b, v45
	v_exp_f32_e32 v53, v51
	v_cvt_pk_bf16_f32 v49, v54, v55
	v_add_co_u32_e32 v54, vcc, s59, v112
	v_cvt_pk_bf16_f32 v50, v56, v57
	v_cvt_pk_bf16_f32 v51, v58, v59
	v_pk_add_f32 v[52:53], v[52:53], 1.0 op_sel_hi:[1,0]
	v_addc_co_u32_e32 v55, vcc, 0, v113, vcc
	v_rcp_f32_e32 v52, v52
	v_rcp_f32_e32 v53, v53
	global_store_dwordx4 v[54:55], v[48:51], off
	v_pk_mul_f32 v[44:45], v[44:45], v[52:53]
	s_nop 0
	v_pk_mul_f32 v[48:49], v[46:47], s[98:99] op_sel_hi:[1,0]
	v_exp_f32_e32 v48, v48
	v_exp_f32_e32 v49, v49
	v_pk_mul_f32 v[36:37], v[44:45], v[36:37]
	v_pk_add_f32 v[44:45], v[48:49], 1.0 op_sel_hi:[1,0]
	v_pk_mul_f32 v[48:49], v[40:41], s[98:99] op_sel_hi:[1,0]
	v_rcp_f32_e32 v44, v44
	v_rcp_f32_e32 v45, v45
	v_exp_f32_e32 v48, v48
	v_exp_f32_e32 v49, v49
	v_pk_mul_f32 v[44:45], v[46:47], v[44:45]
	v_pk_add_f32 v[46:47], v[48:49], 1.0 op_sel_hi:[1,0]
	v_pk_mul_f32 v[48:49], v[42:43], s[98:99] op_sel_hi:[1,0]
	v_exp_f32_e32 v48, v48
	v_exp_f32_e32 v49, v49
	v_rcp_f32_e32 v46, v46
	v_rcp_f32_e32 v47, v47
	v_pk_add_f32 v[48:49], v[48:49], 1.0 op_sel_hi:[1,0]
	v_rcp_f32_e32 v48, v48
	v_rcp_f32_e32 v49, v49
	v_pk_mul_f32 v[40:41], v[40:41], v[46:47]
	v_pk_mul_f32 v[38:39], v[44:45], v[38:39]
	v_pk_mul_f32 v[40:41], v[40:41], v[32:33]
	v_pk_mul_f32 v[32:33], v[42:43], v[48:49]
	s_nop 0
	v_pk_mul_f32 v[42:43], v[32:33], v[34:35]
	v_mul_f32_e32 v35, 0xbfb8aa3b, v28
	v_cvt_pk_bf16_f32 v32, v36, v37
	v_exp_f32_e32 v36, v35
	v_mul_f32_e32 v35, 0xbfb8aa3b, v29
	v_exp_f32_e32 v37, v35
	v_cvt_pk_bf16_f32 v33, v38, v39
	v_add_co_u32_e32 v38, vcc, s60, v112
	v_cvt_pk_bf16_f32 v34, v40, v41
	v_cvt_pk_bf16_f32 v35, v42, v43
	v_pk_add_f32 v[36:37], v[36:37], 1.0 op_sel_hi:[1,0]
	v_addc_co_u32_e32 v39, vcc, 0, v113, vcc
	v_rcp_f32_e32 v36, v36
	v_rcp_f32_e32 v37, v37
	global_store_dwordx4 v[38:39], v[32:35], off
	v_pk_mul_f32 v[28:29], v[28:29], v[36:37]
	s_nop 0
	v_pk_mul_f32 v[32:33], v[30:31], s[98:99] op_sel_hi:[1,0]
	v_exp_f32_e32 v32, v32
	v_exp_f32_e32 v33, v33
	v_pk_mul_f32 v[20:21], v[28:29], v[20:21]
	v_pk_add_f32 v[28:29], v[32:33], 1.0 op_sel_hi:[1,0]
	v_pk_mul_f32 v[32:33], v[24:25], s[98:99] op_sel_hi:[1,0]
	v_rcp_f32_e32 v28, v28
	v_rcp_f32_e32 v29, v29
	v_exp_f32_e32 v32, v32
	v_exp_f32_e32 v33, v33
	v_pk_mul_f32 v[28:29], v[30:31], v[28:29]
	v_pk_add_f32 v[30:31], v[32:33], 1.0 op_sel_hi:[1,0]
	v_pk_mul_f32 v[32:33], v[26:27], s[98:99] op_sel_hi:[1,0]
	v_exp_f32_e32 v32, v32
	v_exp_f32_e32 v33, v33
	v_rcp_f32_e32 v30, v30
	v_rcp_f32_e32 v31, v31
	v_pk_add_f32 v[32:33], v[32:33], 1.0 op_sel_hi:[1,0]
	v_rcp_f32_e32 v32, v32
	v_rcp_f32_e32 v33, v33
	v_pk_mul_f32 v[24:25], v[24:25], v[30:31]
	v_pk_mul_f32 v[22:23], v[28:29], v[22:23]
	v_pk_mul_f32 v[24:25], v[24:25], v[16:17]
	v_pk_mul_f32 v[16:17], v[26:27], v[32:33]
	s_nop 0
	v_pk_mul_f32 v[26:27], v[16:17], v[18:19]
	v_mul_f32_e32 v19, 0xbfb8aa3b, v12
	v_cvt_pk_bf16_f32 v16, v20, v21
	v_exp_f32_e32 v20, v19
	v_mul_f32_e32 v19, 0xbfb8aa3b, v13
	v_exp_f32_e32 v21, v19
	v_cvt_pk_bf16_f32 v17, v22, v23
	v_add_co_u32_e32 v22, vcc, s61, v112
	v_cvt_pk_bf16_f32 v18, v24, v25
	v_cvt_pk_bf16_f32 v19, v26, v27
	v_pk_add_f32 v[20:21], v[20:21], 1.0 op_sel_hi:[1,0]
	v_addc_co_u32_e32 v23, vcc, 0, v113, vcc
	v_rcp_f32_e32 v20, v20
	v_rcp_f32_e32 v21, v21
	global_store_dwordx4 v[22:23], v[16:19], off
	v_pk_mul_f32 v[12:13], v[12:13], v[20:21]
	s_nop 0
	v_pk_mul_f32 v[16:17], v[14:15], s[98:99] op_sel_hi:[1,0]
	v_exp_f32_e32 v16, v16
	v_exp_f32_e32 v17, v17
	v_pk_mul_f32 v[4:5], v[12:13], v[4:5]
	v_pk_add_f32 v[12:13], v[16:17], 1.0 op_sel_hi:[1,0]
	v_pk_mul_f32 v[16:17], v[8:9], s[98:99] op_sel_hi:[1,0]
	v_rcp_f32_e32 v12, v12
	v_rcp_f32_e32 v13, v13
	v_exp_f32_e32 v16, v16
	v_exp_f32_e32 v17, v17
	v_pk_mul_f32 v[12:13], v[14:15], v[12:13]
	v_pk_add_f32 v[14:15], v[16:17], 1.0 op_sel_hi:[1,0]
	v_pk_mul_f32 v[16:17], v[10:11], s[98:99] op_sel_hi:[1,0]
	v_exp_f32_e32 v16, v16
	v_exp_f32_e32 v17, v17
	v_rcp_f32_e32 v14, v14
	v_rcp_f32_e32 v15, v15
	v_pk_add_f32 v[16:17], v[16:17], 1.0 op_sel_hi:[1,0]
	v_rcp_f32_e32 v16, v16
	v_rcp_f32_e32 v17, v17
	v_pk_mul_f32 v[8:9], v[8:9], v[14:15]
	v_pk_mul_f32 v[6:7], v[12:13], v[6:7]
	v_pk_mul_f32 v[8:9], v[8:9], v[0:1]
	v_pk_mul_f32 v[0:1], v[10:11], v[16:17]
	s_nop 0
	v_pk_mul_f32 v[10:11], v[0:1], v[2:3]
	v_cvt_pk_bf16_f32 v0, v4, v5
	v_add_co_u32_e32 v4, vcc, 0xf2000, v112
	v_cvt_pk_bf16_f32 v1, v6, v7
	s_nop 0
	v_addc_co_u32_e32 v5, vcc, 0, v113, vcc
	v_cvt_pk_bf16_f32 v2, v8, v9
	v_cvt_pk_bf16_f32 v3, v10, v11
	s_and_b64 vcc, exec, s[4:5]
	global_store_dwordx4 v[4:5], v[0:3], off
	s_cbranch_vccz .LBB0_3130
	s_waitcnt vmcnt(0)
	s_cmpk_gt_u32 s36, 0xff
	s_cbranch_scc1 .LBB0_3141
	s_barrier
